# A/B of the seed's per-segment s_setprio flips in the GEMM K-loops: all removed
# speedup vs baseline: 1.0144x; 1.0144x over previous
; #define PG8_STAGE(bufoff, gbase, voff) do { _Pragma("unroll") for (int _i = 0; _i < 2; ++_i) \
;         __builtin_amdgcn_global_load_lds((const unsigned*)((const char*)(gbase) + (voff)[_i]), (PG8_LAS unsigned*)(lds + (bufoff) + ldsw + _i * 8192), 16, 0, 0); } while (0)
; #define PG8_LDA(dst, b, h) do { _Pragma("unroll") for (int m = 0; m < 4; ++m) _Pragma("unroll") for (int k = 0; k < 2; ++k) dst[m][k] = *(const PG8_LAS bf16x8*)(lds + PG8_SA(b, h) + aoff + m * 2048 + k * 1024); } while (0)
; #define PG8_LDB(dst, b, h) do { _Pragma("unroll") for (int n = 0; n < 2; ++n) _Pragma("unroll") for (int k = 0; k < 2; ++k) dst[n][k] = *(const PG8_LAS bf16x8*)(lds + PG8_SB(b, h) + boff + n * 2048 + k * 1024); } while (0)
; #define PG8_WAIT_V(n) asm volatile("s_waitcnt vmcnt(" #n ")" ::: "memory")
; #define PG8_WAIT_L(n) asm volatile("s_waitcnt lgkmcnt(" #n ")" ::: "memory")
; #define PG8_BAR __builtin_amdgcn_s_barrier()
; #define PG8_SCHED __builtin_amdgcn_sched_barrier(0)
; template <class Epi, class Sched, bool ALIGN_EPI = false, bool SP2 = false>
; __device__ __forceinline__ void gemm_phase(PG8_LAS unsigned char* lds, const Gemm g, const Sched& S, const Epi& E, int tid_in) {
;     ...
;         const char* nA = has_next ? (const char*)g.A + (size_t)nxt.pm * tstep : cA; const char* nB = has_next ? (const char*)g.Bt + (size_t)nxt.pn * tstep : cB;
;         for (int t = 0; t < nt; t += 2) {
;             const bool last = (t == nt - 2);
;             const char* a1 = cA + (size_t)(t + 1) * kstep;
;             const char* a2 = last ? nA : cA + (size_t)(t + 2) * kstep; const char* b2 = last ? nB : cB + (size_t)(t + 2) * kstep;
;             const char* a3 = a2 + kstep; const char* b3 = b2 + kstep;
;             if (last && has_next) S.a_ready(nxt);
;             if constexpr (SP2) {
;             PG8_LDB(B0, 0, 0); PG8_LDB(B1, 0, 1); PG8_SCHED; PG8_LDA(At, 0, 0); PG8_STAGE(PG8_SA(1, 1), a1 + hstep, voffA);
;             PG8_WAIT_V(8); PG8_WAIT_L(0); PG8_BAR; PG8_MMA(0, 0, At, B0); PG8_MMA(0, 1, At, B1); PG8_BAR; PG8_SCHED;
;             PG8_LDA(At, 0, 1); PG8_STAGE(PG8_SB(0, 0), b2, voffB); PG8_STAGE(PG8_SB(0, 1), b2 + hstep, voffB); PG8_STAGE(PG8_SA(0, 0), a2, voffA);
;             PG8_WAIT_V(8); PG8_WAIT_L(0); PG8_BAR; PG8_MMA(1, 0, At, B0); PG8_MMA(1, 1, At, B1); PG8_BAR; PG8_SCHED;
.LBB0_190:
	s_ashr_i32 s41, s40, 31
	s_lshl_b64 s[46:47], s[40:41], 19
	s_add_u32 s46, s59, s46
	s_addc_u32 s47, s60, s47
	s_and_b64 s[48:49], s[44:45], exec
	s_cselect_b32 s41, s47, s51
	s_cselect_b32 s79, s46, s50
	s_ashr_i32 s43, s42, 31
	s_lshl_b64 s[48:49], s[42:43], 19
	s_add_u32 s48, s33, s48
	s_addc_u32 s49, s56, s49
	s_and_b64 s[54:55], s[44:45], exec
	s_cselect_b32 s43, s49, s53
	s_cselect_b32 s80, s48, s52
	s_add_u32 s50, s50, 0x40080
	s_addc_u32 s51, s51, 0
	s_add_u32 s81, s52, 0x100
	s_addc_u32 s82, s53, 0
	s_mov_b32 s83, -2
	s_add_u32 s52, s50, 0xfffc0080
	s_addc_u32 s53, s51, -1
	s_add_i32 s84, 0, 0x10000
	s_cmp_eq_u32 s83, 12
	s_cselect_b32 s55, s41, s53
	s_cselect_b32 s54, s79, s52
	v_add_u32_e32 v149, s84, v147
	s_cselect_b32 s53, s43, s82
	s_cselect_b32 s52, s80, s81
	s_add_i32 s86, 0, 0x14000
	ds_read_b128 v[142:145], v149
	ds_read_b128 v[150:153], v149 offset:1024
	ds_read_b128 v[154:157], v149 offset:2048
	ds_read_b128 v[158:161], v149 offset:3072
	v_add_u32_e32 v149, s86, v147
	ds_read_b128 v[162:165], v149
	ds_read_b128 v[166:169], v149 offset:1024
	ds_read_b128 v[170:173], v149 offset:2048
	ds_read_b128 v[174:177], v149 offset:3072
	v_lshl_add_u64 v[220:221], s[50:51], 0, v[138:139]
	s_add_i32 m0, s61, 0xc000
	ds_read_b128 v[178:181], v148
	ds_read_b128 v[182:185], v148 offset:1024
	ds_read_b128 v[196:199], v148 offset:2048
	ds_read_b128 v[200:203], v148 offset:3072
	ds_read_b128 v[204:207], v148 offset:4096
	ds_read_b128 v[208:211], v148 offset:5120
	ds_read_b128 v[212:215], v148 offset:6144
	ds_read_b128 v[216:219], v148 offset:7168
	global_load_lds_dwordx4 v[220:221], off
	v_lshl_add_u64 v[220:221], s[50:51], 0, v[140:141]
	s_add_i32 m0, s61, 0xe000
	s_nop 0
	global_load_lds_dwordx4 v[220:221], off
	s_waitcnt vmcnt(8)
	s_waitcnt lgkmcnt(0)
	s_barrier
	s_waitcnt lgkmcnt(0)
	v_mfma_f32_16x16x32_bf16 v[126:129], v[142:145], v[178:181], 0
	v_mfma_f32_16x16x32_bf16 v[122:125], v[154:157], v[178:181], 0
	v_mfma_f32_16x16x32_bf16 v[110:113], v[142:145], v[196:199], 0
	v_mfma_f32_16x16x32_bf16 v[106:109], v[154:157], v[196:199], 0
	v_mfma_f32_16x16x32_bf16 v[94:97], v[142:145], v[204:207], 0
	v_mfma_f32_16x16x32_bf16 v[90:93], v[154:157], v[204:207], 0
	v_mfma_f32_16x16x32_bf16 v[78:81], v[142:145], v[212:215], 0
	v_mfma_f32_16x16x32_bf16 v[74:77], v[154:157], v[212:215], 0
	v_mfma_f32_16x16x32_bf16 v[126:129], v[150:153], v[182:185], v[126:129]
	v_mfma_f32_16x16x32_bf16 v[122:125], v[158:161], v[182:185], v[122:125]
	v_mfma_f32_16x16x32_bf16 v[110:113], v[150:153], v[200:203], v[110:113]
	v_mfma_f32_16x16x32_bf16 v[106:109], v[158:161], v[200:203], v[106:109]
	v_mfma_f32_16x16x32_bf16 v[94:97], v[150:153], v[208:211], v[94:97]
	v_mfma_f32_16x16x32_bf16 v[90:93], v[158:161], v[208:211], v[90:93]
	v_mfma_f32_16x16x32_bf16 v[78:81], v[150:153], v[216:219], v[78:81]
	v_mfma_f32_16x16x32_bf16 v[74:77], v[158:161], v[216:219], v[74:77]
	v_mfma_f32_16x16x32_bf16 v[118:121], v[162:165], v[178:181], 0
	v_mfma_f32_16x16x32_bf16 v[114:117], v[170:173], v[178:181], 0
	v_mfma_f32_16x16x32_bf16 v[102:105], v[162:165], v[196:199], 0
	v_mfma_f32_16x16x32_bf16 v[98:101], v[170:173], v[196:199], 0
	v_mfma_f32_16x16x32_bf16 v[86:89], v[162:165], v[204:207], 0
	v_mfma_f32_16x16x32_bf16 v[82:85], v[170:173], v[204:207], 0
	v_mfma_f32_16x16x32_bf16 v[70:73], v[162:165], v[212:215], 0
	v_mfma_f32_16x16x32_bf16 v[66:69], v[170:173], v[212:215], 0
	v_mfma_f32_16x16x32_bf16 v[118:121], v[166:169], v[182:185], v[118:121]
	v_mfma_f32_16x16x32_bf16 v[114:117], v[174:177], v[182:185], v[114:117]
	v_mfma_f32_16x16x32_bf16 v[102:105], v[166:169], v[200:203], v[102:105]
	v_mfma_f32_16x16x32_bf16 v[98:101], v[174:177], v[200:203], v[98:101]
	v_mfma_f32_16x16x32_bf16 v[86:89], v[166:169], v[208:211], v[86:89]
	v_mfma_f32_16x16x32_bf16 v[82:85], v[174:177], v[208:211], v[82:85]
	v_mfma_f32_16x16x32_bf16 v[70:73], v[166:169], v[216:219], v[70:73]
	v_mfma_f32_16x16x32_bf16 v[66:69], v[174:177], v[216:219], v[66:69]
	s_barrier
	s_add_i32 s84, s84, s57
	v_lshl_add_u64 v[220:221], s[52:53], 0, v[0:1]
	s_mov_b32 m0, s84
	ds_read_b128 v[178:181], v148 offset:16384
	ds_read_b128 v[182:185], v148 offset:17408
	ds_read_b128 v[196:199], v148 offset:18432
	ds_read_b128 v[200:203], v148 offset:19456
	ds_read_b128 v[204:207], v148 offset:20480
	ds_read_b128 v[208:211], v148 offset:21504
	ds_read_b128 v[212:215], v148 offset:22528
	ds_read_b128 v[216:219], v148 offset:23552
	global_load_lds_dwordx4 v[220:221], off
	s_add_i32 m0, s84, 0x2000
	s_add_u32 s84, s52, 0x40000
	v_lshl_add_u64 v[222:223], s[52:53], 0, v[132:133]
	s_addc_u32 s85, s53, 0
	s_add_i32 s86, s86, s57
	global_load_lds_dwordx4 v[222:223], off
	v_lshl_add_u64 v[224:225], s[84:85], 0, v[0:1]
	s_mov_b32 m0, s86
	v_lshl_add_u64 v[226:227], s[54:55], 0, v[134:135]
	global_load_lds_dwordx4 v[224:225], off
	v_lshl_add_u64 v[224:225], s[84:85], 0, v[132:133]
	s_add_i32 m0, s86, 0x2000
	s_nop 0
	global_load_lds_dwordx4 v[224:225], off
	v_lshl_add_u64 v[224:225], s[54:55], 0, v[136:137]
	s_mov_b32 m0, s61
	s_nop 0
	global_load_lds_dwordx4 v[224:225], off
	s_mov_b32 m0, s62
	s_nop 0
	global_load_lds_dwordx4 v[226:227], off
	s_waitcnt vmcnt(8)
	s_waitcnt lgkmcnt(0)
	s_barrier
; #define PG8_STAGE(bufoff, gbase, voff) do { _Pragma("unroll") for (int _i = 0; _i < 2; ++_i) \
;         __builtin_amdgcn_global_load_lds((const unsigned*)((const char*)(gbase) + (voff)[_i]), (PG8_LAS unsigned*)(lds + (bufoff) + ldsw + _i * 8192), 16, 0, 0); } while (0)
; #define PG8_LDA(dst, b, h) do { _Pragma("unroll") for (int m = 0; m < 4; ++m) _Pragma("unroll") for (int k = 0; k < 2; ++k) dst[m][k] = *(const PG8_LAS bf16x8*)(lds + PG8_SA(b, h) + aoff + m * 2048 + k * 1024); } while (0)
; #define PG8_LDB(dst, b, h) do { _Pragma("unroll") for (int n = 0; n < 2; ++n) _Pragma("unroll") for (int k = 0; k < 2; ++k) dst[n][k] = *(const PG8_LAS bf16x8*)(lds + PG8_SB(b, h) + boff + n * 2048 + k * 1024); } while (0)
; #define PG8_MMA(ai, bj, At, Bt) do { __builtin_amdgcn_s_setprio(1); _Pragma("unroll") for (int k = 0; k < 2; ++k) _Pragma("unroll") for (int m = 0; m < 4; ++m) _Pragma("unroll") for (int n = 0; n < 2; ++n) \
;         acc[ai][bj][m][n] = __builtin_amdgcn_mfma_f32_16x16x32_bf16(Bt[n][k], At[m][k], acc[ai][bj][m][n], 0, 0, 0); __builtin_amdgcn_s_setprio(0); } while (0)
; #define PG8_WAIT_V(n) asm volatile("s_waitcnt vmcnt(" #n ")" ::: "memory")
; #define PG8_WAIT_L(n) asm volatile("s_waitcnt lgkmcnt(" #n ")" ::: "memory")
; #define PG8_BAR __builtin_amdgcn_s_barrier()
; #define PG8_SCHED __builtin_amdgcn_sched_barrier(0)
; template <class Epi, class Sched, bool ALIGN_EPI = false, bool SP2 = false>
; __device__ __forceinline__ void gemm_phase(PG8_LAS unsigned char* lds, const Gemm g, const Sched& S, const Epi& E, int tid_in) {
;     ...
;             PG8_WAIT_V(8); PG8_WAIT_L(0); PG8_BAR; PG8_MMA(1, 0, At, B0); PG8_MMA(1, 1, At, B1); PG8_BAR; PG8_SCHED;
;             PG8_LDB(B0, 1, 0); PG8_LDB(B1, 1, 1); PG8_SCHED; PG8_LDA(At, 1, 0); PG8_STAGE(PG8_SA(0, 1), a2 + hstep, voffA);
;             PG8_WAIT_V(8); PG8_WAIT_L(0); PG8_BAR; PG8_MMA(0, 0, At, B0); PG8_MMA(0, 1, At, B1); PG8_BAR; PG8_SCHED;
	s_waitcnt lgkmcnt(0)
	v_mfma_f32_16x16x32_bf16 v[62:65], v[142:145], v[178:181], 0
	v_mfma_f32_16x16x32_bf16 v[58:61], v[154:157], v[178:181], 0
	v_mfma_f32_16x16x32_bf16 v[46:49], v[142:145], v[196:199], 0
	v_mfma_f32_16x16x32_bf16 v[42:45], v[154:157], v[196:199], 0
	v_mfma_f32_16x16x32_bf16 v[30:33], v[142:145], v[204:207], 0
	v_mfma_f32_16x16x32_bf16 v[26:29], v[154:157], v[204:207], 0
	v_mfma_f32_16x16x32_bf16 v[14:17], v[142:145], v[212:215], 0
	v_mfma_f32_16x16x32_bf16 v[10:13], v[154:157], v[212:215], 0
	v_mfma_f32_16x16x32_bf16 v[62:65], v[150:153], v[182:185], v[62:65]
	v_mfma_f32_16x16x32_bf16 v[58:61], v[158:161], v[182:185], v[58:61]
	v_mfma_f32_16x16x32_bf16 v[46:49], v[150:153], v[200:203], v[46:49]
	v_mfma_f32_16x16x32_bf16 v[42:45], v[158:161], v[200:203], v[42:45]
	v_mfma_f32_16x16x32_bf16 v[30:33], v[150:153], v[208:211], v[30:33]
	v_mfma_f32_16x16x32_bf16 v[26:29], v[158:161], v[208:211], v[26:29]
	v_mfma_f32_16x16x32_bf16 v[14:17], v[150:153], v[216:219], v[14:17]
	v_mfma_f32_16x16x32_bf16 v[10:13], v[158:161], v[216:219], v[10:13]
	v_mfma_f32_16x16x32_bf16 v[54:57], v[162:165], v[178:181], 0
	v_mfma_f32_16x16x32_bf16 v[50:53], v[170:173], v[178:181], 0
	v_mfma_f32_16x16x32_bf16 v[38:41], v[162:165], v[196:199], 0
	v_mfma_f32_16x16x32_bf16 v[34:37], v[170:173], v[196:199], 0
	v_mfma_f32_16x16x32_bf16 v[22:25], v[162:165], v[204:207], 0
	v_mfma_f32_16x16x32_bf16 v[18:21], v[170:173], v[204:207], 0
	v_mfma_f32_16x16x32_bf16 v[6:9], v[162:165], v[212:215], 0
	v_mfma_f32_16x16x32_bf16 v[2:5], v[170:173], v[212:215], 0
	v_mfma_f32_16x16x32_bf16 v[54:57], v[166:169], v[182:185], v[54:57]
	v_mfma_f32_16x16x32_bf16 v[50:53], v[174:177], v[182:185], v[50:53]
	v_mfma_f32_16x16x32_bf16 v[38:41], v[166:169], v[200:203], v[38:41]
	v_mfma_f32_16x16x32_bf16 v[34:37], v[174:177], v[200:203], v[34:37]
	v_mfma_f32_16x16x32_bf16 v[22:25], v[166:169], v[208:211], v[22:25]
	v_mfma_f32_16x16x32_bf16 v[18:21], v[174:177], v[208:211], v[18:21]
	v_mfma_f32_16x16x32_bf16 v[6:9], v[166:169], v[216:219], v[6:9]
	v_mfma_f32_16x16x32_bf16 v[2:5], v[174:177], v[216:219], v[2:5]
	s_barrier
	s_add_i32 s84, 0, 0x18000
	v_add_u32_e32 v149, s84, v147
	s_add_i32 s85, 0, 0x1c000
	ds_read_b128 v[142:145], v149
	ds_read_b128 v[150:153], v149 offset:1024
	ds_read_b128 v[154:157], v149 offset:2048
	ds_read_b128 v[158:161], v149 offset:3072
	v_add_u32_e32 v149, s85, v147
	ds_read_b128 v[162:165], v149
	ds_read_b128 v[166:169], v149 offset:1024
	ds_read_b128 v[170:173], v149 offset:2048
	ds_read_b128 v[174:177], v149 offset:3072
	s_add_u32 s54, s54, 0x40000
	s_addc_u32 s55, s55, 0
	s_mov_b32 m0, s63
	v_lshl_add_u64 v[228:229], s[54:55], 0, v[136:137]
	ds_read_b128 v[178:181], v148 offset:32768
	ds_read_b128 v[182:185], v148 offset:33792
	ds_read_b128 v[196:199], v148 offset:34816
	ds_read_b128 v[200:203], v148 offset:35840
	ds_read_b128 v[204:207], v148 offset:36864
	ds_read_b128 v[208:211], v148 offset:37888
	ds_read_b128 v[212:215], v148 offset:38912
	ds_read_b128 v[216:219], v148 offset:39936
	global_load_lds_dwordx4 v[228:229], off
	v_lshl_add_u64 v[228:229], s[54:55], 0, v[134:135]
	s_mov_b32 m0, s64
	s_nop 0
	global_load_lds_dwordx4 v[228:229], off
	s_waitcnt vmcnt(8)
	s_waitcnt lgkmcnt(0)
	s_barrier
	s_waitcnt lgkmcnt(0)
	v_mfma_f32_16x16x32_bf16 v[126:129], v[142:145], v[178:181], v[126:129]
	v_mfma_f32_16x16x32_bf16 v[122:125], v[154:157], v[178:181], v[122:125]
	v_mfma_f32_16x16x32_bf16 v[110:113], v[142:145], v[196:199], v[110:113]
	v_mfma_f32_16x16x32_bf16 v[106:109], v[154:157], v[196:199], v[106:109]
	v_mfma_f32_16x16x32_bf16 v[94:97], v[142:145], v[204:207], v[94:97]
	v_mfma_f32_16x16x32_bf16 v[90:93], v[154:157], v[204:207], v[90:93]
	v_mfma_f32_16x16x32_bf16 v[78:81], v[142:145], v[212:215], v[78:81]
	v_mfma_f32_16x16x32_bf16 v[74:77], v[154:157], v[212:215], v[74:77]
	v_mfma_f32_16x16x32_bf16 v[126:129], v[150:153], v[182:185], v[126:129]
	v_mfma_f32_16x16x32_bf16 v[122:125], v[158:161], v[182:185], v[122:125]
	v_mfma_f32_16x16x32_bf16 v[110:113], v[150:153], v[200:203], v[110:113]
	v_mfma_f32_16x16x32_bf16 v[106:109], v[158:161], v[200:203], v[106:109]
	v_mfma_f32_16x16x32_bf16 v[94:97], v[150:153], v[208:211], v[94:97]
	v_mfma_f32_16x16x32_bf16 v[90:93], v[158:161], v[208:211], v[90:93]
	v_mfma_f32_16x16x32_bf16 v[78:81], v[150:153], v[216:219], v[78:81]
	v_mfma_f32_16x16x32_bf16 v[74:77], v[158:161], v[216:219], v[74:77]
	v_mfma_f32_16x16x32_bf16 v[118:121], v[162:165], v[178:181], v[118:121]
	v_mfma_f32_16x16x32_bf16 v[114:117], v[170:173], v[178:181], v[114:117]
	v_mfma_f32_16x16x32_bf16 v[102:105], v[162:165], v[196:199], v[102:105]
	v_mfma_f32_16x16x32_bf16 v[98:101], v[170:173], v[196:199], v[98:101]
	v_mfma_f32_16x16x32_bf16 v[86:89], v[162:165], v[204:207], v[86:89]
	v_mfma_f32_16x16x32_bf16 v[82:85], v[170:173], v[204:207], v[82:85]
	v_mfma_f32_16x16x32_bf16 v[70:73], v[162:165], v[212:215], v[70:73]
	v_mfma_f32_16x16x32_bf16 v[66:69], v[170:173], v[212:215], v[66:69]
	v_mfma_f32_16x16x32_bf16 v[118:121], v[166:169], v[182:185], v[118:121]
	v_mfma_f32_16x16x32_bf16 v[114:117], v[174:177], v[182:185], v[114:117]
	v_mfma_f32_16x16x32_bf16 v[102:105], v[166:169], v[200:203], v[102:105]
	v_mfma_f32_16x16x32_bf16 v[98:101], v[174:177], v[200:203], v[98:101]
	v_mfma_f32_16x16x32_bf16 v[86:89], v[166:169], v[208:211], v[86:89]
	v_mfma_f32_16x16x32_bf16 v[82:85], v[174:177], v[208:211], v[82:85]
	v_mfma_f32_16x16x32_bf16 v[70:73], v[166:169], v[216:219], v[70:73]
	v_mfma_f32_16x16x32_bf16 v[66:69], v[174:177], v[216:219], v[66:69]
	s_barrier
; #define PG8_STAGE(bufoff, gbase, voff) do { _Pragma("unroll") for (int _i = 0; _i < 2; ++_i) \
;         __builtin_amdgcn_global_load_lds((const unsigned*)((const char*)(gbase) + (voff)[_i]), (PG8_LAS unsigned*)(lds + (bufoff) + ldsw + _i * 8192), 16, 0, 0); } while (0)
; #define PG8_LDA(dst, b, h) do { _Pragma("unroll") for (int m = 0; m < 4; ++m) _Pragma("unroll") for (int k = 0; k < 2; ++k) dst[m][k] = *(const PG8_LAS bf16x8*)(lds + PG8_SA(b, h) + aoff + m * 2048 + k * 1024); } while (0)
; #define PG8_LDB(dst, b, h) do { _Pragma("unroll") for (int n = 0; n < 2; ++n) _Pragma("unroll") for (int k = 0; k < 2; ++k) dst[n][k] = *(const PG8_LAS bf16x8*)(lds + PG8_SB(b, h) + boff + n * 2048 + k * 1024); } while (0)
; #define PG8_MMA(ai, bj, At, Bt) do { __builtin_amdgcn_s_setprio(1); _Pragma("unroll") for (int k = 0; k < 2; ++k) _Pragma("unroll") for (int m = 0; m < 4; ++m) _Pragma("unroll") for (int n = 0; n < 2; ++n) \
;         acc[ai][bj][m][n] = __builtin_amdgcn_mfma_f32_16x16x32_bf16(Bt[n][k], At[m][k], acc[ai][bj][m][n], 0, 0, 0); __builtin_amdgcn_s_setprio(0); } while (0)
; #define PG8_WAIT_V(n) asm volatile("s_waitcnt vmcnt(" #n ")" ::: "memory")
; #define PG8_WAIT_L(n) asm volatile("s_waitcnt lgkmcnt(" #n ")" ::: "memory")
; #define PG8_BAR __builtin_amdgcn_s_barrier()
; #define PG8_SCHED __builtin_amdgcn_sched_barrier(0)
; template <class Epi, class Sched, bool ALIGN_EPI = false, bool SP2 = false>
; __device__ __forceinline__ void gemm_phase(PG8_LAS unsigned char* lds, const Gemm g, const Sched& S, const Epi& E, int tid_in) {
;     ...
;             PG8_LDB(B0, 0, 0); PG8_LDB(B1, 0, 1); PG8_SCHED; PG8_LDA(At, 0, 0); PG8_STAGE(PG8_SA(1, 1), a1 + hstep, voffA);
;             PG8_WAIT_V(8); PG8_WAIT_L(0); PG8_BAR; PG8_MMA(0, 0, At, B0); PG8_MMA(0, 1, At, B1); PG8_BAR; PG8_SCHED;
;     ...
;             PG8_LDA(At, 1, 1); PG8_STAGE(PG8_SB(1, 0), b3, voffB); PG8_STAGE(PG8_SB(1, 1), b3 + hstep, voffB); PG8_STAGE(PG8_SA(1, 0), a3, voffA);
;             PG8_WAIT_V(8); PG8_WAIT_L(0); PG8_BAR; PG8_MMA(1, 0, At, B0); PG8_MMA(1, 1, At, B1); PG8_BAR; PG8_SCHED;
	s_add_i32 s54, s84, s57
	v_lshl_add_u64 v[220:221], v[220:221], 0, s[26:27]
	s_mov_b32 m0, s54
	ds_read_b128 v[178:181], v148 offset:49152
	ds_read_b128 v[182:185], v148 offset:50176
	ds_read_b128 v[196:199], v148 offset:51200
	ds_read_b128 v[200:203], v148 offset:52224
	ds_read_b128 v[204:207], v148 offset:53248
	ds_read_b128 v[208:211], v148 offset:54272
	ds_read_b128 v[212:215], v148 offset:55296
	ds_read_b128 v[216:219], v148 offset:56320
	global_load_lds_dwordx4 v[220:221], off
	s_add_i32 m0, s54, 0x2000
	s_add_u32 s52, s52, 0x40080
	v_lshl_add_u64 v[220:221], v[222:223], 0, s[26:27]
	s_addc_u32 s53, s53, 0
	s_add_i32 s54, s85, s57
	global_load_lds_dwordx4 v[220:221], off
	v_lshl_add_u64 v[220:221], s[52:53], 0, v[0:1]
	s_mov_b32 m0, s54
	s_nop 0
	global_load_lds_dwordx4 v[220:221], off
	v_lshl_add_u64 v[220:221], s[52:53], 0, v[132:133]
	s_add_i32 m0, s54, 0x2000
	s_nop 0
	global_load_lds_dwordx4 v[220:221], off
	v_lshl_add_u64 v[220:221], v[224:225], 0, s[26:27]
	s_mov_b32 m0, s69
	s_nop 0
	global_load_lds_dwordx4 v[220:221], off
	v_lshl_add_u64 v[220:221], v[226:227], 0, s[26:27]
	s_mov_b32 m0, s70
	s_nop 0
	global_load_lds_dwordx4 v[220:221], off
	s_waitcnt vmcnt(8)
	s_waitcnt lgkmcnt(0)
	s_barrier
	s_waitcnt lgkmcnt(0)
	v_mfma_f32_16x16x32_bf16 v[62:65], v[142:145], v[178:181], v[62:65]
	v_mfma_f32_16x16x32_bf16 v[58:61], v[154:157], v[178:181], v[58:61]
	v_mfma_f32_16x16x32_bf16 v[46:49], v[142:145], v[196:199], v[46:49]
	v_mfma_f32_16x16x32_bf16 v[42:45], v[154:157], v[196:199], v[42:45]
	v_mfma_f32_16x16x32_bf16 v[30:33], v[142:145], v[204:207], v[30:33]
	v_mfma_f32_16x16x32_bf16 v[26:29], v[154:157], v[204:207], v[26:29]
	v_mfma_f32_16x16x32_bf16 v[14:17], v[142:145], v[212:215], v[14:17]
	v_mfma_f32_16x16x32_bf16 v[10:13], v[154:157], v[212:215], v[10:13]
	v_mfma_f32_16x16x32_bf16 v[62:65], v[150:153], v[182:185], v[62:65]
	v_mfma_f32_16x16x32_bf16 v[58:61], v[158:161], v[182:185], v[58:61]
	v_mfma_f32_16x16x32_bf16 v[46:49], v[150:153], v[200:203], v[46:49]
	v_mfma_f32_16x16x32_bf16 v[42:45], v[158:161], v[200:203], v[42:45]
	v_mfma_f32_16x16x32_bf16 v[30:33], v[150:153], v[208:211], v[30:33]
	v_mfma_f32_16x16x32_bf16 v[26:29], v[158:161], v[208:211], v[26:29]
	v_mfma_f32_16x16x32_bf16 v[14:17], v[150:153], v[216:219], v[14:17]
	v_mfma_f32_16x16x32_bf16 v[10:13], v[158:161], v[216:219], v[10:13]
	v_mfma_f32_16x16x32_bf16 v[54:57], v[162:165], v[178:181], v[54:57]
	v_mfma_f32_16x16x32_bf16 v[50:53], v[170:173], v[178:181], v[50:53]
	v_mfma_f32_16x16x32_bf16 v[38:41], v[162:165], v[196:199], v[38:41]
	v_mfma_f32_16x16x32_bf16 v[34:37], v[170:173], v[196:199], v[34:37]
	v_mfma_f32_16x16x32_bf16 v[22:25], v[162:165], v[204:207], v[22:25]
	v_mfma_f32_16x16x32_bf16 v[18:21], v[170:173], v[204:207], v[18:21]
	v_mfma_f32_16x16x32_bf16 v[6:9], v[162:165], v[212:215], v[6:9]
	v_mfma_f32_16x16x32_bf16 v[2:5], v[170:173], v[212:215], v[2:5]
	v_mfma_f32_16x16x32_bf16 v[54:57], v[166:169], v[182:185], v[54:57]
	v_mfma_f32_16x16x32_bf16 v[50:53], v[174:177], v[182:185], v[50:53]
	v_mfma_f32_16x16x32_bf16 v[38:41], v[166:169], v[200:203], v[38:41]
	v_mfma_f32_16x16x32_bf16 v[34:37], v[174:177], v[200:203], v[34:37]
	v_mfma_f32_16x16x32_bf16 v[22:25], v[166:169], v[208:211], v[22:25]
	v_mfma_f32_16x16x32_bf16 v[18:21], v[174:177], v[208:211], v[18:21]
	v_mfma_f32_16x16x32_bf16 v[6:9], v[166:169], v[216:219], v[6:9]
	v_mfma_f32_16x16x32_bf16 v[2:5], v[174:177], v[216:219], v[2:5]
	s_barrier
	s_add_i32 s83, s83, 2
	s_add_u32 s50, s50, 0x100
	s_addc_u32 s51, s51, 0
	s_add_u32 s81, s81, 0x100
	s_addc_u32 s82, s82, 0
	s_cmp_gt_u32 s83, 13
.LBB0_191:
	s_add_u32 s52, s50, 0xfffc0080
	s_addc_u32 s53, s51, -1
	s_add_i32 s84, 0, 0x10000
	s_cmp_eq_u32 s83, 12
	s_cselect_b32 s55, s41, s53
	s_cselect_b32 s54, s79, s52
	v_add_u32_e32 v149, s84, v147
	s_cselect_b32 s53, s43, s82
	s_cselect_b32 s52, s80, s81
	s_add_i32 s86, 0, 0x14000
	ds_read_b128 v[142:145], v149
	ds_read_b128 v[150:153], v149 offset:1024
	ds_read_b128 v[154:157], v149 offset:2048
	ds_read_b128 v[158:161], v149 offset:3072
	v_add_u32_e32 v149, s86, v147
	ds_read_b128 v[162:165], v149
	ds_read_b128 v[166:169], v149 offset:1024
	ds_read_b128 v[170:173], v149 offset:2048
	ds_read_b128 v[174:177], v149 offset:3072
	v_lshl_add_u64 v[220:221], s[50:51], 0, v[138:139]
	s_add_i32 m0, s61, 0xc000
	ds_read_b128 v[178:181], v148
	ds_read_b128 v[182:185], v148 offset:1024
	ds_read_b128 v[196:199], v148 offset:2048
	ds_read_b128 v[200:203], v148 offset:3072
	ds_read_b128 v[204:207], v148 offset:4096
	ds_read_b128 v[208:211], v148 offset:5120
	ds_read_b128 v[212:215], v148 offset:6144
	ds_read_b128 v[216:219], v148 offset:7168
	global_load_lds_dwordx4 v[220:221], off
	v_lshl_add_u64 v[220:221], s[50:51], 0, v[140:141]
	s_add_i32 m0, s61, 0xe000
	s_nop 0
	global_load_lds_dwordx4 v[220:221], off
	s_waitcnt vmcnt(8)
	s_waitcnt lgkmcnt(0)
	s_barrier
; #define PG8_STAGE(bufoff, gbase, voff) do { _Pragma("unroll") for (int _i = 0; _i < 2; ++_i) \
;         __builtin_amdgcn_global_load_lds((const unsigned*)((const char*)(gbase) + (voff)[_i]), (PG8_LAS unsigned*)(lds + (bufoff) + ldsw + _i * 8192), 16, 0, 0); } while (0)
; #define PG8_LDA(dst, b, h) do { _Pragma("unroll") for (int m = 0; m < 4; ++m) _Pragma("unroll") for (int k = 0; k < 2; ++k) dst[m][k] = *(const PG8_LAS bf16x8*)(lds + PG8_SA(b, h) + aoff + m * 2048 + k * 1024); } while (0)
; #define PG8_MMA(ai, bj, At, Bt) do { __builtin_amdgcn_s_setprio(1); _Pragma("unroll") for (int k = 0; k < 2; ++k) _Pragma("unroll") for (int m = 0; m < 4; ++m) _Pragma("unroll") for (int n = 0; n < 2; ++n) \
;         acc[ai][bj][m][n] = __builtin_amdgcn_mfma_f32_16x16x32_bf16(Bt[n][k], At[m][k], acc[ai][bj][m][n], 0, 0, 0); __builtin_amdgcn_s_setprio(0); } while (0)
; #define PG8_WAIT_V(n) asm volatile("s_waitcnt vmcnt(" #n ")" ::: "memory")
; #define PG8_WAIT_L(n) asm volatile("s_waitcnt lgkmcnt(" #n ")" ::: "memory")
; #define PG8_BAR __builtin_amdgcn_s_barrier()
; #define PG8_SCHED __builtin_amdgcn_sched_barrier(0)
; template <class Epi, class Sched, bool ALIGN_EPI = false, bool SP2 = false>
; __device__ __forceinline__ void gemm_phase(PG8_LAS unsigned char* lds, const Gemm g, const Sched& S, const Epi& E, int tid_in) {
;     ...
;             PG8_WAIT_V(8); PG8_WAIT_L(0); PG8_BAR; PG8_MMA(0, 0, At, B0); PG8_MMA(0, 1, At, B1); PG8_BAR; PG8_SCHED;
;             PG8_LDA(At, 0, 1); PG8_STAGE(PG8_SB(0, 0), b2, voffB); PG8_STAGE(PG8_SB(0, 1), b2 + hstep, voffB); PG8_STAGE(PG8_SA(0, 0), a2, voffA);
;             PG8_WAIT_V(8); PG8_WAIT_L(0); PG8_BAR; PG8_MMA(1, 0, At, B0); PG8_MMA(1, 1, At, B1); PG8_BAR; PG8_SCHED;
	s_waitcnt lgkmcnt(0)
	v_mfma_f32_16x16x32_bf16 v[126:129], v[142:145], v[178:181], v[126:129]
	v_mfma_f32_16x16x32_bf16 v[122:125], v[154:157], v[178:181], v[122:125]
	v_mfma_f32_16x16x32_bf16 v[110:113], v[142:145], v[196:199], v[110:113]
	v_mfma_f32_16x16x32_bf16 v[106:109], v[154:157], v[196:199], v[106:109]
	v_mfma_f32_16x16x32_bf16 v[94:97], v[142:145], v[204:207], v[94:97]
	v_mfma_f32_16x16x32_bf16 v[90:93], v[154:157], v[204:207], v[90:93]
	v_mfma_f32_16x16x32_bf16 v[78:81], v[142:145], v[212:215], v[78:81]
	v_mfma_f32_16x16x32_bf16 v[74:77], v[154:157], v[212:215], v[74:77]
	v_mfma_f32_16x16x32_bf16 v[126:129], v[150:153], v[182:185], v[126:129]
	v_mfma_f32_16x16x32_bf16 v[122:125], v[158:161], v[182:185], v[122:125]
	v_mfma_f32_16x16x32_bf16 v[110:113], v[150:153], v[200:203], v[110:113]
	v_mfma_f32_16x16x32_bf16 v[106:109], v[158:161], v[200:203], v[106:109]
	v_mfma_f32_16x16x32_bf16 v[94:97], v[150:153], v[208:211], v[94:97]
	v_mfma_f32_16x16x32_bf16 v[90:93], v[158:161], v[208:211], v[90:93]
	v_mfma_f32_16x16x32_bf16 v[78:81], v[150:153], v[216:219], v[78:81]
	v_mfma_f32_16x16x32_bf16 v[74:77], v[158:161], v[216:219], v[74:77]
	v_mfma_f32_16x16x32_bf16 v[118:121], v[162:165], v[178:181], v[118:121]
	v_mfma_f32_16x16x32_bf16 v[114:117], v[170:173], v[178:181], v[114:117]
	v_mfma_f32_16x16x32_bf16 v[102:105], v[162:165], v[196:199], v[102:105]
	v_mfma_f32_16x16x32_bf16 v[98:101], v[170:173], v[196:199], v[98:101]
	v_mfma_f32_16x16x32_bf16 v[86:89], v[162:165], v[204:207], v[86:89]
	v_mfma_f32_16x16x32_bf16 v[82:85], v[170:173], v[204:207], v[82:85]
	v_mfma_f32_16x16x32_bf16 v[70:73], v[162:165], v[212:215], v[70:73]
	v_mfma_f32_16x16x32_bf16 v[66:69], v[170:173], v[212:215], v[66:69]
	v_mfma_f32_16x16x32_bf16 v[118:121], v[166:169], v[182:185], v[118:121]
	v_mfma_f32_16x16x32_bf16 v[114:117], v[174:177], v[182:185], v[114:117]
	v_mfma_f32_16x16x32_bf16 v[102:105], v[166:169], v[200:203], v[102:105]
	v_mfma_f32_16x16x32_bf16 v[98:101], v[174:177], v[200:203], v[98:101]
	v_mfma_f32_16x16x32_bf16 v[86:89], v[166:169], v[208:211], v[86:89]
	v_mfma_f32_16x16x32_bf16 v[82:85], v[174:177], v[208:211], v[82:85]
	v_mfma_f32_16x16x32_bf16 v[70:73], v[166:169], v[216:219], v[70:73]
	v_mfma_f32_16x16x32_bf16 v[66:69], v[174:177], v[216:219], v[66:69]
	s_barrier
	s_add_i32 s84, s84, s57
	v_lshl_add_u64 v[220:221], s[52:53], 0, v[0:1]
	s_mov_b32 m0, s84
	ds_read_b128 v[178:181], v148 offset:16384
	ds_read_b128 v[182:185], v148 offset:17408
	ds_read_b128 v[196:199], v148 offset:18432
	ds_read_b128 v[200:203], v148 offset:19456
	ds_read_b128 v[204:207], v148 offset:20480
	ds_read_b128 v[208:211], v148 offset:21504
	ds_read_b128 v[212:215], v148 offset:22528
	ds_read_b128 v[216:219], v148 offset:23552
	global_load_lds_dwordx4 v[220:221], off
	s_add_i32 m0, s84, 0x2000
	s_add_u32 s84, s52, 0x40000
	v_lshl_add_u64 v[222:223], s[52:53], 0, v[132:133]
	s_addc_u32 s85, s53, 0
	s_add_i32 s86, s86, s57
	global_load_lds_dwordx4 v[222:223], off
	v_lshl_add_u64 v[224:225], s[84:85], 0, v[0:1]
	s_mov_b32 m0, s86
	v_lshl_add_u64 v[226:227], s[54:55], 0, v[134:135]
	global_load_lds_dwordx4 v[224:225], off
	v_lshl_add_u64 v[224:225], s[84:85], 0, v[132:133]
	s_add_i32 m0, s86, 0x2000
	s_nop 0
	global_load_lds_dwordx4 v[224:225], off
	v_lshl_add_u64 v[224:225], s[54:55], 0, v[136:137]
	s_mov_b32 m0, s61
	s_nop 0
	global_load_lds_dwordx4 v[224:225], off
	s_mov_b32 m0, s62
	s_nop 0
	global_load_lds_dwordx4 v[226:227], off
	s_waitcnt vmcnt(8)
	s_waitcnt lgkmcnt(0)
	s_barrier
	s_waitcnt lgkmcnt(0)
	v_mfma_f32_16x16x32_bf16 v[62:65], v[142:145], v[178:181], v[62:65]
	v_mfma_f32_16x16x32_bf16 v[58:61], v[154:157], v[178:181], v[58:61]
	v_mfma_f32_16x16x32_bf16 v[46:49], v[142:145], v[196:199], v[46:49]
	v_mfma_f32_16x16x32_bf16 v[42:45], v[154:157], v[196:199], v[42:45]
	v_mfma_f32_16x16x32_bf16 v[30:33], v[142:145], v[204:207], v[30:33]
	v_mfma_f32_16x16x32_bf16 v[26:29], v[154:157], v[204:207], v[26:29]
	v_mfma_f32_16x16x32_bf16 v[14:17], v[142:145], v[212:215], v[14:17]
	v_mfma_f32_16x16x32_bf16 v[10:13], v[154:157], v[212:215], v[10:13]
	v_mfma_f32_16x16x32_bf16 v[62:65], v[150:153], v[182:185], v[62:65]
	v_mfma_f32_16x16x32_bf16 v[58:61], v[158:161], v[182:185], v[58:61]
	v_mfma_f32_16x16x32_bf16 v[46:49], v[150:153], v[200:203], v[46:49]
	v_mfma_f32_16x16x32_bf16 v[42:45], v[158:161], v[200:203], v[42:45]
	v_mfma_f32_16x16x32_bf16 v[30:33], v[150:153], v[208:211], v[30:33]
	v_mfma_f32_16x16x32_bf16 v[26:29], v[158:161], v[208:211], v[26:29]
	v_mfma_f32_16x16x32_bf16 v[14:17], v[150:153], v[216:219], v[14:17]
	v_mfma_f32_16x16x32_bf16 v[10:13], v[158:161], v[216:219], v[10:13]
	v_mfma_f32_16x16x32_bf16 v[54:57], v[162:165], v[178:181], v[54:57]
	v_mfma_f32_16x16x32_bf16 v[50:53], v[170:173], v[178:181], v[50:53]
	v_mfma_f32_16x16x32_bf16 v[38:41], v[162:165], v[196:199], v[38:41]
	v_mfma_f32_16x16x32_bf16 v[34:37], v[170:173], v[196:199], v[34:37]
	v_mfma_f32_16x16x32_bf16 v[22:25], v[162:165], v[204:207], v[22:25]
	v_mfma_f32_16x16x32_bf16 v[18:21], v[170:173], v[204:207], v[18:21]
	v_mfma_f32_16x16x32_bf16 v[6:9], v[162:165], v[212:215], v[6:9]
	v_mfma_f32_16x16x32_bf16 v[2:5], v[170:173], v[212:215], v[2:5]
	v_mfma_f32_16x16x32_bf16 v[54:57], v[166:169], v[182:185], v[54:57]
	v_mfma_f32_16x16x32_bf16 v[50:53], v[174:177], v[182:185], v[50:53]
	v_mfma_f32_16x16x32_bf16 v[38:41], v[166:169], v[200:203], v[38:41]
	v_mfma_f32_16x16x32_bf16 v[34:37], v[174:177], v[200:203], v[34:37]
	v_mfma_f32_16x16x32_bf16 v[22:25], v[166:169], v[208:211], v[22:25]
	v_mfma_f32_16x16x32_bf16 v[18:21], v[174:177], v[208:211], v[18:21]
	v_mfma_f32_16x16x32_bf16 v[6:9], v[166:169], v[216:219], v[6:9]
	v_mfma_f32_16x16x32_bf16 v[2:5], v[174:177], v[216:219], v[2:5]
	s_barrier
; #define PG8_STAGE(bufoff, gbase, voff) do { _Pragma("unroll") for (int _i = 0; _i < 2; ++_i) \
;         __builtin_amdgcn_global_load_lds((const unsigned*)((const char*)(gbase) + (voff)[_i]), (PG8_LAS unsigned*)(lds + (bufoff) + ldsw + _i * 8192), 16, 0, 0); } while (0)
; #define PG8_LDA(dst, b, h) do { _Pragma("unroll") for (int m = 0; m < 4; ++m) _Pragma("unroll") for (int k = 0; k < 2; ++k) dst[m][k] = *(const PG8_LAS bf16x8*)(lds + PG8_SA(b, h) + aoff + m * 2048 + k * 1024); } while (0)
; #define PG8_LDB(dst, b, h) do { _Pragma("unroll") for (int n = 0; n < 2; ++n) _Pragma("unroll") for (int k = 0; k < 2; ++k) dst[n][k] = *(const PG8_LAS bf16x8*)(lds + PG8_SB(b, h) + boff + n * 2048 + k * 1024); } while (0)
; #define PG8_MMA(ai, bj, At, Bt) do { __builtin_amdgcn_s_setprio(1); _Pragma("unroll") for (int k = 0; k < 2; ++k) _Pragma("unroll") for (int m = 0; m < 4; ++m) _Pragma("unroll") for (int n = 0; n < 2; ++n) \
;         acc[ai][bj][m][n] = __builtin_amdgcn_mfma_f32_16x16x32_bf16(Bt[n][k], At[m][k], acc[ai][bj][m][n], 0, 0, 0); __builtin_amdgcn_s_setprio(0); } while (0)
; #define PG8_WAIT_V(n) asm volatile("s_waitcnt vmcnt(" #n ")" ::: "memory")
; #define PG8_WAIT_L(n) asm volatile("s_waitcnt lgkmcnt(" #n ")" ::: "memory")
; #define PG8_BAR __builtin_amdgcn_s_barrier()
; #define PG8_SCHED __builtin_amdgcn_sched_barrier(0)
; template <class Epi, class Sched, bool ALIGN_EPI = false, bool SP2 = false>
; __device__ __forceinline__ void gemm_phase(PG8_LAS unsigned char* lds, const Gemm g, const Sched& S, const Epi& E, int tid_in) {
;     ...
;             PG8_LDB(B0, 1, 0); PG8_LDB(B1, 1, 1); PG8_SCHED; PG8_LDA(At, 1, 0); PG8_STAGE(PG8_SA(0, 1), a2 + hstep, voffA);
;             PG8_WAIT_V(8); PG8_WAIT_L(0); PG8_BAR; PG8_MMA(0, 0, At, B0); PG8_MMA(0, 1, At, B1); PG8_BAR; PG8_SCHED;
	s_add_i32 s84, 0, 0x18000
	v_add_u32_e32 v149, s84, v147
	s_add_i32 s85, 0, 0x1c000
	ds_read_b128 v[142:145], v149
	ds_read_b128 v[150:153], v149 offset:1024
	ds_read_b128 v[154:157], v149 offset:2048
	ds_read_b128 v[158:161], v149 offset:3072
	v_add_u32_e32 v149, s85, v147
	ds_read_b128 v[162:165], v149
	ds_read_b128 v[166:169], v149 offset:1024
	ds_read_b128 v[170:173], v149 offset:2048
	ds_read_b128 v[174:177], v149 offset:3072
	s_add_u32 s54, s54, 0x40000
	s_addc_u32 s55, s55, 0
	s_mov_b32 m0, s63
	v_lshl_add_u64 v[228:229], s[54:55], 0, v[136:137]
	ds_read_b128 v[178:181], v148 offset:32768
	ds_read_b128 v[182:185], v148 offset:33792
	ds_read_b128 v[196:199], v148 offset:34816
	ds_read_b128 v[200:203], v148 offset:35840
	ds_read_b128 v[204:207], v148 offset:36864
	ds_read_b128 v[208:211], v148 offset:37888
	ds_read_b128 v[212:215], v148 offset:38912
	ds_read_b128 v[216:219], v148 offset:39936
	global_load_lds_dwordx4 v[228:229], off
	v_lshl_add_u64 v[228:229], s[54:55], 0, v[134:135]
	s_mov_b32 m0, s64
	s_nop 0
	global_load_lds_dwordx4 v[228:229], off
	s_waitcnt vmcnt(8)
	s_waitcnt lgkmcnt(0)
	s_barrier
	s_waitcnt lgkmcnt(0)
	v_mfma_f32_16x16x32_bf16 v[126:129], v[142:145], v[178:181], v[126:129]
	v_mfma_f32_16x16x32_bf16 v[122:125], v[154:157], v[178:181], v[122:125]
	v_mfma_f32_16x16x32_bf16 v[110:113], v[142:145], v[196:199], v[110:113]
	v_mfma_f32_16x16x32_bf16 v[106:109], v[154:157], v[196:199], v[106:109]
	v_mfma_f32_16x16x32_bf16 v[94:97], v[142:145], v[204:207], v[94:97]
	v_mfma_f32_16x16x32_bf16 v[90:93], v[154:157], v[204:207], v[90:93]
	v_mfma_f32_16x16x32_bf16 v[78:81], v[142:145], v[212:215], v[78:81]
	v_mfma_f32_16x16x32_bf16 v[74:77], v[154:157], v[212:215], v[74:77]
	v_mfma_f32_16x16x32_bf16 v[126:129], v[150:153], v[182:185], v[126:129]
	v_mfma_f32_16x16x32_bf16 v[122:125], v[158:161], v[182:185], v[122:125]
	v_mfma_f32_16x16x32_bf16 v[110:113], v[150:153], v[200:203], v[110:113]
	v_mfma_f32_16x16x32_bf16 v[106:109], v[158:161], v[200:203], v[106:109]
	v_mfma_f32_16x16x32_bf16 v[94:97], v[150:153], v[208:211], v[94:97]
	v_mfma_f32_16x16x32_bf16 v[90:93], v[158:161], v[208:211], v[90:93]
	v_mfma_f32_16x16x32_bf16 v[78:81], v[150:153], v[216:219], v[78:81]
	v_mfma_f32_16x16x32_bf16 v[74:77], v[158:161], v[216:219], v[74:77]
	v_mfma_f32_16x16x32_bf16 v[118:121], v[162:165], v[178:181], v[118:121]
	v_mfma_f32_16x16x32_bf16 v[114:117], v[170:173], v[178:181], v[114:117]
	v_mfma_f32_16x16x32_bf16 v[102:105], v[162:165], v[196:199], v[102:105]
	v_mfma_f32_16x16x32_bf16 v[98:101], v[170:173], v[196:199], v[98:101]
	v_mfma_f32_16x16x32_bf16 v[86:89], v[162:165], v[204:207], v[86:89]
	v_mfma_f32_16x16x32_bf16 v[82:85], v[170:173], v[204:207], v[82:85]
	v_mfma_f32_16x16x32_bf16 v[70:73], v[162:165], v[212:215], v[70:73]
	v_mfma_f32_16x16x32_bf16 v[66:69], v[170:173], v[212:215], v[66:69]
	v_mfma_f32_16x16x32_bf16 v[118:121], v[166:169], v[182:185], v[118:121]
	v_mfma_f32_16x16x32_bf16 v[114:117], v[174:177], v[182:185], v[114:117]
	v_mfma_f32_16x16x32_bf16 v[102:105], v[166:169], v[200:203], v[102:105]
	v_mfma_f32_16x16x32_bf16 v[98:101], v[174:177], v[200:203], v[98:101]
	v_mfma_f32_16x16x32_bf16 v[86:89], v[166:169], v[208:211], v[86:89]
	v_mfma_f32_16x16x32_bf16 v[82:85], v[174:177], v[208:211], v[82:85]
	v_mfma_f32_16x16x32_bf16 v[70:73], v[166:169], v[216:219], v[70:73]
	v_mfma_f32_16x16x32_bf16 v[66:69], v[174:177], v[216:219], v[66:69]
	s_barrier
; #define PG8_STAGE(bufoff, gbase, voff) do { _Pragma("unroll") for (int _i = 0; _i < 2; ++_i) \
;         __builtin_amdgcn_global_load_lds((const unsigned*)((const char*)(gbase) + (voff)[_i]), (PG8_LAS unsigned*)(lds + (bufoff) + ldsw + _i * 8192), 16, 0, 0); } while (0)
; #define PG8_LDA(dst, b, h) do { _Pragma("unroll") for (int m = 0; m < 4; ++m) _Pragma("unroll") for (int k = 0; k < 2; ++k) dst[m][k] = *(const PG8_LAS bf16x8*)(lds + PG8_SA(b, h) + aoff + m * 2048 + k * 1024); } while (0)
; #define PG8_MMA(ai, bj, At, Bt) do { __builtin_amdgcn_s_setprio(1); _Pragma("unroll") for (int k = 0; k < 2; ++k) _Pragma("unroll") for (int m = 0; m < 4; ++m) _Pragma("unroll") for (int n = 0; n < 2; ++n) \
;         acc[ai][bj][m][n] = __builtin_amdgcn_mfma_f32_16x16x32_bf16(Bt[n][k], At[m][k], acc[ai][bj][m][n], 0, 0, 0); __builtin_amdgcn_s_setprio(0); } while (0)
; #define PG8_WAIT_V(n) asm volatile("s_waitcnt vmcnt(" #n ")" ::: "memory")
; #define PG8_WAIT_L(n) asm volatile("s_waitcnt lgkmcnt(" #n ")" ::: "memory")
; #define PG8_BAR __builtin_amdgcn_s_barrier()
; #define PG8_SCHED __builtin_amdgcn_sched_barrier(0)
; template <class Epi, class Sched, bool ALIGN_EPI = false, bool SP2 = false>
; __device__ __forceinline__ void gemm_phase(PG8_LAS unsigned char* lds, const Gemm g, const Sched& S, const Epi& E, int tid_in) {
;     ...
;             PG8_LDA(At, 1, 1); PG8_STAGE(PG8_SB(1, 0), b3, voffB); PG8_STAGE(PG8_SB(1, 1), b3 + hstep, voffB); PG8_STAGE(PG8_SA(1, 0), a3, voffA);
;             PG8_WAIT_V(8); PG8_WAIT_L(0); PG8_BAR; PG8_MMA(1, 0, At, B0); PG8_MMA(1, 1, At, B1); PG8_BAR; PG8_SCHED;
;     ...
;         if constexpr (ALIGN_EPI) { if (wr == 0) PG8_BAR; }
	s_add_i32 s54, s84, s57
	v_lshl_add_u64 v[220:221], v[220:221], 0, s[26:27]
	s_mov_b32 m0, s54
	ds_read_b128 v[178:181], v148 offset:49152
	ds_read_b128 v[182:185], v148 offset:50176
	ds_read_b128 v[196:199], v148 offset:51200
	ds_read_b128 v[200:203], v148 offset:52224
	ds_read_b128 v[204:207], v148 offset:53248
	ds_read_b128 v[208:211], v148 offset:54272
	ds_read_b128 v[212:215], v148 offset:55296
	ds_read_b128 v[216:219], v148 offset:56320
	global_load_lds_dwordx4 v[220:221], off
	s_add_i32 m0, s54, 0x2000
	s_add_u32 s52, s52, 0x40080
	v_lshl_add_u64 v[220:221], v[222:223], 0, s[26:27]
	s_addc_u32 s53, s53, 0
	s_add_i32 s54, s85, s57
	global_load_lds_dwordx4 v[220:221], off
	v_lshl_add_u64 v[220:221], s[52:53], 0, v[0:1]
	s_mov_b32 m0, s54
	s_nop 0
	global_load_lds_dwordx4 v[220:221], off
	v_lshl_add_u64 v[220:221], s[52:53], 0, v[132:133]
	s_add_i32 m0, s54, 0x2000
	s_nop 0
	global_load_lds_dwordx4 v[220:221], off
	v_lshl_add_u64 v[220:221], v[224:225], 0, s[26:27]
	s_mov_b32 m0, s69
	s_nop 0
	global_load_lds_dwordx4 v[220:221], off
	v_lshl_add_u64 v[220:221], v[226:227], 0, s[26:27]
	s_mov_b32 m0, s70
	s_nop 0
	global_load_lds_dwordx4 v[220:221], off
	s_waitcnt vmcnt(8)
	s_waitcnt lgkmcnt(0)
	s_barrier
	s_waitcnt lgkmcnt(0)
	v_mfma_f32_16x16x32_bf16 v[62:65], v[142:145], v[178:181], v[62:65]
	v_mfma_f32_16x16x32_bf16 v[58:61], v[154:157], v[178:181], v[58:61]
	v_mfma_f32_16x16x32_bf16 v[46:49], v[142:145], v[196:199], v[46:49]
	v_mfma_f32_16x16x32_bf16 v[42:45], v[154:157], v[196:199], v[42:45]
	v_mfma_f32_16x16x32_bf16 v[30:33], v[142:145], v[204:207], v[30:33]
	v_mfma_f32_16x16x32_bf16 v[26:29], v[154:157], v[204:207], v[26:29]
	v_mfma_f32_16x16x32_bf16 v[14:17], v[142:145], v[212:215], v[14:17]
	v_mfma_f32_16x16x32_bf16 v[10:13], v[154:157], v[212:215], v[10:13]
	v_mfma_f32_16x16x32_bf16 v[62:65], v[150:153], v[182:185], v[62:65]
	v_mfma_f32_16x16x32_bf16 v[58:61], v[158:161], v[182:185], v[58:61]
	v_mfma_f32_16x16x32_bf16 v[46:49], v[150:153], v[200:203], v[46:49]
	v_mfma_f32_16x16x32_bf16 v[42:45], v[158:161], v[200:203], v[42:45]
	v_mfma_f32_16x16x32_bf16 v[30:33], v[150:153], v[208:211], v[30:33]
	v_mfma_f32_16x16x32_bf16 v[26:29], v[158:161], v[208:211], v[26:29]
	v_mfma_f32_16x16x32_bf16 v[14:17], v[150:153], v[216:219], v[14:17]
	v_mfma_f32_16x16x32_bf16 v[10:13], v[158:161], v[216:219], v[10:13]
	v_mfma_f32_16x16x32_bf16 v[54:57], v[162:165], v[178:181], v[54:57]
	v_mfma_f32_16x16x32_bf16 v[50:53], v[170:173], v[178:181], v[50:53]
	v_mfma_f32_16x16x32_bf16 v[38:41], v[162:165], v[196:199], v[38:41]
	v_mfma_f32_16x16x32_bf16 v[34:37], v[170:173], v[196:199], v[34:37]
	v_mfma_f32_16x16x32_bf16 v[22:25], v[162:165], v[204:207], v[22:25]
	v_mfma_f32_16x16x32_bf16 v[18:21], v[170:173], v[204:207], v[18:21]
	v_mfma_f32_16x16x32_bf16 v[6:9], v[162:165], v[212:215], v[6:9]
	v_mfma_f32_16x16x32_bf16 v[2:5], v[170:173], v[212:215], v[2:5]
	v_mfma_f32_16x16x32_bf16 v[54:57], v[166:169], v[182:185], v[54:57]
	v_mfma_f32_16x16x32_bf16 v[50:53], v[174:177], v[182:185], v[50:53]
	v_mfma_f32_16x16x32_bf16 v[38:41], v[166:169], v[200:203], v[38:41]
	v_mfma_f32_16x16x32_bf16 v[34:37], v[174:177], v[200:203], v[34:37]
	v_mfma_f32_16x16x32_bf16 v[22:25], v[166:169], v[208:211], v[22:25]
	v_mfma_f32_16x16x32_bf16 v[18:21], v[174:177], v[208:211], v[18:21]
	v_mfma_f32_16x16x32_bf16 v[6:9], v[166:169], v[216:219], v[6:9]
	v_mfma_f32_16x16x32_bf16 v[2:5], v[174:177], v[216:219], v[2:5]
	s_barrier
	s_add_i32 s83, s83, 2
	s_add_u32 s50, s50, 0x100
	s_addc_u32 s51, s51, 0
	s_add_u32 s81, s81, 0x100
	s_addc_u32 s82, s82, 0
	s_cmp_gt_u32 s83, 13
	s_cbranch_scc0 .LBB0_191
	s_and_b64 vcc, exec, s[38:39]
	s_cbranch_vccz .LBB0_194
	s_barrier

; #define PG8_STAGE(bufoff, gbase, voff) do { _Pragma("unroll") for (int _i = 0; _i < 2; ++_i) \
;         __builtin_amdgcn_global_load_lds((const unsigned*)((const char*)(gbase) + (voff)[_i]), (PG8_LAS unsigned*)(lds + (bufoff) + ldsw + _i * 8192), 16, 0, 0); } while (0)
; #define PG8_LDA(dst, b, h) do { _Pragma("unroll") for (int m = 0; m < 4; ++m) _Pragma("unroll") for (int k = 0; k < 2; ++k) dst[m][k] = *(const PG8_LAS bf16x8*)(lds + PG8_SA(b, h) + aoff + m * 2048 + k * 1024); } while (0)
; #define PG8_LDB(dst, b, h) do { _Pragma("unroll") for (int n = 0; n < 2; ++n) _Pragma("unroll") for (int k = 0; k < 2; ++k) dst[n][k] = *(const PG8_LAS bf16x8*)(lds + PG8_SB(b, h) + boff + n * 2048 + k * 1024); } while (0)
; #define PG8_WAIT_V(n) asm volatile("s_waitcnt vmcnt(" #n ")" ::: "memory")
; #define PG8_WAIT_L(n) asm volatile("s_waitcnt lgkmcnt(" #n ")" ::: "memory")
; #define PG8_BAR __builtin_amdgcn_s_barrier()
; #define PG8_SCHED __builtin_amdgcn_sched_barrier(0)
; template <class Epi, class Sched, bool ALIGN_EPI = false, bool SP2 = false>
; __device__ __forceinline__ void gemm_phase(PG8_LAS unsigned char* lds, const Gemm g, const Sched& S, const Epi& E, int tid_in) {
;     ...
;         const char* nA = has_next ? (const char*)g.A + (size_t)nxt.pm * tstep : cA; const char* nB = has_next ? (const char*)g.Bt + (size_t)nxt.pn * tstep : cB;
;         for (int t = 0; t < nt; t += 2) {
;             const bool last = (t == nt - 2);
;             const char* a1 = cA + (size_t)(t + 1) * kstep;
;             const char* a2 = last ? nA : cA + (size_t)(t + 2) * kstep; const char* b2 = last ? nB : cB + (size_t)(t + 2) * kstep;
;             const char* a3 = a2 + kstep; const char* b3 = b2 + kstep;
;             if (last && has_next) S.a_ready(nxt);
;             if constexpr (SP2) {
;             PG8_LDB(B0, 0, 0); PG8_LDB(B1, 0, 1); PG8_SCHED; PG8_LDA(At, 0, 0); PG8_STAGE(PG8_SA(1, 1), a1 + hstep, voffA);
;             PG8_WAIT_V(8); PG8_WAIT_L(0); PG8_BAR; PG8_MMA(0, 0, At, B0); PG8_MMA(0, 1, At, B1); PG8_BAR; PG8_SCHED;
;             PG8_LDA(At, 0, 1); PG8_STAGE(PG8_SB(0, 0), b2, voffB); PG8_STAGE(PG8_SB(0, 1), b2 + hstep, voffB); PG8_STAGE(PG8_SA(0, 0), a2, voffA);
;             PG8_WAIT_V(8); PG8_WAIT_L(0); PG8_BAR; PG8_MMA(1, 0, At, B0); PG8_MMA(1, 1, At, B1); PG8_BAR; PG8_SCHED;
.LBB0_205:
	s_ashr_i32 s45, s44, 31
	s_lshl_b64 s[46:47], s[44:45], 19
	s_add_u32 s46, s28, s46
	s_addc_u32 s47, s29, s47
	s_and_b64 s[48:49], s[52:53], exec
	s_cselect_b32 s45, s47, s57
	s_cselect_b32 s76, s46, s56
	s_ashr_i32 s43, s42, 31
	s_lshl_b64 s[48:49], s[42:43], 19
	s_add_u32 s48, s59, s48
	s_addc_u32 s49, s60, s49
	s_and_b64 s[52:53], s[52:53], exec
	s_cselect_b32 s43, s49, s55
	s_cselect_b32 s77, s48, s54
	s_add_u32 s52, s56, 0x40080
	s_addc_u32 s53, s57, 0
	s_add_u32 s78, s54, 0x100
	s_addc_u32 s79, s55, 0
	s_mov_b32 s80, -2
	s_add_u32 s33, s52, 0xfffc0080
	s_addc_u32 s54, s53, -1
	s_add_i32 s84, 0, 0x10000
	s_cmp_eq_u32 s80, 12
	s_cselect_b32 s57, s45, s54
	s_cselect_b32 s56, s76, s33
	s_cselect_b32 s55, s43, s79
	s_cselect_b32 s54, s77, s78
	s_add_i32 s85, 0, 0x14000
	v_add_u32_e32 v142, s84, v162
	v_add_u32_e32 v172, s85, v162
	ds_read_b128 v[130:133], v142
	ds_read_b128 v[134:137], v142 offset:1024
	ds_read_b128 v[138:141], v142 offset:2048
	ds_read_b128 v[142:145], v142 offset:3072
	ds_read_b128 v[156:159], v172
	ds_read_b128 v[164:167], v172 offset:1024
	ds_read_b128 v[168:171], v172 offset:2048
	ds_read_b128 v[172:175], v172 offset:3072
	v_lshl_add_u64 v[184:185], s[52:53], 0, v[152:153]
	s_add_i32 m0, s62, 0xc000
	ds_read_b128 v[176:179], v163
	ds_read_b128 v[180:183], v163 offset:1024
	ds_read_b128 v[196:199], v163 offset:2048
	ds_read_b128 v[200:203], v163 offset:3072
	ds_read_b128 v[204:207], v163 offset:4096
	ds_read_b128 v[208:211], v163 offset:5120
	ds_read_b128 v[212:215], v163 offset:6144
	ds_read_b128 v[216:219], v163 offset:7168
	global_load_lds_dwordx4 v[184:185], off
	v_lshl_add_u64 v[184:185], s[52:53], 0, v[154:155]
	s_add_i32 m0, s62, 0xe000
	s_nop 0
	global_load_lds_dwordx4 v[184:185], off
	s_waitcnt vmcnt(8)
	s_waitcnt lgkmcnt(0)
	s_barrier
	s_waitcnt lgkmcnt(0)
	v_mfma_f32_16x16x32_bf16 v[126:129], v[130:133], v[176:179], 0
	v_mfma_f32_16x16x32_bf16 v[122:125], v[138:141], v[176:179], 0
	v_mfma_f32_16x16x32_bf16 v[110:113], v[130:133], v[196:199], 0
	v_mfma_f32_16x16x32_bf16 v[106:109], v[138:141], v[196:199], 0
	v_mfma_f32_16x16x32_bf16 v[94:97], v[130:133], v[204:207], 0
	v_mfma_f32_16x16x32_bf16 v[90:93], v[138:141], v[204:207], 0
	v_mfma_f32_16x16x32_bf16 v[78:81], v[130:133], v[212:215], 0
	v_mfma_f32_16x16x32_bf16 v[74:77], v[138:141], v[212:215], 0
	v_mfma_f32_16x16x32_bf16 v[126:129], v[134:137], v[180:183], v[126:129]
	v_mfma_f32_16x16x32_bf16 v[122:125], v[142:145], v[180:183], v[122:125]
	v_mfma_f32_16x16x32_bf16 v[110:113], v[134:137], v[200:203], v[110:113]
	v_mfma_f32_16x16x32_bf16 v[106:109], v[142:145], v[200:203], v[106:109]
	v_mfma_f32_16x16x32_bf16 v[94:97], v[134:137], v[208:211], v[94:97]
	v_mfma_f32_16x16x32_bf16 v[90:93], v[142:145], v[208:211], v[90:93]
	v_mfma_f32_16x16x32_bf16 v[78:81], v[134:137], v[216:219], v[78:81]
	v_mfma_f32_16x16x32_bf16 v[74:77], v[142:145], v[216:219], v[74:77]
	v_mfma_f32_16x16x32_bf16 v[118:121], v[156:159], v[176:179], 0
	v_mfma_f32_16x16x32_bf16 v[114:117], v[168:171], v[176:179], 0
	v_mfma_f32_16x16x32_bf16 v[102:105], v[156:159], v[196:199], 0
	v_mfma_f32_16x16x32_bf16 v[98:101], v[168:171], v[196:199], 0
	v_mfma_f32_16x16x32_bf16 v[86:89], v[156:159], v[204:207], 0
	v_mfma_f32_16x16x32_bf16 v[82:85], v[168:171], v[204:207], 0
	v_mfma_f32_16x16x32_bf16 v[70:73], v[156:159], v[212:215], 0
	v_mfma_f32_16x16x32_bf16 v[66:69], v[168:171], v[212:215], 0
	v_mfma_f32_16x16x32_bf16 v[118:121], v[164:167], v[180:183], v[118:121]
	v_mfma_f32_16x16x32_bf16 v[114:117], v[172:175], v[180:183], v[114:117]
	v_mfma_f32_16x16x32_bf16 v[102:105], v[164:167], v[200:203], v[102:105]
	v_mfma_f32_16x16x32_bf16 v[98:101], v[172:175], v[200:203], v[98:101]
	v_mfma_f32_16x16x32_bf16 v[86:89], v[164:167], v[208:211], v[86:89]
	v_mfma_f32_16x16x32_bf16 v[82:85], v[172:175], v[208:211], v[82:85]
	v_mfma_f32_16x16x32_bf16 v[70:73], v[164:167], v[216:219], v[70:73]
	v_mfma_f32_16x16x32_bf16 v[66:69], v[172:175], v[216:219], v[66:69]
	s_barrier
	s_add_i32 s33, s84, s61
	v_lshl_add_u64 v[184:185], s[54:55], 0, v[0:1]
	s_mov_b32 m0, s33
	ds_read_b128 v[176:179], v163 offset:16384
	ds_read_b128 v[180:183], v163 offset:17408
	ds_read_b128 v[196:199], v163 offset:18432
	ds_read_b128 v[200:203], v163 offset:19456
	ds_read_b128 v[204:207], v163 offset:20480
	ds_read_b128 v[208:211], v163 offset:21504
	ds_read_b128 v[212:215], v163 offset:22528
	ds_read_b128 v[216:219], v163 offset:23552
	global_load_lds_dwordx4 v[184:185], off
	s_add_i32 m0, s33, 0x2000
	s_add_u32 s82, s54, 0x40000
	v_lshl_add_u64 v[220:221], s[54:55], 0, v[146:147]
	s_addc_u32 s83, s55, 0
	s_add_i32 s33, s85, s61
	global_load_lds_dwordx4 v[220:221], off
	v_lshl_add_u64 v[222:223], s[82:83], 0, v[0:1]
	s_mov_b32 m0, s33
	v_lshl_add_u64 v[224:225], s[56:57], 0, v[148:149]
	global_load_lds_dwordx4 v[222:223], off
	v_lshl_add_u64 v[222:223], s[82:83], 0, v[146:147]
	s_add_i32 m0, s33, 0x2000
	s_nop 0
	global_load_lds_dwordx4 v[222:223], off
	v_lshl_add_u64 v[222:223], s[56:57], 0, v[150:151]
	s_mov_b32 m0, s62
	s_nop 0
	global_load_lds_dwordx4 v[222:223], off
	s_mov_b32 m0, s63
	s_nop 0
	global_load_lds_dwordx4 v[224:225], off
	s_waitcnt vmcnt(8)
	s_waitcnt lgkmcnt(0)
	s_barrier
; #define PG8_STAGE(bufoff, gbase, voff) do { _Pragma("unroll") for (int _i = 0; _i < 2; ++_i) \
;         __builtin_amdgcn_global_load_lds((const unsigned*)((const char*)(gbase) + (voff)[_i]), (PG8_LAS unsigned*)(lds + (bufoff) + ldsw + _i * 8192), 16, 0, 0); } while (0)
; #define PG8_LDA(dst, b, h) do { _Pragma("unroll") for (int m = 0; m < 4; ++m) _Pragma("unroll") for (int k = 0; k < 2; ++k) dst[m][k] = *(const PG8_LAS bf16x8*)(lds + PG8_SA(b, h) + aoff + m * 2048 + k * 1024); } while (0)
; #define PG8_LDB(dst, b, h) do { _Pragma("unroll") for (int n = 0; n < 2; ++n) _Pragma("unroll") for (int k = 0; k < 2; ++k) dst[n][k] = *(const PG8_LAS bf16x8*)(lds + PG8_SB(b, h) + boff + n * 2048 + k * 1024); } while (0)
; #define PG8_MMA(ai, bj, At, Bt) do { __builtin_amdgcn_s_setprio(1); _Pragma("unroll") for (int k = 0; k < 2; ++k) _Pragma("unroll") for (int m = 0; m < 4; ++m) _Pragma("unroll") for (int n = 0; n < 2; ++n) \
;         acc[ai][bj][m][n] = __builtin_amdgcn_mfma_f32_16x16x32_bf16(Bt[n][k], At[m][k], acc[ai][bj][m][n], 0, 0, 0); __builtin_amdgcn_s_setprio(0); } while (0)
; #define PG8_WAIT_V(n) asm volatile("s_waitcnt vmcnt(" #n ")" ::: "memory")
; #define PG8_WAIT_L(n) asm volatile("s_waitcnt lgkmcnt(" #n ")" ::: "memory")
; #define PG8_BAR __builtin_amdgcn_s_barrier()
; #define PG8_SCHED __builtin_amdgcn_sched_barrier(0)
; template <class Epi, class Sched, bool ALIGN_EPI = false, bool SP2 = false>
; __device__ __forceinline__ void gemm_phase(PG8_LAS unsigned char* lds, const Gemm g, const Sched& S, const Epi& E, int tid_in) {
;     ...
;             PG8_WAIT_V(8); PG8_WAIT_L(0); PG8_BAR; PG8_MMA(1, 0, At, B0); PG8_MMA(1, 1, At, B1); PG8_BAR; PG8_SCHED;
;             PG8_LDB(B0, 1, 0); PG8_LDB(B1, 1, 1); PG8_SCHED; PG8_LDA(At, 1, 0); PG8_STAGE(PG8_SA(0, 1), a2 + hstep, voffA);
;             PG8_WAIT_V(8); PG8_WAIT_L(0); PG8_BAR; PG8_MMA(0, 0, At, B0); PG8_MMA(0, 1, At, B1); PG8_BAR; PG8_SCHED;
	s_waitcnt lgkmcnt(0)
	v_mfma_f32_16x16x32_bf16 v[62:65], v[130:133], v[176:179], 0
	v_mfma_f32_16x16x32_bf16 v[58:61], v[138:141], v[176:179], 0
	v_mfma_f32_16x16x32_bf16 v[46:49], v[130:133], v[196:199], 0
	v_mfma_f32_16x16x32_bf16 v[42:45], v[138:141], v[196:199], 0
	v_mfma_f32_16x16x32_bf16 v[30:33], v[130:133], v[204:207], 0
	v_mfma_f32_16x16x32_bf16 v[26:29], v[138:141], v[204:207], 0
	v_mfma_f32_16x16x32_bf16 v[14:17], v[130:133], v[212:215], 0
	v_mfma_f32_16x16x32_bf16 v[10:13], v[138:141], v[212:215], 0
	v_mfma_f32_16x16x32_bf16 v[62:65], v[134:137], v[180:183], v[62:65]
	v_mfma_f32_16x16x32_bf16 v[58:61], v[142:145], v[180:183], v[58:61]
	v_mfma_f32_16x16x32_bf16 v[46:49], v[134:137], v[200:203], v[46:49]
	v_mfma_f32_16x16x32_bf16 v[42:45], v[142:145], v[200:203], v[42:45]
	v_mfma_f32_16x16x32_bf16 v[30:33], v[134:137], v[208:211], v[30:33]
	v_mfma_f32_16x16x32_bf16 v[26:29], v[142:145], v[208:211], v[26:29]
	v_mfma_f32_16x16x32_bf16 v[14:17], v[134:137], v[216:219], v[14:17]
	v_mfma_f32_16x16x32_bf16 v[10:13], v[142:145], v[216:219], v[10:13]
	v_mfma_f32_16x16x32_bf16 v[54:57], v[156:159], v[176:179], 0
	v_mfma_f32_16x16x32_bf16 v[50:53], v[168:171], v[176:179], 0
	v_mfma_f32_16x16x32_bf16 v[38:41], v[156:159], v[196:199], 0
	v_mfma_f32_16x16x32_bf16 v[34:37], v[168:171], v[196:199], 0
	v_mfma_f32_16x16x32_bf16 v[22:25], v[156:159], v[204:207], 0
	v_mfma_f32_16x16x32_bf16 v[18:21], v[168:171], v[204:207], 0
	v_mfma_f32_16x16x32_bf16 v[6:9], v[156:159], v[212:215], 0
	v_mfma_f32_16x16x32_bf16 v[2:5], v[168:171], v[212:215], 0
	v_mfma_f32_16x16x32_bf16 v[54:57], v[164:167], v[180:183], v[54:57]
	v_mfma_f32_16x16x32_bf16 v[50:53], v[172:175], v[180:183], v[50:53]
	v_mfma_f32_16x16x32_bf16 v[38:41], v[164:167], v[200:203], v[38:41]
	v_mfma_f32_16x16x32_bf16 v[34:37], v[172:175], v[200:203], v[34:37]
	v_mfma_f32_16x16x32_bf16 v[22:25], v[164:167], v[208:211], v[22:25]
	v_mfma_f32_16x16x32_bf16 v[18:21], v[172:175], v[208:211], v[18:21]
	v_mfma_f32_16x16x32_bf16 v[6:9], v[164:167], v[216:219], v[6:9]
	v_mfma_f32_16x16x32_bf16 v[2:5], v[172:175], v[216:219], v[2:5]
	s_barrier
	s_add_i32 s33, 0, 0x18000
	s_add_i32 s74, 0, 0x1c000
	v_add_u32_e32 v142, s33, v162
	v_add_u32_e32 v172, s74, v162
	ds_read_b128 v[130:133], v142
	ds_read_b128 v[134:137], v142 offset:1024
	ds_read_b128 v[138:141], v142 offset:2048
	ds_read_b128 v[142:145], v142 offset:3072
	ds_read_b128 v[156:159], v172
	ds_read_b128 v[164:167], v172 offset:1024
	ds_read_b128 v[168:171], v172 offset:2048
	ds_read_b128 v[172:175], v172 offset:3072
	s_add_u32 s56, s56, 0x40000
	s_addc_u32 s57, s57, 0
	s_mov_b32 m0, s64
	v_lshl_add_u64 v[226:227], s[56:57], 0, v[150:151]
	ds_read_b128 v[176:179], v163 offset:32768
	ds_read_b128 v[180:183], v163 offset:33792
	ds_read_b128 v[196:199], v163 offset:34816
	ds_read_b128 v[200:203], v163 offset:35840
	ds_read_b128 v[204:207], v163 offset:36864
	ds_read_b128 v[208:211], v163 offset:37888
	ds_read_b128 v[212:215], v163 offset:38912
	ds_read_b128 v[216:219], v163 offset:39936
	global_load_lds_dwordx4 v[226:227], off
	v_lshl_add_u64 v[226:227], s[56:57], 0, v[148:149]
	s_mov_b32 m0, s65
	s_nop 0
	global_load_lds_dwordx4 v[226:227], off
	s_waitcnt vmcnt(8)
	s_waitcnt lgkmcnt(0)
	s_barrier
	s_waitcnt lgkmcnt(0)
	v_mfma_f32_16x16x32_bf16 v[126:129], v[130:133], v[176:179], v[126:129]
	v_mfma_f32_16x16x32_bf16 v[122:125], v[138:141], v[176:179], v[122:125]
	v_mfma_f32_16x16x32_bf16 v[110:113], v[130:133], v[196:199], v[110:113]
	v_mfma_f32_16x16x32_bf16 v[106:109], v[138:141], v[196:199], v[106:109]
	v_mfma_f32_16x16x32_bf16 v[94:97], v[130:133], v[204:207], v[94:97]
	v_mfma_f32_16x16x32_bf16 v[90:93], v[138:141], v[204:207], v[90:93]
	v_mfma_f32_16x16x32_bf16 v[78:81], v[130:133], v[212:215], v[78:81]
	v_mfma_f32_16x16x32_bf16 v[74:77], v[138:141], v[212:215], v[74:77]
	v_mfma_f32_16x16x32_bf16 v[126:129], v[134:137], v[180:183], v[126:129]
	v_mfma_f32_16x16x32_bf16 v[122:125], v[142:145], v[180:183], v[122:125]
	v_mfma_f32_16x16x32_bf16 v[110:113], v[134:137], v[200:203], v[110:113]
	v_mfma_f32_16x16x32_bf16 v[106:109], v[142:145], v[200:203], v[106:109]
	v_mfma_f32_16x16x32_bf16 v[94:97], v[134:137], v[208:211], v[94:97]
	v_mfma_f32_16x16x32_bf16 v[90:93], v[142:145], v[208:211], v[90:93]
	v_mfma_f32_16x16x32_bf16 v[78:81], v[134:137], v[216:219], v[78:81]
	v_mfma_f32_16x16x32_bf16 v[74:77], v[142:145], v[216:219], v[74:77]
	v_mfma_f32_16x16x32_bf16 v[118:121], v[156:159], v[176:179], v[118:121]
	v_mfma_f32_16x16x32_bf16 v[114:117], v[168:171], v[176:179], v[114:117]
	v_mfma_f32_16x16x32_bf16 v[102:105], v[156:159], v[196:199], v[102:105]
	v_mfma_f32_16x16x32_bf16 v[98:101], v[168:171], v[196:199], v[98:101]
	v_mfma_f32_16x16x32_bf16 v[86:89], v[156:159], v[204:207], v[86:89]
	v_mfma_f32_16x16x32_bf16 v[82:85], v[168:171], v[204:207], v[82:85]
	v_mfma_f32_16x16x32_bf16 v[70:73], v[156:159], v[212:215], v[70:73]
	v_mfma_f32_16x16x32_bf16 v[66:69], v[168:171], v[212:215], v[66:69]
	v_mfma_f32_16x16x32_bf16 v[118:121], v[164:167], v[180:183], v[118:121]
	v_mfma_f32_16x16x32_bf16 v[114:117], v[172:175], v[180:183], v[114:117]
	v_mfma_f32_16x16x32_bf16 v[102:105], v[164:167], v[200:203], v[102:105]
	v_mfma_f32_16x16x32_bf16 v[98:101], v[172:175], v[200:203], v[98:101]
	v_mfma_f32_16x16x32_bf16 v[86:89], v[164:167], v[208:211], v[86:89]
	v_mfma_f32_16x16x32_bf16 v[82:85], v[172:175], v[208:211], v[82:85]
	v_mfma_f32_16x16x32_bf16 v[70:73], v[164:167], v[216:219], v[70:73]
	v_mfma_f32_16x16x32_bf16 v[66:69], v[172:175], v[216:219], v[66:69]
	s_barrier
; #define PG8_STAGE(bufoff, gbase, voff) do { _Pragma("unroll") for (int _i = 0; _i < 2; ++_i) \
;         __builtin_amdgcn_global_load_lds((const unsigned*)((const char*)(gbase) + (voff)[_i]), (PG8_LAS unsigned*)(lds + (bufoff) + ldsw + _i * 8192), 16, 0, 0); } while (0)
; #define PG8_LDA(dst, b, h) do { _Pragma("unroll") for (int m = 0; m < 4; ++m) _Pragma("unroll") for (int k = 0; k < 2; ++k) dst[m][k] = *(const PG8_LAS bf16x8*)(lds + PG8_SA(b, h) + aoff + m * 2048 + k * 1024); } while (0)
; #define PG8_LDB(dst, b, h) do { _Pragma("unroll") for (int n = 0; n < 2; ++n) _Pragma("unroll") for (int k = 0; k < 2; ++k) dst[n][k] = *(const PG8_LAS bf16x8*)(lds + PG8_SB(b, h) + boff + n * 2048 + k * 1024); } while (0)
; #define PG8_MMA(ai, bj, At, Bt) do { __builtin_amdgcn_s_setprio(1); _Pragma("unroll") for (int k = 0; k < 2; ++k) _Pragma("unroll") for (int m = 0; m < 4; ++m) _Pragma("unroll") for (int n = 0; n < 2; ++n) \
;         acc[ai][bj][m][n] = __builtin_amdgcn_mfma_f32_16x16x32_bf16(Bt[n][k], At[m][k], acc[ai][bj][m][n], 0, 0, 0); __builtin_amdgcn_s_setprio(0); } while (0)
; #define PG8_WAIT_V(n) asm volatile("s_waitcnt vmcnt(" #n ")" ::: "memory")
; #define PG8_WAIT_L(n) asm volatile("s_waitcnt lgkmcnt(" #n ")" ::: "memory")
; #define PG8_BAR __builtin_amdgcn_s_barrier()
; #define PG8_SCHED __builtin_amdgcn_sched_barrier(0)
; template <class Epi, class Sched, bool ALIGN_EPI = false, bool SP2 = false>
; __device__ __forceinline__ void gemm_phase(PG8_LAS unsigned char* lds, const Gemm g, const Sched& S, const Epi& E, int tid_in) {
;     ...
;             PG8_LDB(B0, 0, 0); PG8_LDB(B1, 0, 1); PG8_SCHED; PG8_LDA(At, 0, 0); PG8_STAGE(PG8_SA(1, 1), a1 + hstep, voffA);
;             PG8_WAIT_V(8); PG8_WAIT_L(0); PG8_BAR; PG8_MMA(0, 0, At, B0); PG8_MMA(0, 1, At, B1); PG8_BAR; PG8_SCHED;
;     ...
;             PG8_LDA(At, 1, 1); PG8_STAGE(PG8_SB(1, 0), b3, voffB); PG8_STAGE(PG8_SB(1, 1), b3 + hstep, voffB); PG8_STAGE(PG8_SA(1, 0), a3, voffA);
;             PG8_WAIT_V(8); PG8_WAIT_L(0); PG8_BAR; PG8_MMA(1, 0, At, B0); PG8_MMA(1, 1, At, B1); PG8_BAR; PG8_SCHED;
	s_add_i32 s56, s33, s61
	v_lshl_add_u64 v[184:185], v[184:185], 0, s[26:27]
	s_mov_b32 m0, s56
	ds_read_b128 v[176:179], v163 offset:49152
	ds_read_b128 v[180:183], v163 offset:50176
	ds_read_b128 v[196:199], v163 offset:51200
	ds_read_b128 v[200:203], v163 offset:52224
	ds_read_b128 v[204:207], v163 offset:53248
	ds_read_b128 v[208:211], v163 offset:54272
	ds_read_b128 v[212:215], v163 offset:55296
	ds_read_b128 v[216:219], v163 offset:56320
	global_load_lds_dwordx4 v[184:185], off
	s_add_i32 m0, s56, 0x2000
	s_add_u32 s54, s54, 0x40080
	v_lshl_add_u64 v[184:185], v[220:221], 0, s[26:27]
	s_addc_u32 s55, s55, 0
	s_add_i32 s56, s74, s61
	global_load_lds_dwordx4 v[184:185], off
	v_lshl_add_u64 v[184:185], s[54:55], 0, v[0:1]
	s_mov_b32 m0, s56
	s_nop 0
	global_load_lds_dwordx4 v[184:185], off
	v_lshl_add_u64 v[184:185], s[54:55], 0, v[146:147]
	s_add_i32 m0, s56, 0x2000
	s_nop 0
	global_load_lds_dwordx4 v[184:185], off
	v_lshl_add_u64 v[184:185], v[222:223], 0, s[26:27]
	s_mov_b32 m0, s70
	s_nop 0
	global_load_lds_dwordx4 v[184:185], off
	v_lshl_add_u64 v[184:185], v[224:225], 0, s[26:27]
	s_mov_b32 m0, s75
	s_nop 0
	global_load_lds_dwordx4 v[184:185], off
	s_waitcnt vmcnt(8)
	s_waitcnt lgkmcnt(0)
	s_barrier
	s_waitcnt lgkmcnt(0)
	v_mfma_f32_16x16x32_bf16 v[62:65], v[130:133], v[176:179], v[62:65]
	v_mfma_f32_16x16x32_bf16 v[58:61], v[138:141], v[176:179], v[58:61]
	v_mfma_f32_16x16x32_bf16 v[46:49], v[130:133], v[196:199], v[46:49]
	v_mfma_f32_16x16x32_bf16 v[42:45], v[138:141], v[196:199], v[42:45]
	v_mfma_f32_16x16x32_bf16 v[30:33], v[130:133], v[204:207], v[30:33]
	v_mfma_f32_16x16x32_bf16 v[26:29], v[138:141], v[204:207], v[26:29]
	v_mfma_f32_16x16x32_bf16 v[14:17], v[130:133], v[212:215], v[14:17]
	v_mfma_f32_16x16x32_bf16 v[10:13], v[138:141], v[212:215], v[10:13]
	v_mfma_f32_16x16x32_bf16 v[62:65], v[134:137], v[180:183], v[62:65]
	v_mfma_f32_16x16x32_bf16 v[58:61], v[142:145], v[180:183], v[58:61]
	v_mfma_f32_16x16x32_bf16 v[46:49], v[134:137], v[200:203], v[46:49]
	v_mfma_f32_16x16x32_bf16 v[42:45], v[142:145], v[200:203], v[42:45]
	v_mfma_f32_16x16x32_bf16 v[30:33], v[134:137], v[208:211], v[30:33]
	v_mfma_f32_16x16x32_bf16 v[26:29], v[142:145], v[208:211], v[26:29]
	v_mfma_f32_16x16x32_bf16 v[14:17], v[134:137], v[216:219], v[14:17]
	v_mfma_f32_16x16x32_bf16 v[10:13], v[142:145], v[216:219], v[10:13]
	v_mfma_f32_16x16x32_bf16 v[54:57], v[156:159], v[176:179], v[54:57]
	v_mfma_f32_16x16x32_bf16 v[50:53], v[168:171], v[176:179], v[50:53]
	v_mfma_f32_16x16x32_bf16 v[38:41], v[156:159], v[196:199], v[38:41]
	v_mfma_f32_16x16x32_bf16 v[34:37], v[168:171], v[196:199], v[34:37]
	v_mfma_f32_16x16x32_bf16 v[22:25], v[156:159], v[204:207], v[22:25]
	v_mfma_f32_16x16x32_bf16 v[18:21], v[168:171], v[204:207], v[18:21]
	v_mfma_f32_16x16x32_bf16 v[6:9], v[156:159], v[212:215], v[6:9]
	v_mfma_f32_16x16x32_bf16 v[2:5], v[168:171], v[212:215], v[2:5]
	v_mfma_f32_16x16x32_bf16 v[54:57], v[164:167], v[180:183], v[54:57]
	v_mfma_f32_16x16x32_bf16 v[50:53], v[172:175], v[180:183], v[50:53]
	v_mfma_f32_16x16x32_bf16 v[38:41], v[164:167], v[200:203], v[38:41]
	v_mfma_f32_16x16x32_bf16 v[34:37], v[172:175], v[200:203], v[34:37]
	v_mfma_f32_16x16x32_bf16 v[22:25], v[164:167], v[208:211], v[22:25]
	v_mfma_f32_16x16x32_bf16 v[18:21], v[172:175], v[208:211], v[18:21]
	v_mfma_f32_16x16x32_bf16 v[6:9], v[164:167], v[216:219], v[6:9]
	v_mfma_f32_16x16x32_bf16 v[2:5], v[172:175], v[216:219], v[2:5]
	s_barrier
	s_add_i32 s80, s80, 2
	s_add_u32 s52, s52, 0x100
	s_addc_u32 s53, s53, 0
	s_add_u32 s78, s78, 0x100
	s_addc_u32 s79, s79, 0
	s_cmp_gt_u32 s80, 13
.LBB0_206:
	s_add_u32 s33, s52, 0xfffc0080
	s_addc_u32 s54, s53, -1
	s_add_i32 s84, 0, 0x10000
	s_cmp_eq_u32 s80, 12
	s_cselect_b32 s57, s45, s54
	s_cselect_b32 s56, s76, s33
	s_cselect_b32 s55, s43, s79
	s_cselect_b32 s54, s77, s78
	s_add_i32 s85, 0, 0x14000
	v_add_u32_e32 v142, s84, v162
	v_add_u32_e32 v172, s85, v162
	ds_read_b128 v[130:133], v142
	ds_read_b128 v[134:137], v142 offset:1024
	ds_read_b128 v[138:141], v142 offset:2048
	ds_read_b128 v[142:145], v142 offset:3072
	ds_read_b128 v[156:159], v172
	ds_read_b128 v[164:167], v172 offset:1024
	ds_read_b128 v[168:171], v172 offset:2048
	ds_read_b128 v[172:175], v172 offset:3072
	v_lshl_add_u64 v[184:185], s[52:53], 0, v[152:153]
	s_add_i32 m0, s62, 0xc000
	ds_read_b128 v[176:179], v163
	ds_read_b128 v[180:183], v163 offset:1024
	ds_read_b128 v[196:199], v163 offset:2048
	ds_read_b128 v[200:203], v163 offset:3072
	ds_read_b128 v[204:207], v163 offset:4096
	ds_read_b128 v[208:211], v163 offset:5120
	ds_read_b128 v[212:215], v163 offset:6144
	ds_read_b128 v[216:219], v163 offset:7168
	global_load_lds_dwordx4 v[184:185], off
	v_lshl_add_u64 v[184:185], s[52:53], 0, v[154:155]
	s_add_i32 m0, s62, 0xe000
	s_nop 0
	global_load_lds_dwordx4 v[184:185], off
	s_waitcnt vmcnt(8)
	s_waitcnt lgkmcnt(0)
	s_barrier
; #define PG8_STAGE(bufoff, gbase, voff) do { _Pragma("unroll") for (int _i = 0; _i < 2; ++_i) \
;         __builtin_amdgcn_global_load_lds((const unsigned*)((const char*)(gbase) + (voff)[_i]), (PG8_LAS unsigned*)(lds + (bufoff) + ldsw + _i * 8192), 16, 0, 0); } while (0)
; #define PG8_LDA(dst, b, h) do { _Pragma("unroll") for (int m = 0; m < 4; ++m) _Pragma("unroll") for (int k = 0; k < 2; ++k) dst[m][k] = *(const PG8_LAS bf16x8*)(lds + PG8_SA(b, h) + aoff + m * 2048 + k * 1024); } while (0)
; #define PG8_MMA(ai, bj, At, Bt) do { __builtin_amdgcn_s_setprio(1); _Pragma("unroll") for (int k = 0; k < 2; ++k) _Pragma("unroll") for (int m = 0; m < 4; ++m) _Pragma("unroll") for (int n = 0; n < 2; ++n) \
;         acc[ai][bj][m][n] = __builtin_amdgcn_mfma_f32_16x16x32_bf16(Bt[n][k], At[m][k], acc[ai][bj][m][n], 0, 0, 0); __builtin_amdgcn_s_setprio(0); } while (0)
; #define PG8_WAIT_V(n) asm volatile("s_waitcnt vmcnt(" #n ")" ::: "memory")
; #define PG8_WAIT_L(n) asm volatile("s_waitcnt lgkmcnt(" #n ")" ::: "memory")
; #define PG8_BAR __builtin_amdgcn_s_barrier()
; #define PG8_SCHED __builtin_amdgcn_sched_barrier(0)
; template <class Epi, class Sched, bool ALIGN_EPI = false, bool SP2 = false>
; __device__ __forceinline__ void gemm_phase(PG8_LAS unsigned char* lds, const Gemm g, const Sched& S, const Epi& E, int tid_in) {
;     ...
;             PG8_WAIT_V(8); PG8_WAIT_L(0); PG8_BAR; PG8_MMA(0, 0, At, B0); PG8_MMA(0, 1, At, B1); PG8_BAR; PG8_SCHED;
;             PG8_LDA(At, 0, 1); PG8_STAGE(PG8_SB(0, 0), b2, voffB); PG8_STAGE(PG8_SB(0, 1), b2 + hstep, voffB); PG8_STAGE(PG8_SA(0, 0), a2, voffA);
;             PG8_WAIT_V(8); PG8_WAIT_L(0); PG8_BAR; PG8_MMA(1, 0, At, B0); PG8_MMA(1, 1, At, B1); PG8_BAR; PG8_SCHED;
	s_waitcnt lgkmcnt(0)
	v_mfma_f32_16x16x32_bf16 v[126:129], v[130:133], v[176:179], v[126:129]
	v_mfma_f32_16x16x32_bf16 v[122:125], v[138:141], v[176:179], v[122:125]
	v_mfma_f32_16x16x32_bf16 v[110:113], v[130:133], v[196:199], v[110:113]
	v_mfma_f32_16x16x32_bf16 v[106:109], v[138:141], v[196:199], v[106:109]
	v_mfma_f32_16x16x32_bf16 v[94:97], v[130:133], v[204:207], v[94:97]
	v_mfma_f32_16x16x32_bf16 v[90:93], v[138:141], v[204:207], v[90:93]
	v_mfma_f32_16x16x32_bf16 v[78:81], v[130:133], v[212:215], v[78:81]
	v_mfma_f32_16x16x32_bf16 v[74:77], v[138:141], v[212:215], v[74:77]
	v_mfma_f32_16x16x32_bf16 v[126:129], v[134:137], v[180:183], v[126:129]
	v_mfma_f32_16x16x32_bf16 v[122:125], v[142:145], v[180:183], v[122:125]
	v_mfma_f32_16x16x32_bf16 v[110:113], v[134:137], v[200:203], v[110:113]
	v_mfma_f32_16x16x32_bf16 v[106:109], v[142:145], v[200:203], v[106:109]
	v_mfma_f32_16x16x32_bf16 v[94:97], v[134:137], v[208:211], v[94:97]
	v_mfma_f32_16x16x32_bf16 v[90:93], v[142:145], v[208:211], v[90:93]
	v_mfma_f32_16x16x32_bf16 v[78:81], v[134:137], v[216:219], v[78:81]
	v_mfma_f32_16x16x32_bf16 v[74:77], v[142:145], v[216:219], v[74:77]
	v_mfma_f32_16x16x32_bf16 v[118:121], v[156:159], v[176:179], v[118:121]
	v_mfma_f32_16x16x32_bf16 v[114:117], v[168:171], v[176:179], v[114:117]
	v_mfma_f32_16x16x32_bf16 v[102:105], v[156:159], v[196:199], v[102:105]
	v_mfma_f32_16x16x32_bf16 v[98:101], v[168:171], v[196:199], v[98:101]
	v_mfma_f32_16x16x32_bf16 v[86:89], v[156:159], v[204:207], v[86:89]
	v_mfma_f32_16x16x32_bf16 v[82:85], v[168:171], v[204:207], v[82:85]
	v_mfma_f32_16x16x32_bf16 v[70:73], v[156:159], v[212:215], v[70:73]
	v_mfma_f32_16x16x32_bf16 v[66:69], v[168:171], v[212:215], v[66:69]
	v_mfma_f32_16x16x32_bf16 v[118:121], v[164:167], v[180:183], v[118:121]
	v_mfma_f32_16x16x32_bf16 v[114:117], v[172:175], v[180:183], v[114:117]
	v_mfma_f32_16x16x32_bf16 v[102:105], v[164:167], v[200:203], v[102:105]
	v_mfma_f32_16x16x32_bf16 v[98:101], v[172:175], v[200:203], v[98:101]
	v_mfma_f32_16x16x32_bf16 v[86:89], v[164:167], v[208:211], v[86:89]
	v_mfma_f32_16x16x32_bf16 v[82:85], v[172:175], v[208:211], v[82:85]
	v_mfma_f32_16x16x32_bf16 v[70:73], v[164:167], v[216:219], v[70:73]
	v_mfma_f32_16x16x32_bf16 v[66:69], v[172:175], v[216:219], v[66:69]
	s_barrier
	s_add_i32 s33, s84, s61
	v_lshl_add_u64 v[184:185], s[54:55], 0, v[0:1]
	s_mov_b32 m0, s33
	ds_read_b128 v[176:179], v163 offset:16384
	ds_read_b128 v[180:183], v163 offset:17408
	ds_read_b128 v[196:199], v163 offset:18432
	ds_read_b128 v[200:203], v163 offset:19456
	ds_read_b128 v[204:207], v163 offset:20480
	ds_read_b128 v[208:211], v163 offset:21504
	ds_read_b128 v[212:215], v163 offset:22528
	ds_read_b128 v[216:219], v163 offset:23552
	global_load_lds_dwordx4 v[184:185], off
	s_add_i32 m0, s33, 0x2000
	s_add_u32 s82, s54, 0x40000
	v_lshl_add_u64 v[220:221], s[54:55], 0, v[146:147]
	s_addc_u32 s83, s55, 0
	s_add_i32 s33, s85, s61
	global_load_lds_dwordx4 v[220:221], off
	v_lshl_add_u64 v[222:223], s[82:83], 0, v[0:1]
	s_mov_b32 m0, s33
	v_lshl_add_u64 v[224:225], s[56:57], 0, v[148:149]
	global_load_lds_dwordx4 v[222:223], off
	v_lshl_add_u64 v[222:223], s[82:83], 0, v[146:147]
	s_add_i32 m0, s33, 0x2000
	s_nop 0
	global_load_lds_dwordx4 v[222:223], off
	v_lshl_add_u64 v[222:223], s[56:57], 0, v[150:151]
	s_mov_b32 m0, s62
	s_nop 0
	global_load_lds_dwordx4 v[222:223], off
	s_mov_b32 m0, s63
	s_nop 0
	global_load_lds_dwordx4 v[224:225], off
	s_waitcnt vmcnt(8)
	s_waitcnt lgkmcnt(0)
	s_barrier
	s_waitcnt lgkmcnt(0)
	v_mfma_f32_16x16x32_bf16 v[62:65], v[130:133], v[176:179], v[62:65]
	v_mfma_f32_16x16x32_bf16 v[58:61], v[138:141], v[176:179], v[58:61]
	v_mfma_f32_16x16x32_bf16 v[46:49], v[130:133], v[196:199], v[46:49]
	v_mfma_f32_16x16x32_bf16 v[42:45], v[138:141], v[196:199], v[42:45]
	v_mfma_f32_16x16x32_bf16 v[30:33], v[130:133], v[204:207], v[30:33]
	v_mfma_f32_16x16x32_bf16 v[26:29], v[138:141], v[204:207], v[26:29]
	v_mfma_f32_16x16x32_bf16 v[14:17], v[130:133], v[212:215], v[14:17]
	v_mfma_f32_16x16x32_bf16 v[10:13], v[138:141], v[212:215], v[10:13]
	v_mfma_f32_16x16x32_bf16 v[62:65], v[134:137], v[180:183], v[62:65]
	v_mfma_f32_16x16x32_bf16 v[58:61], v[142:145], v[180:183], v[58:61]
	v_mfma_f32_16x16x32_bf16 v[46:49], v[134:137], v[200:203], v[46:49]
	v_mfma_f32_16x16x32_bf16 v[42:45], v[142:145], v[200:203], v[42:45]
	v_mfma_f32_16x16x32_bf16 v[30:33], v[134:137], v[208:211], v[30:33]
	v_mfma_f32_16x16x32_bf16 v[26:29], v[142:145], v[208:211], v[26:29]
	v_mfma_f32_16x16x32_bf16 v[14:17], v[134:137], v[216:219], v[14:17]
	v_mfma_f32_16x16x32_bf16 v[10:13], v[142:145], v[216:219], v[10:13]
	v_mfma_f32_16x16x32_bf16 v[54:57], v[156:159], v[176:179], v[54:57]
	v_mfma_f32_16x16x32_bf16 v[50:53], v[168:171], v[176:179], v[50:53]
	v_mfma_f32_16x16x32_bf16 v[38:41], v[156:159], v[196:199], v[38:41]
	v_mfma_f32_16x16x32_bf16 v[34:37], v[168:171], v[196:199], v[34:37]
	v_mfma_f32_16x16x32_bf16 v[22:25], v[156:159], v[204:207], v[22:25]
	v_mfma_f32_16x16x32_bf16 v[18:21], v[168:171], v[204:207], v[18:21]
	v_mfma_f32_16x16x32_bf16 v[6:9], v[156:159], v[212:215], v[6:9]
	v_mfma_f32_16x16x32_bf16 v[2:5], v[168:171], v[212:215], v[2:5]
	v_mfma_f32_16x16x32_bf16 v[54:57], v[164:167], v[180:183], v[54:57]
	v_mfma_f32_16x16x32_bf16 v[50:53], v[172:175], v[180:183], v[50:53]
	v_mfma_f32_16x16x32_bf16 v[38:41], v[164:167], v[200:203], v[38:41]
	v_mfma_f32_16x16x32_bf16 v[34:37], v[172:175], v[200:203], v[34:37]
	v_mfma_f32_16x16x32_bf16 v[22:25], v[164:167], v[208:211], v[22:25]
	v_mfma_f32_16x16x32_bf16 v[18:21], v[172:175], v[208:211], v[18:21]
	v_mfma_f32_16x16x32_bf16 v[6:9], v[164:167], v[216:219], v[6:9]
	v_mfma_f32_16x16x32_bf16 v[2:5], v[172:175], v[216:219], v[2:5]
	s_barrier
; #define PG8_STAGE(bufoff, gbase, voff) do { _Pragma("unroll") for (int _i = 0; _i < 2; ++_i) \
;         __builtin_amdgcn_global_load_lds((const unsigned*)((const char*)(gbase) + (voff)[_i]), (PG8_LAS unsigned*)(lds + (bufoff) + ldsw + _i * 8192), 16, 0, 0); } while (0)
; #define PG8_LDA(dst, b, h) do { _Pragma("unroll") for (int m = 0; m < 4; ++m) _Pragma("unroll") for (int k = 0; k < 2; ++k) dst[m][k] = *(const PG8_LAS bf16x8*)(lds + PG8_SA(b, h) + aoff + m * 2048 + k * 1024); } while (0)
; #define PG8_LDB(dst, b, h) do { _Pragma("unroll") for (int n = 0; n < 2; ++n) _Pragma("unroll") for (int k = 0; k < 2; ++k) dst[n][k] = *(const PG8_LAS bf16x8*)(lds + PG8_SB(b, h) + boff + n * 2048 + k * 1024); } while (0)
; #define PG8_MMA(ai, bj, At, Bt) do { __builtin_amdgcn_s_setprio(1); _Pragma("unroll") for (int k = 0; k < 2; ++k) _Pragma("unroll") for (int m = 0; m < 4; ++m) _Pragma("unroll") for (int n = 0; n < 2; ++n) \
;         acc[ai][bj][m][n] = __builtin_amdgcn_mfma_f32_16x16x32_bf16(Bt[n][k], At[m][k], acc[ai][bj][m][n], 0, 0, 0); __builtin_amdgcn_s_setprio(0); } while (0)
; #define PG8_WAIT_V(n) asm volatile("s_waitcnt vmcnt(" #n ")" ::: "memory")
; #define PG8_WAIT_L(n) asm volatile("s_waitcnt lgkmcnt(" #n ")" ::: "memory")
; #define PG8_BAR __builtin_amdgcn_s_barrier()
; #define PG8_SCHED __builtin_amdgcn_sched_barrier(0)
; template <class Epi, class Sched, bool ALIGN_EPI = false, bool SP2 = false>
; __device__ __forceinline__ void gemm_phase(PG8_LAS unsigned char* lds, const Gemm g, const Sched& S, const Epi& E, int tid_in) {
;     ...
;             PG8_LDB(B0, 1, 0); PG8_LDB(B1, 1, 1); PG8_SCHED; PG8_LDA(At, 1, 0); PG8_STAGE(PG8_SA(0, 1), a2 + hstep, voffA);
;             PG8_WAIT_V(8); PG8_WAIT_L(0); PG8_BAR; PG8_MMA(0, 0, At, B0); PG8_MMA(0, 1, At, B1); PG8_BAR; PG8_SCHED;
	s_add_i32 s33, 0, 0x18000
	s_add_i32 s74, 0, 0x1c000
	v_add_u32_e32 v142, s33, v162
	v_add_u32_e32 v172, s74, v162
	ds_read_b128 v[130:133], v142
	ds_read_b128 v[134:137], v142 offset:1024
	ds_read_b128 v[138:141], v142 offset:2048
	ds_read_b128 v[142:145], v142 offset:3072
	ds_read_b128 v[156:159], v172
	ds_read_b128 v[164:167], v172 offset:1024
	ds_read_b128 v[168:171], v172 offset:2048
	ds_read_b128 v[172:175], v172 offset:3072
	s_add_u32 s56, s56, 0x40000
	s_addc_u32 s57, s57, 0
	s_mov_b32 m0, s64
	v_lshl_add_u64 v[226:227], s[56:57], 0, v[150:151]
	ds_read_b128 v[176:179], v163 offset:32768
	ds_read_b128 v[180:183], v163 offset:33792
	ds_read_b128 v[196:199], v163 offset:34816
	ds_read_b128 v[200:203], v163 offset:35840
	ds_read_b128 v[204:207], v163 offset:36864
	ds_read_b128 v[208:211], v163 offset:37888
	ds_read_b128 v[212:215], v163 offset:38912
	ds_read_b128 v[216:219], v163 offset:39936
	global_load_lds_dwordx4 v[226:227], off
	v_lshl_add_u64 v[226:227], s[56:57], 0, v[148:149]
	s_mov_b32 m0, s65
	s_nop 0
	global_load_lds_dwordx4 v[226:227], off
	s_waitcnt vmcnt(8)
	s_waitcnt lgkmcnt(0)
	s_barrier
	s_waitcnt lgkmcnt(0)
	v_mfma_f32_16x16x32_bf16 v[126:129], v[130:133], v[176:179], v[126:129]
	v_mfma_f32_16x16x32_bf16 v[122:125], v[138:141], v[176:179], v[122:125]
	v_mfma_f32_16x16x32_bf16 v[110:113], v[130:133], v[196:199], v[110:113]
	v_mfma_f32_16x16x32_bf16 v[106:109], v[138:141], v[196:199], v[106:109]
	v_mfma_f32_16x16x32_bf16 v[94:97], v[130:133], v[204:207], v[94:97]
	v_mfma_f32_16x16x32_bf16 v[90:93], v[138:141], v[204:207], v[90:93]
	v_mfma_f32_16x16x32_bf16 v[78:81], v[130:133], v[212:215], v[78:81]
	v_mfma_f32_16x16x32_bf16 v[74:77], v[138:141], v[212:215], v[74:77]
	v_mfma_f32_16x16x32_bf16 v[126:129], v[134:137], v[180:183], v[126:129]
	v_mfma_f32_16x16x32_bf16 v[122:125], v[142:145], v[180:183], v[122:125]
	v_mfma_f32_16x16x32_bf16 v[110:113], v[134:137], v[200:203], v[110:113]
	v_mfma_f32_16x16x32_bf16 v[106:109], v[142:145], v[200:203], v[106:109]
	v_mfma_f32_16x16x32_bf16 v[94:97], v[134:137], v[208:211], v[94:97]
	v_mfma_f32_16x16x32_bf16 v[90:93], v[142:145], v[208:211], v[90:93]
	v_mfma_f32_16x16x32_bf16 v[78:81], v[134:137], v[216:219], v[78:81]
	v_mfma_f32_16x16x32_bf16 v[74:77], v[142:145], v[216:219], v[74:77]
	v_mfma_f32_16x16x32_bf16 v[118:121], v[156:159], v[176:179], v[118:121]
	v_mfma_f32_16x16x32_bf16 v[114:117], v[168:171], v[176:179], v[114:117]
	v_mfma_f32_16x16x32_bf16 v[102:105], v[156:159], v[196:199], v[102:105]
	v_mfma_f32_16x16x32_bf16 v[98:101], v[168:171], v[196:199], v[98:101]
	v_mfma_f32_16x16x32_bf16 v[86:89], v[156:159], v[204:207], v[86:89]
	v_mfma_f32_16x16x32_bf16 v[82:85], v[168:171], v[204:207], v[82:85]
	v_mfma_f32_16x16x32_bf16 v[70:73], v[156:159], v[212:215], v[70:73]
	v_mfma_f32_16x16x32_bf16 v[66:69], v[168:171], v[212:215], v[66:69]
	v_mfma_f32_16x16x32_bf16 v[118:121], v[164:167], v[180:183], v[118:121]
	v_mfma_f32_16x16x32_bf16 v[114:117], v[172:175], v[180:183], v[114:117]
	v_mfma_f32_16x16x32_bf16 v[102:105], v[164:167], v[200:203], v[102:105]
	v_mfma_f32_16x16x32_bf16 v[98:101], v[172:175], v[200:203], v[98:101]
	v_mfma_f32_16x16x32_bf16 v[86:89], v[164:167], v[208:211], v[86:89]
	v_mfma_f32_16x16x32_bf16 v[82:85], v[172:175], v[208:211], v[82:85]
	v_mfma_f32_16x16x32_bf16 v[70:73], v[164:167], v[216:219], v[70:73]
	v_mfma_f32_16x16x32_bf16 v[66:69], v[172:175], v[216:219], v[66:69]
	s_barrier
; #define PG8_STAGE(bufoff, gbase, voff) do { _Pragma("unroll") for (int _i = 0; _i < 2; ++_i) \
;         __builtin_amdgcn_global_load_lds((const unsigned*)((const char*)(gbase) + (voff)[_i]), (PG8_LAS unsigned*)(lds + (bufoff) + ldsw + _i * 8192), 16, 0, 0); } while (0)
; #define PG8_LDA(dst, b, h) do { _Pragma("unroll") for (int m = 0; m < 4; ++m) _Pragma("unroll") for (int k = 0; k < 2; ++k) dst[m][k] = *(const PG8_LAS bf16x8*)(lds + PG8_SA(b, h) + aoff + m * 2048 + k * 1024); } while (0)
; #define PG8_MMA(ai, bj, At, Bt) do { __builtin_amdgcn_s_setprio(1); _Pragma("unroll") for (int k = 0; k < 2; ++k) _Pragma("unroll") for (int m = 0; m < 4; ++m) _Pragma("unroll") for (int n = 0; n < 2; ++n) \
;         acc[ai][bj][m][n] = __builtin_amdgcn_mfma_f32_16x16x32_bf16(Bt[n][k], At[m][k], acc[ai][bj][m][n], 0, 0, 0); __builtin_amdgcn_s_setprio(0); } while (0)
; #define PG8_WAIT_V(n) asm volatile("s_waitcnt vmcnt(" #n ")" ::: "memory")
; #define PG8_WAIT_L(n) asm volatile("s_waitcnt lgkmcnt(" #n ")" ::: "memory")
; #define PG8_BAR __builtin_amdgcn_s_barrier()
; #define PG8_SCHED __builtin_amdgcn_sched_barrier(0)
; template <class Epi, class Sched, bool ALIGN_EPI = false, bool SP2 = false>
; __device__ __forceinline__ void gemm_phase(PG8_LAS unsigned char* lds, const Gemm g, const Sched& S, const Epi& E, int tid_in) {
;     ...
;             PG8_LDA(At, 1, 1); PG8_STAGE(PG8_SB(1, 0), b3, voffB); PG8_STAGE(PG8_SB(1, 1), b3 + hstep, voffB); PG8_STAGE(PG8_SA(1, 0), a3, voffA);
;             PG8_WAIT_V(8); PG8_WAIT_L(0); PG8_BAR; PG8_MMA(1, 0, At, B0); PG8_MMA(1, 1, At, B1); PG8_BAR; PG8_SCHED;
;     ...
;         if constexpr (ALIGN_EPI) { if (wr == 0) PG8_BAR; }
	s_add_i32 s56, s33, s61
	v_lshl_add_u64 v[184:185], v[184:185], 0, s[26:27]
	s_mov_b32 m0, s56
	ds_read_b128 v[176:179], v163 offset:49152
	ds_read_b128 v[180:183], v163 offset:50176
	ds_read_b128 v[196:199], v163 offset:51200
	ds_read_b128 v[200:203], v163 offset:52224
	ds_read_b128 v[204:207], v163 offset:53248
	ds_read_b128 v[208:211], v163 offset:54272
	ds_read_b128 v[212:215], v163 offset:55296
	ds_read_b128 v[216:219], v163 offset:56320
	global_load_lds_dwordx4 v[184:185], off
	s_add_i32 m0, s56, 0x2000
	s_add_u32 s54, s54, 0x40080
	v_lshl_add_u64 v[184:185], v[220:221], 0, s[26:27]
	s_addc_u32 s55, s55, 0
	s_add_i32 s56, s74, s61
	global_load_lds_dwordx4 v[184:185], off
	v_lshl_add_u64 v[184:185], s[54:55], 0, v[0:1]
	s_mov_b32 m0, s56
	s_nop 0
	global_load_lds_dwordx4 v[184:185], off
	v_lshl_add_u64 v[184:185], s[54:55], 0, v[146:147]
	s_add_i32 m0, s56, 0x2000
	s_nop 0
	global_load_lds_dwordx4 v[184:185], off
	v_lshl_add_u64 v[184:185], v[222:223], 0, s[26:27]
	s_mov_b32 m0, s70
	s_nop 0
	global_load_lds_dwordx4 v[184:185], off
	v_lshl_add_u64 v[184:185], v[224:225], 0, s[26:27]
	s_mov_b32 m0, s75
	s_nop 0
	global_load_lds_dwordx4 v[184:185], off
	s_waitcnt vmcnt(8)
	s_waitcnt lgkmcnt(0)
	s_barrier
	s_waitcnt lgkmcnt(0)
	v_mfma_f32_16x16x32_bf16 v[62:65], v[130:133], v[176:179], v[62:65]
	v_mfma_f32_16x16x32_bf16 v[58:61], v[138:141], v[176:179], v[58:61]
	v_mfma_f32_16x16x32_bf16 v[46:49], v[130:133], v[196:199], v[46:49]
	v_mfma_f32_16x16x32_bf16 v[42:45], v[138:141], v[196:199], v[42:45]
	v_mfma_f32_16x16x32_bf16 v[30:33], v[130:133], v[204:207], v[30:33]
	v_mfma_f32_16x16x32_bf16 v[26:29], v[138:141], v[204:207], v[26:29]
	v_mfma_f32_16x16x32_bf16 v[14:17], v[130:133], v[212:215], v[14:17]
	v_mfma_f32_16x16x32_bf16 v[10:13], v[138:141], v[212:215], v[10:13]
	v_mfma_f32_16x16x32_bf16 v[62:65], v[134:137], v[180:183], v[62:65]
	v_mfma_f32_16x16x32_bf16 v[58:61], v[142:145], v[180:183], v[58:61]
	v_mfma_f32_16x16x32_bf16 v[46:49], v[134:137], v[200:203], v[46:49]
	v_mfma_f32_16x16x32_bf16 v[42:45], v[142:145], v[200:203], v[42:45]
	v_mfma_f32_16x16x32_bf16 v[30:33], v[134:137], v[208:211], v[30:33]
	v_mfma_f32_16x16x32_bf16 v[26:29], v[142:145], v[208:211], v[26:29]
	v_mfma_f32_16x16x32_bf16 v[14:17], v[134:137], v[216:219], v[14:17]
	v_mfma_f32_16x16x32_bf16 v[10:13], v[142:145], v[216:219], v[10:13]
	v_mfma_f32_16x16x32_bf16 v[54:57], v[156:159], v[176:179], v[54:57]
	v_mfma_f32_16x16x32_bf16 v[50:53], v[168:171], v[176:179], v[50:53]
	v_mfma_f32_16x16x32_bf16 v[38:41], v[156:159], v[196:199], v[38:41]
	v_mfma_f32_16x16x32_bf16 v[34:37], v[168:171], v[196:199], v[34:37]
	v_mfma_f32_16x16x32_bf16 v[22:25], v[156:159], v[204:207], v[22:25]
	v_mfma_f32_16x16x32_bf16 v[18:21], v[168:171], v[204:207], v[18:21]
	v_mfma_f32_16x16x32_bf16 v[6:9], v[156:159], v[212:215], v[6:9]
	v_mfma_f32_16x16x32_bf16 v[2:5], v[168:171], v[212:215], v[2:5]
	v_mfma_f32_16x16x32_bf16 v[54:57], v[164:167], v[180:183], v[54:57]
	v_mfma_f32_16x16x32_bf16 v[50:53], v[172:175], v[180:183], v[50:53]
	v_mfma_f32_16x16x32_bf16 v[38:41], v[164:167], v[200:203], v[38:41]
	v_mfma_f32_16x16x32_bf16 v[34:37], v[172:175], v[200:203], v[34:37]
	v_mfma_f32_16x16x32_bf16 v[22:25], v[164:167], v[208:211], v[22:25]
	v_mfma_f32_16x16x32_bf16 v[18:21], v[172:175], v[208:211], v[18:21]
	v_mfma_f32_16x16x32_bf16 v[6:9], v[164:167], v[216:219], v[6:9]
	v_mfma_f32_16x16x32_bf16 v[2:5], v[172:175], v[216:219], v[2:5]
	s_barrier
	s_add_i32 s80, s80, 2
	s_add_u32 s52, s52, 0x100
	s_addc_u32 s53, s53, 0
	s_add_u32 s78, s78, 0x100
	s_addc_u32 s79, s79, 0
	s_cmp_gt_u32 s80, 13
	s_cbranch_scc0 .LBB0_206
	s_and_b64 vcc, exec, s[40:41]
	s_cbranch_vccz .LBB0_209
	s_barrier

;     __device__ __forceinline__ bool next(int i, Unit& u) const { if (i >= n) return false; int o = own; asm volatile("" : "+s"(o)); u.pm = swap ? i : o; u.pn = swap ? o : i; u.idx = i; return true; }
; #define PG8_STAGE(bufoff, gbase, voff) do { _Pragma("unroll") for (int _i = 0; _i < 2; ++_i) \
;         __builtin_amdgcn_global_load_lds((const unsigned*)((const char*)(gbase) + (voff)[_i]), (PG8_LAS unsigned*)(lds + (bufoff) + ldsw + _i * 8192), 16, 0, 0); } while (0)
; #define PG8_LDA(dst, b, h) do { _Pragma("unroll") for (int m = 0; m < 4; ++m) _Pragma("unroll") for (int k = 0; k < 2; ++k) dst[m][k] = *(const PG8_LAS bf16x8*)(lds + PG8_SA(b, h) + aoff + m * 2048 + k * 1024); } while (0)
; #define PG8_LDB(dst, b, h) do { _Pragma("unroll") for (int n = 0; n < 2; ++n) _Pragma("unroll") for (int k = 0; k < 2; ++k) dst[n][k] = *(const PG8_LAS bf16x8*)(lds + PG8_SB(b, h) + boff + n * 2048 + k * 1024); } while (0)
; #define PG8_WAIT_V(n) asm volatile("s_waitcnt vmcnt(" #n ")" ::: "memory")
; template <class Epi, class Sched, bool ALIGN_EPI = false, bool SP2 = false>
; __device__ __forceinline__ void gemm_phase(PG8_LAS unsigned char* lds, const Gemm g, const Sched& S, const Epi& E, int tid_in) {
;     ...
;         const bool has_next = S.next(ui + 1, nxt);
;         const char* nA = has_next ? (const char*)g.A + (size_t)nxt.pm * tstep : cA; const char* nB = has_next ? (const char*)g.Bt + (size_t)nxt.pn * tstep : cB;
;         for (int t = 0; t < nt; t += 2) {
;             const bool last = (t == nt - 2);
;             const char* a1 = cA + (size_t)(t + 1) * kstep;
;             const char* a2 = last ? nA : cA + (size_t)(t + 2) * kstep; const char* b2 = last ? nB : cB + (size_t)(t + 2) * kstep;
;             const char* a3 = a2 + kstep; const char* b3 = b2 + kstep;
;             if (last && has_next) S.a_ready(nxt);
;             if constexpr (SP2) {
;             PG8_LDB(B0, 0, 0); PG8_LDB(B1, 0, 1); PG8_SCHED; PG8_LDA(At, 0, 0); PG8_STAGE(PG8_SA(1, 1), a1 + hstep, voffA);
;             PG8_WAIT_V(8); PG8_WAIT_L(0); PG8_BAR; PG8_MMA(0, 0, At, B0); PG8_MMA(0, 1, At, B1); PG8_BAR; PG8_SCHED;
;             PG8_LDA(At, 0, 1); PG8_STAGE(PG8_SB(0, 0), b2, voffB); PG8_STAGE(PG8_SB(0, 1), b2 + hstep, voffB); PG8_STAGE(PG8_SA(0, 0), a2, voffA);
;             PG8_WAIT_V(8); PG8_WAIT_L(0); PG8_BAR; PG8_MMA(1, 0, At, B0); PG8_MMA(1, 1, At, B1); PG8_BAR; PG8_SCHED;
.LBB0_358:
	s_ashr_i32 s51, s50, 31
	s_lshl_b64 s[54:55], s[50:51], 19
	s_add_u32 s54, s68, s54
	s_addc_u32 s55, s69, s55
	s_and_b64 s[56:57], s[48:49], exec
	s_cselect_b32 s51, s55, s59
	s_cselect_b32 s81, s54, s58
	s_ashr_i32 s53, s52, 31
	s_lshl_b64 s[56:57], s[52:53], 19
	s_add_u32 s56, s64, s56
	s_addc_u32 s57, s65, s57
	s_and_b64 s[62:63], s[48:49], exec
	s_cselect_b32 s53, s57, s61
	s_cselect_b32 s82, s56, s60
	s_add_u32 s58, s58, 0x40080
	s_addc_u32 s59, s59, 0
	s_add_u32 s83, s60, 0x100
	s_addc_u32 vcc_lo, s61, 0
	s_mov_b32 vcc_hi, -2
	s_waitcnt vmcnt(0)
	v_add_u32_e32 v142, s84, v214
	v_add_u32_e32 v158, s85, v214
	s_waitcnt lgkmcnt(0)
	ds_read_b128 v[130:133], v142
	ds_read_b128 v[134:137], v142 offset:1024
	ds_read_b128 v[138:141], v142 offset:2048
	ds_read_b128 v[142:145], v142 offset:3072
	ds_read_b128 v[146:149], v158
	ds_read_b128 v[150:153], v158 offset:1024
	ds_read_b128 v[154:157], v158 offset:2048
	ds_read_b128 v[158:161], v158 offset:3072
	s_add_u32 s60, s58, 0xfffc0080
	s_addc_u32 s61, s59, -1
	s_cmp_eq_u32 vcc_hi, 12
	s_cselect_b32 s63, s51, s61
	s_cselect_b32 s62, s81, s60
	s_cselect_b32 s61, s53, vcc_lo
	s_cselect_b32 s60, s82, s83
	v_lshl_add_u64 v[216:217], s[58:59], 0, v[202:203]
	s_add_i32 m0, s76, 0xc000
	ds_read_b128 v[162:165], v215
	ds_read_b128 v[166:169], v215 offset:1024
	ds_read_b128 v[170:173], v215 offset:2048
	ds_read_b128 v[174:177], v215 offset:3072
	ds_read_b128 v[178:181], v215 offset:4096
	ds_read_b128 v[182:185], v215 offset:5120
	ds_read_b128 v[206:209], v215 offset:6144
	ds_read_b128 v[210:213], v215 offset:7168
	global_load_lds_dwordx4 v[216:217], off
	v_lshl_add_u64 v[216:217], s[58:59], 0, v[204:205]
	s_add_i32 m0, s76, 0xe000
	s_nop 0
	global_load_lds_dwordx4 v[216:217], off
	s_waitcnt vmcnt(8)
	s_waitcnt lgkmcnt(0)
	s_barrier
	s_waitcnt lgkmcnt(0)
	v_mfma_f32_16x16x32_bf16 v[126:129], v[130:133], v[162:165], 0
	v_mfma_f32_16x16x32_bf16 v[122:125], v[138:141], v[162:165], 0
	v_mfma_f32_16x16x32_bf16 v[110:113], v[130:133], v[170:173], 0
	v_mfma_f32_16x16x32_bf16 v[106:109], v[138:141], v[170:173], 0
	v_mfma_f32_16x16x32_bf16 v[94:97], v[130:133], v[178:181], 0
	v_mfma_f32_16x16x32_bf16 v[90:93], v[138:141], v[178:181], 0
	v_mfma_f32_16x16x32_bf16 v[78:81], v[130:133], v[206:209], 0
	v_mfma_f32_16x16x32_bf16 v[74:77], v[138:141], v[206:209], 0
	v_mfma_f32_16x16x32_bf16 v[126:129], v[134:137], v[166:169], v[126:129]
	v_mfma_f32_16x16x32_bf16 v[122:125], v[142:145], v[166:169], v[122:125]
	v_mfma_f32_16x16x32_bf16 v[110:113], v[134:137], v[174:177], v[110:113]
	v_mfma_f32_16x16x32_bf16 v[106:109], v[142:145], v[174:177], v[106:109]
	v_mfma_f32_16x16x32_bf16 v[94:97], v[134:137], v[182:185], v[94:97]
	v_mfma_f32_16x16x32_bf16 v[90:93], v[142:145], v[182:185], v[90:93]
	v_mfma_f32_16x16x32_bf16 v[78:81], v[134:137], v[210:213], v[78:81]
	v_mfma_f32_16x16x32_bf16 v[74:77], v[142:145], v[210:213], v[74:77]
	v_mfma_f32_16x16x32_bf16 v[118:121], v[146:149], v[162:165], 0
	v_mfma_f32_16x16x32_bf16 v[114:117], v[154:157], v[162:165], 0
	v_mfma_f32_16x16x32_bf16 v[102:105], v[146:149], v[170:173], 0
	v_mfma_f32_16x16x32_bf16 v[98:101], v[154:157], v[170:173], 0
	v_mfma_f32_16x16x32_bf16 v[86:89], v[146:149], v[178:181], 0
	v_mfma_f32_16x16x32_bf16 v[82:85], v[154:157], v[178:181], 0
	v_mfma_f32_16x16x32_bf16 v[70:73], v[146:149], v[206:209], 0
	v_mfma_f32_16x16x32_bf16 v[66:69], v[154:157], v[206:209], 0
	v_mfma_f32_16x16x32_bf16 v[118:121], v[150:153], v[166:169], v[118:121]
	v_mfma_f32_16x16x32_bf16 v[114:117], v[158:161], v[166:169], v[114:117]
	v_mfma_f32_16x16x32_bf16 v[102:105], v[150:153], v[174:177], v[102:105]
	v_mfma_f32_16x16x32_bf16 v[98:101], v[158:161], v[174:177], v[98:101]
	v_mfma_f32_16x16x32_bf16 v[86:89], v[150:153], v[182:185], v[86:89]
	v_mfma_f32_16x16x32_bf16 v[82:85], v[158:161], v[182:185], v[82:85]
	v_mfma_f32_16x16x32_bf16 v[70:73], v[150:153], v[210:213], v[70:73]
	v_mfma_f32_16x16x32_bf16 v[66:69], v[158:161], v[210:213], v[66:69]
	s_barrier
	s_add_i32 s92, s84, s75
	v_lshl_add_u64 v[216:217], s[60:61], 0, v[0:1]
	s_mov_b32 m0, s92
	ds_read_b128 v[162:165], v215 offset:16384
	ds_read_b128 v[166:169], v215 offset:17408
	ds_read_b128 v[170:173], v215 offset:18432
	ds_read_b128 v[174:177], v215 offset:19456
	ds_read_b128 v[178:181], v215 offset:20480
	ds_read_b128 v[182:185], v215 offset:21504
	ds_read_b128 v[206:209], v215 offset:22528
	ds_read_b128 v[210:213], v215 offset:23552
	global_load_lds_dwordx4 v[216:217], off
	s_add_i32 m0, s92, 0x2000
	s_add_u32 s92, s60, 0x40000
	v_lshl_add_u64 v[218:219], s[60:61], 0, v[196:197]
	s_addc_u32 s93, s61, 0
	s_add_i32 s94, s85, s75
	global_load_lds_dwordx4 v[218:219], off
	v_lshl_add_u64 v[220:221], s[92:93], 0, v[0:1]
	s_mov_b32 m0, s94
	v_lshl_add_u64 v[222:223], s[62:63], 0, v[198:199]
	global_load_lds_dwordx4 v[220:221], off
	v_lshl_add_u64 v[220:221], s[92:93], 0, v[196:197]
	s_add_i32 m0, s94, 0x2000
	s_nop 0
	global_load_lds_dwordx4 v[220:221], off
	v_lshl_add_u64 v[220:221], s[62:63], 0, v[200:201]
	s_mov_b32 m0, s76
	s_nop 0
	global_load_lds_dwordx4 v[220:221], off
	s_mov_b32 m0, s77
	s_nop 0
	global_load_lds_dwordx4 v[222:223], off
	s_waitcnt vmcnt(8)
	s_waitcnt lgkmcnt(0)
	s_barrier
; #define PG8_STAGE(bufoff, gbase, voff) do { _Pragma("unroll") for (int _i = 0; _i < 2; ++_i) \
;         __builtin_amdgcn_global_load_lds((const unsigned*)((const char*)(gbase) + (voff)[_i]), (PG8_LAS unsigned*)(lds + (bufoff) + ldsw + _i * 8192), 16, 0, 0); } while (0)
; #define PG8_LDA(dst, b, h) do { _Pragma("unroll") for (int m = 0; m < 4; ++m) _Pragma("unroll") for (int k = 0; k < 2; ++k) dst[m][k] = *(const PG8_LAS bf16x8*)(lds + PG8_SA(b, h) + aoff + m * 2048 + k * 1024); } while (0)
; #define PG8_LDB(dst, b, h) do { _Pragma("unroll") for (int n = 0; n < 2; ++n) _Pragma("unroll") for (int k = 0; k < 2; ++k) dst[n][k] = *(const PG8_LAS bf16x8*)(lds + PG8_SB(b, h) + boff + n * 2048 + k * 1024); } while (0)
; #define PG8_MMA(ai, bj, At, Bt) do { __builtin_amdgcn_s_setprio(1); _Pragma("unroll") for (int k = 0; k < 2; ++k) _Pragma("unroll") for (int m = 0; m < 4; ++m) _Pragma("unroll") for (int n = 0; n < 2; ++n) \
;         acc[ai][bj][m][n] = __builtin_amdgcn_mfma_f32_16x16x32_bf16(Bt[n][k], At[m][k], acc[ai][bj][m][n], 0, 0, 0); __builtin_amdgcn_s_setprio(0); } while (0)
; #define PG8_WAIT_V(n) asm volatile("s_waitcnt vmcnt(" #n ")" ::: "memory")
; #define PG8_WAIT_L(n) asm volatile("s_waitcnt lgkmcnt(" #n ")" ::: "memory")
; #define PG8_BAR __builtin_amdgcn_s_barrier()
; #define PG8_SCHED __builtin_amdgcn_sched_barrier(0)
; template <class Epi, class Sched, bool ALIGN_EPI = false, bool SP2 = false>
; __device__ __forceinline__ void gemm_phase(PG8_LAS unsigned char* lds, const Gemm g, const Sched& S, const Epi& E, int tid_in) {
;     ...
;             PG8_WAIT_V(8); PG8_WAIT_L(0); PG8_BAR; PG8_MMA(1, 0, At, B0); PG8_MMA(1, 1, At, B1); PG8_BAR; PG8_SCHED;
;             PG8_LDB(B0, 1, 0); PG8_LDB(B1, 1, 1); PG8_SCHED; PG8_LDA(At, 1, 0); PG8_STAGE(PG8_SA(0, 1), a2 + hstep, voffA);
;             PG8_WAIT_V(8); PG8_WAIT_L(0); PG8_BAR; PG8_MMA(0, 0, At, B0); PG8_MMA(0, 1, At, B1); PG8_BAR; PG8_SCHED;
	s_waitcnt lgkmcnt(0)
	v_mfma_f32_16x16x32_bf16 v[62:65], v[130:133], v[162:165], 0
	v_mfma_f32_16x16x32_bf16 v[58:61], v[138:141], v[162:165], 0
	v_mfma_f32_16x16x32_bf16 v[46:49], v[130:133], v[170:173], 0
	v_mfma_f32_16x16x32_bf16 v[42:45], v[138:141], v[170:173], 0
	v_mfma_f32_16x16x32_bf16 v[30:33], v[130:133], v[178:181], 0
	v_mfma_f32_16x16x32_bf16 v[26:29], v[138:141], v[178:181], 0
	v_mfma_f32_16x16x32_bf16 v[14:17], v[130:133], v[206:209], 0
	v_mfma_f32_16x16x32_bf16 v[10:13], v[138:141], v[206:209], 0
	v_mfma_f32_16x16x32_bf16 v[62:65], v[134:137], v[166:169], v[62:65]
	v_mfma_f32_16x16x32_bf16 v[58:61], v[142:145], v[166:169], v[58:61]
	v_mfma_f32_16x16x32_bf16 v[46:49], v[134:137], v[174:177], v[46:49]
	v_mfma_f32_16x16x32_bf16 v[42:45], v[142:145], v[174:177], v[42:45]
	v_mfma_f32_16x16x32_bf16 v[30:33], v[134:137], v[182:185], v[30:33]
	v_mfma_f32_16x16x32_bf16 v[26:29], v[142:145], v[182:185], v[26:29]
	v_mfma_f32_16x16x32_bf16 v[14:17], v[134:137], v[210:213], v[14:17]
	v_mfma_f32_16x16x32_bf16 v[10:13], v[142:145], v[210:213], v[10:13]
	v_mfma_f32_16x16x32_bf16 v[54:57], v[146:149], v[162:165], 0
	v_mfma_f32_16x16x32_bf16 v[50:53], v[154:157], v[162:165], 0
	v_mfma_f32_16x16x32_bf16 v[38:41], v[146:149], v[170:173], 0
	v_mfma_f32_16x16x32_bf16 v[34:37], v[154:157], v[170:173], 0
	v_mfma_f32_16x16x32_bf16 v[22:25], v[146:149], v[178:181], 0
	v_mfma_f32_16x16x32_bf16 v[18:21], v[154:157], v[178:181], 0
	v_mfma_f32_16x16x32_bf16 v[6:9], v[146:149], v[206:209], 0
	v_mfma_f32_16x16x32_bf16 v[2:5], v[154:157], v[206:209], 0
	v_mfma_f32_16x16x32_bf16 v[54:57], v[150:153], v[166:169], v[54:57]
	v_mfma_f32_16x16x32_bf16 v[50:53], v[158:161], v[166:169], v[50:53]
	v_mfma_f32_16x16x32_bf16 v[38:41], v[150:153], v[174:177], v[38:41]
	v_mfma_f32_16x16x32_bf16 v[34:37], v[158:161], v[174:177], v[34:37]
	v_mfma_f32_16x16x32_bf16 v[22:25], v[150:153], v[182:185], v[22:25]
	v_mfma_f32_16x16x32_bf16 v[18:21], v[158:161], v[182:185], v[18:21]
	v_mfma_f32_16x16x32_bf16 v[6:9], v[150:153], v[210:213], v[6:9]
	v_mfma_f32_16x16x32_bf16 v[2:5], v[158:161], v[210:213], v[2:5]
	s_barrier
	v_add_u32_e32 v142, s33, v214
	v_add_u32_e32 v158, s74, v214
	ds_read_b128 v[130:133], v142
	ds_read_b128 v[134:137], v142 offset:1024
	ds_read_b128 v[138:141], v142 offset:2048
	ds_read_b128 v[142:145], v142 offset:3072
	ds_read_b128 v[146:149], v158
	ds_read_b128 v[150:153], v158 offset:1024
	ds_read_b128 v[154:157], v158 offset:2048
	ds_read_b128 v[158:161], v158 offset:3072
	s_add_u32 s62, s62, 0x40000
	s_addc_u32 s63, s63, 0
	s_mov_b32 m0, s78
	v_lshl_add_u64 v[224:225], s[62:63], 0, v[200:201]
	ds_read_b128 v[162:165], v215 offset:32768
	ds_read_b128 v[166:169], v215 offset:33792
	ds_read_b128 v[170:173], v215 offset:34816
	ds_read_b128 v[174:177], v215 offset:35840
	ds_read_b128 v[178:181], v215 offset:36864
	ds_read_b128 v[182:185], v215 offset:37888
	ds_read_b128 v[206:209], v215 offset:38912
	ds_read_b128 v[210:213], v215 offset:39936
	global_load_lds_dwordx4 v[224:225], off
	v_lshl_add_u64 v[224:225], s[62:63], 0, v[198:199]
	s_mov_b32 m0, s79
	s_nop 0
	global_load_lds_dwordx4 v[224:225], off
	s_waitcnt vmcnt(8)
	s_waitcnt lgkmcnt(0)
	s_barrier
	s_waitcnt lgkmcnt(0)
	v_mfma_f32_16x16x32_bf16 v[126:129], v[130:133], v[162:165], v[126:129]
	v_mfma_f32_16x16x32_bf16 v[122:125], v[138:141], v[162:165], v[122:125]
	v_mfma_f32_16x16x32_bf16 v[110:113], v[130:133], v[170:173], v[110:113]
	v_mfma_f32_16x16x32_bf16 v[106:109], v[138:141], v[170:173], v[106:109]
	v_mfma_f32_16x16x32_bf16 v[94:97], v[130:133], v[178:181], v[94:97]
	v_mfma_f32_16x16x32_bf16 v[90:93], v[138:141], v[178:181], v[90:93]
	v_mfma_f32_16x16x32_bf16 v[78:81], v[130:133], v[206:209], v[78:81]
	v_mfma_f32_16x16x32_bf16 v[74:77], v[138:141], v[206:209], v[74:77]
	v_mfma_f32_16x16x32_bf16 v[126:129], v[134:137], v[166:169], v[126:129]
	v_mfma_f32_16x16x32_bf16 v[122:125], v[142:145], v[166:169], v[122:125]
	v_mfma_f32_16x16x32_bf16 v[110:113], v[134:137], v[174:177], v[110:113]
	v_mfma_f32_16x16x32_bf16 v[106:109], v[142:145], v[174:177], v[106:109]
	v_mfma_f32_16x16x32_bf16 v[94:97], v[134:137], v[182:185], v[94:97]
	v_mfma_f32_16x16x32_bf16 v[90:93], v[142:145], v[182:185], v[90:93]
	v_mfma_f32_16x16x32_bf16 v[78:81], v[134:137], v[210:213], v[78:81]
	v_mfma_f32_16x16x32_bf16 v[74:77], v[142:145], v[210:213], v[74:77]
	v_mfma_f32_16x16x32_bf16 v[118:121], v[146:149], v[162:165], v[118:121]
	v_mfma_f32_16x16x32_bf16 v[114:117], v[154:157], v[162:165], v[114:117]
	v_mfma_f32_16x16x32_bf16 v[102:105], v[146:149], v[170:173], v[102:105]
	v_mfma_f32_16x16x32_bf16 v[98:101], v[154:157], v[170:173], v[98:101]
	v_mfma_f32_16x16x32_bf16 v[86:89], v[146:149], v[178:181], v[86:89]
	v_mfma_f32_16x16x32_bf16 v[82:85], v[154:157], v[178:181], v[82:85]
	v_mfma_f32_16x16x32_bf16 v[70:73], v[146:149], v[206:209], v[70:73]
	v_mfma_f32_16x16x32_bf16 v[66:69], v[154:157], v[206:209], v[66:69]
	v_mfma_f32_16x16x32_bf16 v[118:121], v[150:153], v[166:169], v[118:121]
	v_mfma_f32_16x16x32_bf16 v[114:117], v[158:161], v[166:169], v[114:117]
	v_mfma_f32_16x16x32_bf16 v[102:105], v[150:153], v[174:177], v[102:105]
	v_mfma_f32_16x16x32_bf16 v[98:101], v[158:161], v[174:177], v[98:101]
	v_mfma_f32_16x16x32_bf16 v[86:89], v[150:153], v[182:185], v[86:89]
	v_mfma_f32_16x16x32_bf16 v[82:85], v[158:161], v[182:185], v[82:85]
	v_mfma_f32_16x16x32_bf16 v[70:73], v[150:153], v[210:213], v[70:73]
	v_mfma_f32_16x16x32_bf16 v[66:69], v[158:161], v[210:213], v[66:69]
	s_barrier
; #define PG8_STAGE(bufoff, gbase, voff) do { _Pragma("unroll") for (int _i = 0; _i < 2; ++_i) \
;         __builtin_amdgcn_global_load_lds((const unsigned*)((const char*)(gbase) + (voff)[_i]), (PG8_LAS unsigned*)(lds + (bufoff) + ldsw + _i * 8192), 16, 0, 0); } while (0)
; #define PG8_LDA(dst, b, h) do { _Pragma("unroll") for (int m = 0; m < 4; ++m) _Pragma("unroll") for (int k = 0; k < 2; ++k) dst[m][k] = *(const PG8_LAS bf16x8*)(lds + PG8_SA(b, h) + aoff + m * 2048 + k * 1024); } while (0)
; #define PG8_LDB(dst, b, h) do { _Pragma("unroll") for (int n = 0; n < 2; ++n) _Pragma("unroll") for (int k = 0; k < 2; ++k) dst[n][k] = *(const PG8_LAS bf16x8*)(lds + PG8_SB(b, h) + boff + n * 2048 + k * 1024); } while (0)
; template <class Epi, class Sched, bool ALIGN_EPI = false, bool SP2 = false>
; __device__ __forceinline__ void gemm_phase(PG8_LAS unsigned char* lds, const Gemm g, const Sched& S, const Epi& E, int tid_in) {
;     ...
;             const bool last = (t == nt - 2);
;             const char* a1 = cA + (size_t)(t + 1) * kstep;
;             const char* a2 = last ? nA : cA + (size_t)(t + 2) * kstep; const char* b2 = last ? nB : cB + (size_t)(t + 2) * kstep;
;             const char* a3 = a2 + kstep; const char* b3 = b2 + kstep;
;             if (last && has_next) S.a_ready(nxt);
;             if constexpr (SP2) {
;             PG8_LDB(B0, 0, 0); PG8_LDB(B1, 0, 1); PG8_SCHED; PG8_LDA(At, 0, 0); PG8_STAGE(PG8_SA(1, 1), a1 + hstep, voffA);
;             PG8_WAIT_V(8); PG8_WAIT_L(0); PG8_BAR; PG8_MMA(0, 0, At, B0); PG8_MMA(0, 1, At, B1); PG8_BAR; PG8_SCHED;
;             PG8_LDA(At, 0, 1); PG8_STAGE(PG8_SB(0, 0), b2, voffB); PG8_STAGE(PG8_SB(0, 1), b2 + hstep, voffB); PG8_STAGE(PG8_SA(0, 0), a2, voffA);
;             PG8_WAIT_V(8); PG8_WAIT_L(0); PG8_BAR; PG8_MMA(1, 0, At, B0); PG8_MMA(1, 1, At, B1); PG8_BAR; PG8_SCHED;
;             PG8_LDB(B0, 1, 0); PG8_LDB(B1, 1, 1); PG8_SCHED; PG8_LDA(At, 1, 0); PG8_STAGE(PG8_SA(0, 1), a2 + hstep, voffA);
;             PG8_WAIT_V(8); PG8_WAIT_L(0); PG8_BAR; PG8_MMA(0, 0, At, B0); PG8_MMA(0, 1, At, B1); PG8_BAR; PG8_SCHED;
;             PG8_LDA(At, 1, 1); PG8_STAGE(PG8_SB(1, 0), b3, voffB); PG8_STAGE(PG8_SB(1, 1), b3 + hstep, voffB); PG8_STAGE(PG8_SA(1, 0), a3, voffA);
;             PG8_WAIT_V(8); PG8_WAIT_L(0); PG8_BAR; PG8_MMA(1, 0, At, B0); PG8_MMA(1, 1, At, B1); PG8_BAR; PG8_SCHED;
	s_add_i32 s62, s33, s75
	v_lshl_add_u64 v[216:217], v[216:217], 0, s[26:27]
	s_mov_b32 m0, s62
	ds_read_b128 v[162:165], v215 offset:49152
	ds_read_b128 v[166:169], v215 offset:50176
	ds_read_b128 v[170:173], v215 offset:51200
	ds_read_b128 v[174:177], v215 offset:52224
	ds_read_b128 v[178:181], v215 offset:53248
	ds_read_b128 v[182:185], v215 offset:54272
	ds_read_b128 v[206:209], v215 offset:55296
	ds_read_b128 v[210:213], v215 offset:56320
	global_load_lds_dwordx4 v[216:217], off
	s_add_i32 m0, s62, 0x2000
	s_add_u32 s60, s60, 0x40080
	v_lshl_add_u64 v[216:217], v[218:219], 0, s[26:27]
	s_addc_u32 s61, s61, 0
	s_add_i32 s62, s74, s75
	global_load_lds_dwordx4 v[216:217], off
	v_lshl_add_u64 v[216:217], s[60:61], 0, v[0:1]
	s_mov_b32 m0, s62
	s_nop 0
	global_load_lds_dwordx4 v[216:217], off
	v_lshl_add_u64 v[216:217], s[60:61], 0, v[196:197]
	s_add_i32 m0, s62, 0x2000
	s_nop 0
	global_load_lds_dwordx4 v[216:217], off
	v_lshl_add_u64 v[216:217], v[220:221], 0, s[26:27]
	s_mov_b32 m0, s38
	s_nop 0
	global_load_lds_dwordx4 v[216:217], off
	v_lshl_add_u64 v[216:217], v[222:223], 0, s[26:27]
	s_mov_b32 m0, s39
	s_nop 0
	global_load_lds_dwordx4 v[216:217], off
	s_waitcnt vmcnt(8)
	s_waitcnt lgkmcnt(0)
	s_barrier
	s_waitcnt lgkmcnt(0)
	v_mfma_f32_16x16x32_bf16 v[62:65], v[130:133], v[162:165], v[62:65]
	v_mfma_f32_16x16x32_bf16 v[58:61], v[138:141], v[162:165], v[58:61]
	v_mfma_f32_16x16x32_bf16 v[46:49], v[130:133], v[170:173], v[46:49]
	v_mfma_f32_16x16x32_bf16 v[42:45], v[138:141], v[170:173], v[42:45]
	v_mfma_f32_16x16x32_bf16 v[30:33], v[130:133], v[178:181], v[30:33]
	v_mfma_f32_16x16x32_bf16 v[26:29], v[138:141], v[178:181], v[26:29]
	v_mfma_f32_16x16x32_bf16 v[14:17], v[130:133], v[206:209], v[14:17]
	v_mfma_f32_16x16x32_bf16 v[10:13], v[138:141], v[206:209], v[10:13]
	v_mfma_f32_16x16x32_bf16 v[62:65], v[134:137], v[166:169], v[62:65]
	v_mfma_f32_16x16x32_bf16 v[58:61], v[142:145], v[166:169], v[58:61]
	v_mfma_f32_16x16x32_bf16 v[46:49], v[134:137], v[174:177], v[46:49]
	v_mfma_f32_16x16x32_bf16 v[42:45], v[142:145], v[174:177], v[42:45]
	v_mfma_f32_16x16x32_bf16 v[30:33], v[134:137], v[182:185], v[30:33]
	v_mfma_f32_16x16x32_bf16 v[26:29], v[142:145], v[182:185], v[26:29]
	v_mfma_f32_16x16x32_bf16 v[14:17], v[134:137], v[210:213], v[14:17]
	v_mfma_f32_16x16x32_bf16 v[10:13], v[142:145], v[210:213], v[10:13]
	v_mfma_f32_16x16x32_bf16 v[54:57], v[146:149], v[162:165], v[54:57]
	v_mfma_f32_16x16x32_bf16 v[50:53], v[154:157], v[162:165], v[50:53]
	v_mfma_f32_16x16x32_bf16 v[38:41], v[146:149], v[170:173], v[38:41]
	v_mfma_f32_16x16x32_bf16 v[34:37], v[154:157], v[170:173], v[34:37]
	v_mfma_f32_16x16x32_bf16 v[22:25], v[146:149], v[178:181], v[22:25]
	v_mfma_f32_16x16x32_bf16 v[18:21], v[154:157], v[178:181], v[18:21]
	v_mfma_f32_16x16x32_bf16 v[6:9], v[146:149], v[206:209], v[6:9]
	v_mfma_f32_16x16x32_bf16 v[2:5], v[154:157], v[206:209], v[2:5]
	v_mfma_f32_16x16x32_bf16 v[54:57], v[150:153], v[166:169], v[54:57]
	v_mfma_f32_16x16x32_bf16 v[50:53], v[158:161], v[166:169], v[50:53]
	v_mfma_f32_16x16x32_bf16 v[38:41], v[150:153], v[174:177], v[38:41]
	v_mfma_f32_16x16x32_bf16 v[34:37], v[158:161], v[174:177], v[34:37]
	v_mfma_f32_16x16x32_bf16 v[22:25], v[150:153], v[182:185], v[22:25]
	v_mfma_f32_16x16x32_bf16 v[18:21], v[158:161], v[182:185], v[18:21]
	v_mfma_f32_16x16x32_bf16 v[6:9], v[150:153], v[210:213], v[6:9]
	v_mfma_f32_16x16x32_bf16 v[2:5], v[158:161], v[210:213], v[2:5]
	s_barrier
	s_add_i32 vcc_hi, vcc_hi, 2
	s_add_u32 s58, s58, 0x100
	s_addc_u32 s59, s59, 0
	s_add_u32 s83, s83, 0x100
	s_addc_u32 vcc_lo, vcc_lo, 0
	s_cmp_gt_u32 vcc_hi, 13
.LBB0_359:
	v_add_u32_e32 v142, s84, v214
	v_add_u32_e32 v158, s85, v214
	s_waitcnt lgkmcnt(0)
	ds_read_b128 v[130:133], v142
	ds_read_b128 v[134:137], v142 offset:1024
	ds_read_b128 v[138:141], v142 offset:2048
	ds_read_b128 v[142:145], v142 offset:3072
	ds_read_b128 v[146:149], v158
	ds_read_b128 v[150:153], v158 offset:1024
	ds_read_b128 v[154:157], v158 offset:2048
	ds_read_b128 v[158:161], v158 offset:3072
	s_add_u32 s60, s58, 0xfffc0080
	s_addc_u32 s61, s59, -1
	s_cmp_eq_u32 vcc_hi, 12
	s_cselect_b32 s63, s51, s61
	s_cselect_b32 s62, s81, s60
	s_cselect_b32 s61, s53, vcc_lo
	s_cselect_b32 s60, s82, s83
	v_lshl_add_u64 v[216:217], s[58:59], 0, v[202:203]
	s_add_i32 m0, s76, 0xc000
	ds_read_b128 v[162:165], v215
	ds_read_b128 v[166:169], v215 offset:1024
	ds_read_b128 v[170:173], v215 offset:2048
	ds_read_b128 v[174:177], v215 offset:3072
	ds_read_b128 v[178:181], v215 offset:4096
	ds_read_b128 v[182:185], v215 offset:5120
	ds_read_b128 v[206:209], v215 offset:6144
	ds_read_b128 v[210:213], v215 offset:7168
	global_load_lds_dwordx4 v[216:217], off
	v_lshl_add_u64 v[216:217], s[58:59], 0, v[204:205]
	s_add_i32 m0, s76, 0xe000
	s_nop 0
	global_load_lds_dwordx4 v[216:217], off
	s_waitcnt vmcnt(8)
	s_waitcnt lgkmcnt(0)
	s_barrier
; #define PG8_STAGE(bufoff, gbase, voff) do { _Pragma("unroll") for (int _i = 0; _i < 2; ++_i) \
;         __builtin_amdgcn_global_load_lds((const unsigned*)((const char*)(gbase) + (voff)[_i]), (PG8_LAS unsigned*)(lds + (bufoff) + ldsw + _i * 8192), 16, 0, 0); } while (0)
; #define PG8_LDA(dst, b, h) do { _Pragma("unroll") for (int m = 0; m < 4; ++m) _Pragma("unroll") for (int k = 0; k < 2; ++k) dst[m][k] = *(const PG8_LAS bf16x8*)(lds + PG8_SA(b, h) + aoff + m * 2048 + k * 1024); } while (0)
; #define PG8_MMA(ai, bj, At, Bt) do { __builtin_amdgcn_s_setprio(1); _Pragma("unroll") for (int k = 0; k < 2; ++k) _Pragma("unroll") for (int m = 0; m < 4; ++m) _Pragma("unroll") for (int n = 0; n < 2; ++n) \
;         acc[ai][bj][m][n] = __builtin_amdgcn_mfma_f32_16x16x32_bf16(Bt[n][k], At[m][k], acc[ai][bj][m][n], 0, 0, 0); __builtin_amdgcn_s_setprio(0); } while (0)
; #define PG8_WAIT_V(n) asm volatile("s_waitcnt vmcnt(" #n ")" ::: "memory")
; #define PG8_WAIT_L(n) asm volatile("s_waitcnt lgkmcnt(" #n ")" ::: "memory")
; #define PG8_BAR __builtin_amdgcn_s_barrier()
; #define PG8_SCHED __builtin_amdgcn_sched_barrier(0)
; template <class Epi, class Sched, bool ALIGN_EPI = false, bool SP2 = false>
; __device__ __forceinline__ void gemm_phase(PG8_LAS unsigned char* lds, const Gemm g, const Sched& S, const Epi& E, int tid_in) {
;     ...
;             PG8_WAIT_V(8); PG8_WAIT_L(0); PG8_BAR; PG8_MMA(0, 0, At, B0); PG8_MMA(0, 1, At, B1); PG8_BAR; PG8_SCHED;
;             PG8_LDA(At, 0, 1); PG8_STAGE(PG8_SB(0, 0), b2, voffB); PG8_STAGE(PG8_SB(0, 1), b2 + hstep, voffB); PG8_STAGE(PG8_SA(0, 0), a2, voffA);
;             PG8_WAIT_V(8); PG8_WAIT_L(0); PG8_BAR; PG8_MMA(1, 0, At, B0); PG8_MMA(1, 1, At, B1); PG8_BAR; PG8_SCHED;
	s_waitcnt lgkmcnt(0)
	v_mfma_f32_16x16x32_bf16 v[126:129], v[130:133], v[162:165], v[126:129]
	v_mfma_f32_16x16x32_bf16 v[122:125], v[138:141], v[162:165], v[122:125]
	v_mfma_f32_16x16x32_bf16 v[110:113], v[130:133], v[170:173], v[110:113]
	v_mfma_f32_16x16x32_bf16 v[106:109], v[138:141], v[170:173], v[106:109]
	v_mfma_f32_16x16x32_bf16 v[94:97], v[130:133], v[178:181], v[94:97]
	v_mfma_f32_16x16x32_bf16 v[90:93], v[138:141], v[178:181], v[90:93]
	v_mfma_f32_16x16x32_bf16 v[78:81], v[130:133], v[206:209], v[78:81]
	v_mfma_f32_16x16x32_bf16 v[74:77], v[138:141], v[206:209], v[74:77]
	v_mfma_f32_16x16x32_bf16 v[126:129], v[134:137], v[166:169], v[126:129]
	v_mfma_f32_16x16x32_bf16 v[122:125], v[142:145], v[166:169], v[122:125]
	v_mfma_f32_16x16x32_bf16 v[110:113], v[134:137], v[174:177], v[110:113]
	v_mfma_f32_16x16x32_bf16 v[106:109], v[142:145], v[174:177], v[106:109]
	v_mfma_f32_16x16x32_bf16 v[94:97], v[134:137], v[182:185], v[94:97]
	v_mfma_f32_16x16x32_bf16 v[90:93], v[142:145], v[182:185], v[90:93]
	v_mfma_f32_16x16x32_bf16 v[78:81], v[134:137], v[210:213], v[78:81]
	v_mfma_f32_16x16x32_bf16 v[74:77], v[142:145], v[210:213], v[74:77]
	v_mfma_f32_16x16x32_bf16 v[118:121], v[146:149], v[162:165], v[118:121]
	v_mfma_f32_16x16x32_bf16 v[114:117], v[154:157], v[162:165], v[114:117]
	v_mfma_f32_16x16x32_bf16 v[102:105], v[146:149], v[170:173], v[102:105]
	v_mfma_f32_16x16x32_bf16 v[98:101], v[154:157], v[170:173], v[98:101]
	v_mfma_f32_16x16x32_bf16 v[86:89], v[146:149], v[178:181], v[86:89]
	v_mfma_f32_16x16x32_bf16 v[82:85], v[154:157], v[178:181], v[82:85]
	v_mfma_f32_16x16x32_bf16 v[70:73], v[146:149], v[206:209], v[70:73]
	v_mfma_f32_16x16x32_bf16 v[66:69], v[154:157], v[206:209], v[66:69]
	v_mfma_f32_16x16x32_bf16 v[118:121], v[150:153], v[166:169], v[118:121]
	v_mfma_f32_16x16x32_bf16 v[114:117], v[158:161], v[166:169], v[114:117]
	v_mfma_f32_16x16x32_bf16 v[102:105], v[150:153], v[174:177], v[102:105]
	v_mfma_f32_16x16x32_bf16 v[98:101], v[158:161], v[174:177], v[98:101]
	v_mfma_f32_16x16x32_bf16 v[86:89], v[150:153], v[182:185], v[86:89]
	v_mfma_f32_16x16x32_bf16 v[82:85], v[158:161], v[182:185], v[82:85]
	v_mfma_f32_16x16x32_bf16 v[70:73], v[150:153], v[210:213], v[70:73]
	v_mfma_f32_16x16x32_bf16 v[66:69], v[158:161], v[210:213], v[66:69]
	s_barrier
	s_add_i32 s92, s84, s75
	v_lshl_add_u64 v[216:217], s[60:61], 0, v[0:1]
	s_mov_b32 m0, s92
	ds_read_b128 v[162:165], v215 offset:16384
	ds_read_b128 v[166:169], v215 offset:17408
	ds_read_b128 v[170:173], v215 offset:18432
	ds_read_b128 v[174:177], v215 offset:19456
	ds_read_b128 v[178:181], v215 offset:20480
	ds_read_b128 v[182:185], v215 offset:21504
	ds_read_b128 v[206:209], v215 offset:22528
	ds_read_b128 v[210:213], v215 offset:23552
	global_load_lds_dwordx4 v[216:217], off
	s_add_i32 m0, s92, 0x2000
	s_add_u32 s92, s60, 0x40000
	v_lshl_add_u64 v[218:219], s[60:61], 0, v[196:197]
	s_addc_u32 s93, s61, 0
	s_add_i32 s94, s85, s75
	global_load_lds_dwordx4 v[218:219], off
	v_lshl_add_u64 v[220:221], s[92:93], 0, v[0:1]
	s_mov_b32 m0, s94
	v_lshl_add_u64 v[222:223], s[62:63], 0, v[198:199]
	global_load_lds_dwordx4 v[220:221], off
	v_lshl_add_u64 v[220:221], s[92:93], 0, v[196:197]
	s_add_i32 m0, s94, 0x2000
	s_nop 0
	global_load_lds_dwordx4 v[220:221], off
	v_lshl_add_u64 v[220:221], s[62:63], 0, v[200:201]
	s_mov_b32 m0, s76
	s_nop 0
	global_load_lds_dwordx4 v[220:221], off
	s_mov_b32 m0, s77
	s_nop 0
	global_load_lds_dwordx4 v[222:223], off
	s_waitcnt vmcnt(8)
	s_waitcnt lgkmcnt(0)
	s_barrier
	s_waitcnt lgkmcnt(0)
	v_mfma_f32_16x16x32_bf16 v[62:65], v[130:133], v[162:165], v[62:65]
	v_mfma_f32_16x16x32_bf16 v[58:61], v[138:141], v[162:165], v[58:61]
	v_mfma_f32_16x16x32_bf16 v[46:49], v[130:133], v[170:173], v[46:49]
	v_mfma_f32_16x16x32_bf16 v[42:45], v[138:141], v[170:173], v[42:45]
	v_mfma_f32_16x16x32_bf16 v[30:33], v[130:133], v[178:181], v[30:33]
	v_mfma_f32_16x16x32_bf16 v[26:29], v[138:141], v[178:181], v[26:29]
	v_mfma_f32_16x16x32_bf16 v[14:17], v[130:133], v[206:209], v[14:17]
	v_mfma_f32_16x16x32_bf16 v[10:13], v[138:141], v[206:209], v[10:13]
	v_mfma_f32_16x16x32_bf16 v[62:65], v[134:137], v[166:169], v[62:65]
	v_mfma_f32_16x16x32_bf16 v[58:61], v[142:145], v[166:169], v[58:61]
	v_mfma_f32_16x16x32_bf16 v[46:49], v[134:137], v[174:177], v[46:49]
	v_mfma_f32_16x16x32_bf16 v[42:45], v[142:145], v[174:177], v[42:45]
	v_mfma_f32_16x16x32_bf16 v[30:33], v[134:137], v[182:185], v[30:33]
	v_mfma_f32_16x16x32_bf16 v[26:29], v[142:145], v[182:185], v[26:29]
	v_mfma_f32_16x16x32_bf16 v[14:17], v[134:137], v[210:213], v[14:17]
	v_mfma_f32_16x16x32_bf16 v[10:13], v[142:145], v[210:213], v[10:13]
	v_mfma_f32_16x16x32_bf16 v[54:57], v[146:149], v[162:165], v[54:57]
	v_mfma_f32_16x16x32_bf16 v[50:53], v[154:157], v[162:165], v[50:53]
	v_mfma_f32_16x16x32_bf16 v[38:41], v[146:149], v[170:173], v[38:41]
	v_mfma_f32_16x16x32_bf16 v[34:37], v[154:157], v[170:173], v[34:37]
	v_mfma_f32_16x16x32_bf16 v[22:25], v[146:149], v[178:181], v[22:25]
	v_mfma_f32_16x16x32_bf16 v[18:21], v[154:157], v[178:181], v[18:21]
	v_mfma_f32_16x16x32_bf16 v[6:9], v[146:149], v[206:209], v[6:9]
	v_mfma_f32_16x16x32_bf16 v[2:5], v[154:157], v[206:209], v[2:5]
	v_mfma_f32_16x16x32_bf16 v[54:57], v[150:153], v[166:169], v[54:57]
	v_mfma_f32_16x16x32_bf16 v[50:53], v[158:161], v[166:169], v[50:53]
	v_mfma_f32_16x16x32_bf16 v[38:41], v[150:153], v[174:177], v[38:41]
	v_mfma_f32_16x16x32_bf16 v[34:37], v[158:161], v[174:177], v[34:37]
	v_mfma_f32_16x16x32_bf16 v[22:25], v[150:153], v[182:185], v[22:25]
	v_mfma_f32_16x16x32_bf16 v[18:21], v[158:161], v[182:185], v[18:21]
	v_mfma_f32_16x16x32_bf16 v[6:9], v[150:153], v[210:213], v[6:9]
	v_mfma_f32_16x16x32_bf16 v[2:5], v[158:161], v[210:213], v[2:5]
	s_barrier
; #define PG8_STAGE(bufoff, gbase, voff) do { _Pragma("unroll") for (int _i = 0; _i < 2; ++_i) \
;         __builtin_amdgcn_global_load_lds((const unsigned*)((const char*)(gbase) + (voff)[_i]), (PG8_LAS unsigned*)(lds + (bufoff) + ldsw + _i * 8192), 16, 0, 0); } while (0)
; #define PG8_LDA(dst, b, h) do { _Pragma("unroll") for (int m = 0; m < 4; ++m) _Pragma("unroll") for (int k = 0; k < 2; ++k) dst[m][k] = *(const PG8_LAS bf16x8*)(lds + PG8_SA(b, h) + aoff + m * 2048 + k * 1024); } while (0)
; #define PG8_LDB(dst, b, h) do { _Pragma("unroll") for (int n = 0; n < 2; ++n) _Pragma("unroll") for (int k = 0; k < 2; ++k) dst[n][k] = *(const PG8_LAS bf16x8*)(lds + PG8_SB(b, h) + boff + n * 2048 + k * 1024); } while (0)
; #define PG8_MMA(ai, bj, At, Bt) do { __builtin_amdgcn_s_setprio(1); _Pragma("unroll") for (int k = 0; k < 2; ++k) _Pragma("unroll") for (int m = 0; m < 4; ++m) _Pragma("unroll") for (int n = 0; n < 2; ++n) \
;         acc[ai][bj][m][n] = __builtin_amdgcn_mfma_f32_16x16x32_bf16(Bt[n][k], At[m][k], acc[ai][bj][m][n], 0, 0, 0); __builtin_amdgcn_s_setprio(0); } while (0)
; #define PG8_WAIT_V(n) asm volatile("s_waitcnt vmcnt(" #n ")" ::: "memory")
; #define PG8_WAIT_L(n) asm volatile("s_waitcnt lgkmcnt(" #n ")" ::: "memory")
; #define PG8_BAR __builtin_amdgcn_s_barrier()
; #define PG8_SCHED __builtin_amdgcn_sched_barrier(0)
; template <class Epi, class Sched, bool ALIGN_EPI = false, bool SP2 = false>
; __device__ __forceinline__ void gemm_phase(PG8_LAS unsigned char* lds, const Gemm g, const Sched& S, const Epi& E, int tid_in) {
;     ...
;             PG8_LDB(B0, 1, 0); PG8_LDB(B1, 1, 1); PG8_SCHED; PG8_LDA(At, 1, 0); PG8_STAGE(PG8_SA(0, 1), a2 + hstep, voffA);
;             PG8_WAIT_V(8); PG8_WAIT_L(0); PG8_BAR; PG8_MMA(0, 0, At, B0); PG8_MMA(0, 1, At, B1); PG8_BAR; PG8_SCHED;
	v_add_u32_e32 v142, s33, v214
	v_add_u32_e32 v158, s74, v214
	ds_read_b128 v[130:133], v142
	ds_read_b128 v[134:137], v142 offset:1024
	ds_read_b128 v[138:141], v142 offset:2048
	ds_read_b128 v[142:145], v142 offset:3072
	ds_read_b128 v[146:149], v158
	ds_read_b128 v[150:153], v158 offset:1024
	ds_read_b128 v[154:157], v158 offset:2048
	ds_read_b128 v[158:161], v158 offset:3072
	s_add_u32 s62, s62, 0x40000
	s_addc_u32 s63, s63, 0
	s_mov_b32 m0, s78
	v_lshl_add_u64 v[224:225], s[62:63], 0, v[200:201]
	ds_read_b128 v[162:165], v215 offset:32768
	ds_read_b128 v[166:169], v215 offset:33792
	ds_read_b128 v[170:173], v215 offset:34816
	ds_read_b128 v[174:177], v215 offset:35840
	ds_read_b128 v[178:181], v215 offset:36864
	ds_read_b128 v[182:185], v215 offset:37888
	ds_read_b128 v[206:209], v215 offset:38912
	ds_read_b128 v[210:213], v215 offset:39936
	global_load_lds_dwordx4 v[224:225], off
	v_lshl_add_u64 v[224:225], s[62:63], 0, v[198:199]
	s_mov_b32 m0, s79
	s_nop 0
	global_load_lds_dwordx4 v[224:225], off
	s_waitcnt vmcnt(8)
	s_waitcnt lgkmcnt(0)
	s_barrier
	s_waitcnt lgkmcnt(0)
	v_mfma_f32_16x16x32_bf16 v[126:129], v[130:133], v[162:165], v[126:129]
	v_mfma_f32_16x16x32_bf16 v[122:125], v[138:141], v[162:165], v[122:125]
	v_mfma_f32_16x16x32_bf16 v[110:113], v[130:133], v[170:173], v[110:113]
	v_mfma_f32_16x16x32_bf16 v[106:109], v[138:141], v[170:173], v[106:109]
	v_mfma_f32_16x16x32_bf16 v[94:97], v[130:133], v[178:181], v[94:97]
	v_mfma_f32_16x16x32_bf16 v[90:93], v[138:141], v[178:181], v[90:93]
	v_mfma_f32_16x16x32_bf16 v[78:81], v[130:133], v[206:209], v[78:81]
	v_mfma_f32_16x16x32_bf16 v[74:77], v[138:141], v[206:209], v[74:77]
	v_mfma_f32_16x16x32_bf16 v[126:129], v[134:137], v[166:169], v[126:129]
	v_mfma_f32_16x16x32_bf16 v[122:125], v[142:145], v[166:169], v[122:125]
	v_mfma_f32_16x16x32_bf16 v[110:113], v[134:137], v[174:177], v[110:113]
	v_mfma_f32_16x16x32_bf16 v[106:109], v[142:145], v[174:177], v[106:109]
	v_mfma_f32_16x16x32_bf16 v[94:97], v[134:137], v[182:185], v[94:97]
	v_mfma_f32_16x16x32_bf16 v[90:93], v[142:145], v[182:185], v[90:93]
	v_mfma_f32_16x16x32_bf16 v[78:81], v[134:137], v[210:213], v[78:81]
	v_mfma_f32_16x16x32_bf16 v[74:77], v[142:145], v[210:213], v[74:77]
	v_mfma_f32_16x16x32_bf16 v[118:121], v[146:149], v[162:165], v[118:121]
	v_mfma_f32_16x16x32_bf16 v[114:117], v[154:157], v[162:165], v[114:117]
	v_mfma_f32_16x16x32_bf16 v[102:105], v[146:149], v[170:173], v[102:105]
	v_mfma_f32_16x16x32_bf16 v[98:101], v[154:157], v[170:173], v[98:101]
	v_mfma_f32_16x16x32_bf16 v[86:89], v[146:149], v[178:181], v[86:89]
	v_mfma_f32_16x16x32_bf16 v[82:85], v[154:157], v[178:181], v[82:85]
	v_mfma_f32_16x16x32_bf16 v[70:73], v[146:149], v[206:209], v[70:73]
	v_mfma_f32_16x16x32_bf16 v[66:69], v[154:157], v[206:209], v[66:69]
	v_mfma_f32_16x16x32_bf16 v[118:121], v[150:153], v[166:169], v[118:121]
	v_mfma_f32_16x16x32_bf16 v[114:117], v[158:161], v[166:169], v[114:117]
	v_mfma_f32_16x16x32_bf16 v[102:105], v[150:153], v[174:177], v[102:105]
	v_mfma_f32_16x16x32_bf16 v[98:101], v[158:161], v[174:177], v[98:101]
	v_mfma_f32_16x16x32_bf16 v[86:89], v[150:153], v[182:185], v[86:89]
	v_mfma_f32_16x16x32_bf16 v[82:85], v[158:161], v[182:185], v[82:85]
	v_mfma_f32_16x16x32_bf16 v[70:73], v[150:153], v[210:213], v[70:73]
	v_mfma_f32_16x16x32_bf16 v[66:69], v[158:161], v[210:213], v[66:69]
	s_barrier
; #define PG8_STAGE(bufoff, gbase, voff) do { _Pragma("unroll") for (int _i = 0; _i < 2; ++_i) \
;         __builtin_amdgcn_global_load_lds((const unsigned*)((const char*)(gbase) + (voff)[_i]), (PG8_LAS unsigned*)(lds + (bufoff) + ldsw + _i * 8192), 16, 0, 0); } while (0)
; #define PG8_LDA(dst, b, h) do { _Pragma("unroll") for (int m = 0; m < 4; ++m) _Pragma("unroll") for (int k = 0; k < 2; ++k) dst[m][k] = *(const PG8_LAS bf16x8*)(lds + PG8_SA(b, h) + aoff + m * 2048 + k * 1024); } while (0)
; #define PG8_MMA(ai, bj, At, Bt) do { __builtin_amdgcn_s_setprio(1); _Pragma("unroll") for (int k = 0; k < 2; ++k) _Pragma("unroll") for (int m = 0; m < 4; ++m) _Pragma("unroll") for (int n = 0; n < 2; ++n) \
;         acc[ai][bj][m][n] = __builtin_amdgcn_mfma_f32_16x16x32_bf16(Bt[n][k], At[m][k], acc[ai][bj][m][n], 0, 0, 0); __builtin_amdgcn_s_setprio(0); } while (0)
; #define PG8_WAIT_V(n) asm volatile("s_waitcnt vmcnt(" #n ")" ::: "memory")
; #define PG8_WAIT_L(n) asm volatile("s_waitcnt lgkmcnt(" #n ")" ::: "memory")
; #define PG8_BAR __builtin_amdgcn_s_barrier()
; #define PG8_SCHED __builtin_amdgcn_sched_barrier(0)
; template <class Epi, class Sched, bool ALIGN_EPI = false, bool SP2 = false>
; __device__ __forceinline__ void gemm_phase(PG8_LAS unsigned char* lds, const Gemm g, const Sched& S, const Epi& E, int tid_in) {
;     ...
;             PG8_LDA(At, 1, 1); PG8_STAGE(PG8_SB(1, 0), b3, voffB); PG8_STAGE(PG8_SB(1, 1), b3 + hstep, voffB); PG8_STAGE(PG8_SA(1, 0), a3, voffA);
;             PG8_WAIT_V(8); PG8_WAIT_L(0); PG8_BAR; PG8_MMA(1, 0, At, B0); PG8_MMA(1, 1, At, B1); PG8_BAR; PG8_SCHED;
;     ...
;         if constexpr (ALIGN_EPI) { if (wr == 0) PG8_BAR; }
	s_add_i32 s62, s33, s75
	v_lshl_add_u64 v[216:217], v[216:217], 0, s[26:27]
	s_mov_b32 m0, s62
	ds_read_b128 v[162:165], v215 offset:49152
	ds_read_b128 v[166:169], v215 offset:50176
	ds_read_b128 v[170:173], v215 offset:51200
	ds_read_b128 v[174:177], v215 offset:52224
	ds_read_b128 v[178:181], v215 offset:53248
	ds_read_b128 v[182:185], v215 offset:54272
	ds_read_b128 v[206:209], v215 offset:55296
	ds_read_b128 v[210:213], v215 offset:56320
	global_load_lds_dwordx4 v[216:217], off
	s_add_i32 m0, s62, 0x2000
	s_add_u32 s60, s60, 0x40080
	v_lshl_add_u64 v[216:217], v[218:219], 0, s[26:27]
	s_addc_u32 s61, s61, 0
	s_add_i32 s62, s74, s75
	global_load_lds_dwordx4 v[216:217], off
	v_lshl_add_u64 v[216:217], s[60:61], 0, v[0:1]
	s_mov_b32 m0, s62
	s_nop 0
	global_load_lds_dwordx4 v[216:217], off
	v_lshl_add_u64 v[216:217], s[60:61], 0, v[196:197]
	s_add_i32 m0, s62, 0x2000
	s_nop 0
	global_load_lds_dwordx4 v[216:217], off
	v_lshl_add_u64 v[216:217], v[220:221], 0, s[26:27]
	s_mov_b32 m0, s38
	s_nop 0
	global_load_lds_dwordx4 v[216:217], off
	v_lshl_add_u64 v[216:217], v[222:223], 0, s[26:27]
	s_mov_b32 m0, s39
	s_nop 0
	global_load_lds_dwordx4 v[216:217], off
	s_waitcnt vmcnt(8)
	s_waitcnt lgkmcnt(0)
	s_barrier
	s_waitcnt lgkmcnt(0)
	v_mfma_f32_16x16x32_bf16 v[62:65], v[130:133], v[162:165], v[62:65]
	v_mfma_f32_16x16x32_bf16 v[58:61], v[138:141], v[162:165], v[58:61]
	v_mfma_f32_16x16x32_bf16 v[46:49], v[130:133], v[170:173], v[46:49]
	v_mfma_f32_16x16x32_bf16 v[42:45], v[138:141], v[170:173], v[42:45]
	v_mfma_f32_16x16x32_bf16 v[30:33], v[130:133], v[178:181], v[30:33]
	v_mfma_f32_16x16x32_bf16 v[26:29], v[138:141], v[178:181], v[26:29]
	v_mfma_f32_16x16x32_bf16 v[14:17], v[130:133], v[206:209], v[14:17]
	v_mfma_f32_16x16x32_bf16 v[10:13], v[138:141], v[206:209], v[10:13]
	v_mfma_f32_16x16x32_bf16 v[62:65], v[134:137], v[166:169], v[62:65]
	v_mfma_f32_16x16x32_bf16 v[58:61], v[142:145], v[166:169], v[58:61]
	v_mfma_f32_16x16x32_bf16 v[46:49], v[134:137], v[174:177], v[46:49]
	v_mfma_f32_16x16x32_bf16 v[42:45], v[142:145], v[174:177], v[42:45]
	v_mfma_f32_16x16x32_bf16 v[30:33], v[134:137], v[182:185], v[30:33]
	v_mfma_f32_16x16x32_bf16 v[26:29], v[142:145], v[182:185], v[26:29]
	v_mfma_f32_16x16x32_bf16 v[14:17], v[134:137], v[210:213], v[14:17]
	v_mfma_f32_16x16x32_bf16 v[10:13], v[142:145], v[210:213], v[10:13]
	v_mfma_f32_16x16x32_bf16 v[54:57], v[146:149], v[162:165], v[54:57]
	v_mfma_f32_16x16x32_bf16 v[50:53], v[154:157], v[162:165], v[50:53]
	v_mfma_f32_16x16x32_bf16 v[38:41], v[146:149], v[170:173], v[38:41]
	v_mfma_f32_16x16x32_bf16 v[34:37], v[154:157], v[170:173], v[34:37]
	v_mfma_f32_16x16x32_bf16 v[22:25], v[146:149], v[178:181], v[22:25]
	v_mfma_f32_16x16x32_bf16 v[18:21], v[154:157], v[178:181], v[18:21]
	v_mfma_f32_16x16x32_bf16 v[6:9], v[146:149], v[206:209], v[6:9]
	v_mfma_f32_16x16x32_bf16 v[2:5], v[154:157], v[206:209], v[2:5]
	v_mfma_f32_16x16x32_bf16 v[54:57], v[150:153], v[166:169], v[54:57]
	v_mfma_f32_16x16x32_bf16 v[50:53], v[158:161], v[166:169], v[50:53]
	v_mfma_f32_16x16x32_bf16 v[38:41], v[150:153], v[174:177], v[38:41]
	v_mfma_f32_16x16x32_bf16 v[34:37], v[158:161], v[174:177], v[34:37]
	v_mfma_f32_16x16x32_bf16 v[22:25], v[150:153], v[182:185], v[22:25]
	v_mfma_f32_16x16x32_bf16 v[18:21], v[158:161], v[182:185], v[18:21]
	v_mfma_f32_16x16x32_bf16 v[6:9], v[150:153], v[210:213], v[6:9]
	v_mfma_f32_16x16x32_bf16 v[2:5], v[158:161], v[210:213], v[2:5]
	s_barrier
	s_add_i32 vcc_hi, vcc_hi, 2
	s_add_u32 s58, s58, 0x100
	s_addc_u32 s59, s59, 0
	s_add_u32 s83, s83, 0x100
	s_addc_u32 vcc_lo, vcc_lo, 0
	s_cmp_gt_u32 vcc_hi, 13
	s_cbranch_scc0 .LBB0_359
	s_and_b64 vcc, exec, s[44:45]
	s_cbranch_vccz .LBB0_362
	s_barrier

;     __device__ __forceinline__ bool next(int i, Unit& u) const { if (i >= n) return false; int o = own; asm volatile("" : "+s"(o)); u.pm = swap ? i : o; u.pn = swap ? o : i; u.idx = i; return true; }
; #define PG8_STAGE(bufoff, gbase, voff) do { _Pragma("unroll") for (int _i = 0; _i < 2; ++_i) \
;         __builtin_amdgcn_global_load_lds((const unsigned*)((const char*)(gbase) + (voff)[_i]), (PG8_LAS unsigned*)(lds + (bufoff) + ldsw + _i * 8192), 16, 0, 0); } while (0)
; #define PG8_LDA(dst, b, h) do { _Pragma("unroll") for (int m = 0; m < 4; ++m) _Pragma("unroll") for (int k = 0; k < 2; ++k) dst[m][k] = *(const PG8_LAS bf16x8*)(lds + PG8_SA(b, h) + aoff + m * 2048 + k * 1024); } while (0)
; #define PG8_LDB(dst, b, h) do { _Pragma("unroll") for (int n = 0; n < 2; ++n) _Pragma("unroll") for (int k = 0; k < 2; ++k) dst[n][k] = *(const PG8_LAS bf16x8*)(lds + PG8_SB(b, h) + boff + n * 2048 + k * 1024); } while (0)
; #define PG8_WAIT_V(n) asm volatile("s_waitcnt vmcnt(" #n ")" ::: "memory")
; template <class Epi, class Sched, bool ALIGN_EPI = false, bool SP2 = false>
; __device__ __forceinline__ void gemm_phase(PG8_LAS unsigned char* lds, const Gemm g, const Sched& S, const Epi& E, int tid_in) {
;     ...
;         const bool has_next = S.next(ui + 1, nxt);
;         const char* nA = has_next ? (const char*)g.A + (size_t)nxt.pm * tstep : cA; const char* nB = has_next ? (const char*)g.Bt + (size_t)nxt.pn * tstep : cB;
;         for (int t = 0; t < nt; t += 2) {
;             const bool last = (t == nt - 2);
;             const char* a1 = cA + (size_t)(t + 1) * kstep;
;             const char* a2 = last ? nA : cA + (size_t)(t + 2) * kstep; const char* b2 = last ? nB : cB + (size_t)(t + 2) * kstep;
;             const char* a3 = a2 + kstep; const char* b3 = b2 + kstep;
;             if (last && has_next) S.a_ready(nxt);
;             if constexpr (SP2) {
;             PG8_LDB(B0, 0, 0); PG8_LDB(B1, 0, 1); PG8_SCHED; PG8_LDA(At, 0, 0); PG8_STAGE(PG8_SA(1, 1), a1 + hstep, voffA);
;             PG8_WAIT_V(8); PG8_WAIT_L(0); PG8_BAR; PG8_MMA(0, 0, At, B0); PG8_MMA(0, 1, At, B1); PG8_BAR; PG8_SCHED;
;             PG8_LDA(At, 0, 1); PG8_STAGE(PG8_SB(0, 0), b2, voffB); PG8_STAGE(PG8_SB(0, 1), b2 + hstep, voffB); PG8_STAGE(PG8_SA(0, 0), a2, voffA);
;             PG8_WAIT_V(8); PG8_WAIT_L(0); PG8_BAR; PG8_MMA(1, 0, At, B0); PG8_MMA(1, 1, At, B1); PG8_BAR; PG8_SCHED;
.LBB0_491:
	s_ashr_i32 s43, s42, 31
	s_lshl_b64 s[48:49], s[42:43], 19
	s_add_u32 s48, s38, s48
	s_addc_u32 s49, s39, s49
	s_and_b64 s[50:51], s[46:47], exec
	s_cselect_b32 s43, s49, s53
	s_cselect_b32 s78, s48, s52
	s_ashr_i32 s45, s44, 31
	s_lshl_b64 s[50:51], s[44:45], 19
	s_add_u32 s50, s36, s50
	s_addc_u32 s51, s37, s51
	s_and_b64 s[56:57], s[46:47], exec
	s_cselect_b32 s45, s51, s55
	s_cselect_b32 s79, s50, s54
	s_add_u32 s52, s52, 0x40080
	s_addc_u32 s53, s53, 0
	s_add_u32 s80, s54, 0x100
	s_addc_u32 s81, s55, 0
	s_mov_b32 s82, -2
	v_add_u32_e32 v156, s84, v146
	v_add_u32_e32 v172, s85, v146
	ds_read_b128 v[140:143], v156
	ds_read_b128 v[148:151], v156 offset:1024
	ds_read_b128 v[152:155], v156 offset:2048
	ds_read_b128 v[156:159], v156 offset:3072
	ds_read_b128 v[160:163], v172
	ds_read_b128 v[164:167], v172 offset:1024
	ds_read_b128 v[168:171], v172 offset:2048
	ds_read_b128 v[172:175], v172 offset:3072
	s_add_u32 s54, s52, 0xfffc0080
	s_addc_u32 s55, s53, -1
	s_cmp_eq_u32 s82, 12
	s_cselect_b32 s57, s43, s55
	s_cselect_b32 s56, s78, s54
	s_cselect_b32 s55, s45, s81
	s_cselect_b32 s54, s79, s80
	v_lshl_add_u64 v[184:185], s[52:53], 0, v[136:137]
	s_add_i32 m0, s59, 0xc000
	ds_read_b128 v[176:179], v147
	ds_read_b128 v[180:183], v147 offset:1024
	ds_read_b128 v[196:199], v147 offset:2048
	ds_read_b128 v[200:203], v147 offset:3072
	ds_read_b128 v[204:207], v147 offset:4096
	ds_read_b128 v[208:211], v147 offset:5120
	ds_read_b128 v[212:215], v147 offset:6144
	ds_read_b128 v[216:219], v147 offset:7168
	global_load_lds_dwordx4 v[184:185], off
	v_lshl_add_u64 v[184:185], s[52:53], 0, v[138:139]
	s_add_i32 m0, s59, 0xe000
	s_nop 0
	global_load_lds_dwordx4 v[184:185], off
	s_waitcnt vmcnt(8)
	s_waitcnt lgkmcnt(0)
	s_barrier
	s_waitcnt lgkmcnt(0)
	v_mfma_f32_16x16x32_bf16 v[126:129], v[140:143], v[176:179], 0
	v_mfma_f32_16x16x32_bf16 v[122:125], v[152:155], v[176:179], 0
	v_mfma_f32_16x16x32_bf16 v[110:113], v[140:143], v[196:199], 0
	v_mfma_f32_16x16x32_bf16 v[106:109], v[152:155], v[196:199], 0
	v_mfma_f32_16x16x32_bf16 v[94:97], v[140:143], v[204:207], 0
	v_mfma_f32_16x16x32_bf16 v[90:93], v[152:155], v[204:207], 0
	v_mfma_f32_16x16x32_bf16 v[78:81], v[140:143], v[212:215], 0
	v_mfma_f32_16x16x32_bf16 v[74:77], v[152:155], v[212:215], 0
	v_mfma_f32_16x16x32_bf16 v[126:129], v[148:151], v[180:183], v[126:129]
	v_mfma_f32_16x16x32_bf16 v[122:125], v[156:159], v[180:183], v[122:125]
	v_mfma_f32_16x16x32_bf16 v[110:113], v[148:151], v[200:203], v[110:113]
	v_mfma_f32_16x16x32_bf16 v[106:109], v[156:159], v[200:203], v[106:109]
	v_mfma_f32_16x16x32_bf16 v[94:97], v[148:151], v[208:211], v[94:97]
	v_mfma_f32_16x16x32_bf16 v[90:93], v[156:159], v[208:211], v[90:93]
	v_mfma_f32_16x16x32_bf16 v[78:81], v[148:151], v[216:219], v[78:81]
	v_mfma_f32_16x16x32_bf16 v[74:77], v[156:159], v[216:219], v[74:77]
	v_mfma_f32_16x16x32_bf16 v[118:121], v[160:163], v[176:179], 0
	v_mfma_f32_16x16x32_bf16 v[114:117], v[168:171], v[176:179], 0
	v_mfma_f32_16x16x32_bf16 v[102:105], v[160:163], v[196:199], 0
	v_mfma_f32_16x16x32_bf16 v[98:101], v[168:171], v[196:199], 0
	v_mfma_f32_16x16x32_bf16 v[86:89], v[160:163], v[204:207], 0
	v_mfma_f32_16x16x32_bf16 v[82:85], v[168:171], v[204:207], 0
	v_mfma_f32_16x16x32_bf16 v[70:73], v[160:163], v[212:215], 0
	v_mfma_f32_16x16x32_bf16 v[66:69], v[168:171], v[212:215], 0
	v_mfma_f32_16x16x32_bf16 v[118:121], v[164:167], v[180:183], v[118:121]
	v_mfma_f32_16x16x32_bf16 v[114:117], v[172:175], v[180:183], v[114:117]
	v_mfma_f32_16x16x32_bf16 v[102:105], v[164:167], v[200:203], v[102:105]
	v_mfma_f32_16x16x32_bf16 v[98:101], v[172:175], v[200:203], v[98:101]
	v_mfma_f32_16x16x32_bf16 v[86:89], v[164:167], v[208:211], v[86:89]
	v_mfma_f32_16x16x32_bf16 v[82:85], v[172:175], v[208:211], v[82:85]
	v_mfma_f32_16x16x32_bf16 v[70:73], v[164:167], v[216:219], v[70:73]
	v_mfma_f32_16x16x32_bf16 v[66:69], v[172:175], v[216:219], v[66:69]
	s_barrier
	s_add_i32 s83, s84, s58
	v_lshl_add_u64 v[184:185], s[54:55], 0, v[0:1]
	s_mov_b32 m0, s83
	ds_read_b128 v[176:179], v147 offset:16384
	ds_read_b128 v[180:183], v147 offset:17408
	ds_read_b128 v[196:199], v147 offset:18432
	ds_read_b128 v[200:203], v147 offset:19456
	ds_read_b128 v[204:207], v147 offset:20480
	ds_read_b128 v[208:211], v147 offset:21504
	ds_read_b128 v[212:215], v147 offset:22528
	ds_read_b128 v[216:219], v147 offset:23552
	global_load_lds_dwordx4 v[184:185], off
	s_add_i32 m0, s83, 0x2000
	s_add_u32 s86, s54, 0x40000
	v_lshl_add_u64 v[220:221], s[54:55], 0, v[130:131]
	s_addc_u32 s87, s55, 0
	s_add_i32 s83, s85, s58
	global_load_lds_dwordx4 v[220:221], off
	v_lshl_add_u64 v[222:223], s[86:87], 0, v[0:1]
	s_mov_b32 m0, s83
	v_lshl_add_u64 v[224:225], s[56:57], 0, v[132:133]
	global_load_lds_dwordx4 v[222:223], off
	v_lshl_add_u64 v[222:223], s[86:87], 0, v[130:131]
	s_add_i32 m0, s83, 0x2000
	s_nop 0
	global_load_lds_dwordx4 v[222:223], off
	v_lshl_add_u64 v[222:223], s[56:57], 0, v[134:135]
	s_mov_b32 m0, s59
	s_nop 0
	global_load_lds_dwordx4 v[222:223], off
	s_mov_b32 m0, s60
	s_nop 0
	global_load_lds_dwordx4 v[224:225], off
	s_waitcnt vmcnt(8)
	s_waitcnt lgkmcnt(0)
	s_barrier
; #define PG8_STAGE(bufoff, gbase, voff) do { _Pragma("unroll") for (int _i = 0; _i < 2; ++_i) \
;         __builtin_amdgcn_global_load_lds((const unsigned*)((const char*)(gbase) + (voff)[_i]), (PG8_LAS unsigned*)(lds + (bufoff) + ldsw + _i * 8192), 16, 0, 0); } while (0)
; #define PG8_LDA(dst, b, h) do { _Pragma("unroll") for (int m = 0; m < 4; ++m) _Pragma("unroll") for (int k = 0; k < 2; ++k) dst[m][k] = *(const PG8_LAS bf16x8*)(lds + PG8_SA(b, h) + aoff + m * 2048 + k * 1024); } while (0)
; #define PG8_LDB(dst, b, h) do { _Pragma("unroll") for (int n = 0; n < 2; ++n) _Pragma("unroll") for (int k = 0; k < 2; ++k) dst[n][k] = *(const PG8_LAS bf16x8*)(lds + PG8_SB(b, h) + boff + n * 2048 + k * 1024); } while (0)
; #define PG8_MMA(ai, bj, At, Bt) do { __builtin_amdgcn_s_setprio(1); _Pragma("unroll") for (int k = 0; k < 2; ++k) _Pragma("unroll") for (int m = 0; m < 4; ++m) _Pragma("unroll") for (int n = 0; n < 2; ++n) \
;         acc[ai][bj][m][n] = __builtin_amdgcn_mfma_f32_16x16x32_bf16(Bt[n][k], At[m][k], acc[ai][bj][m][n], 0, 0, 0); __builtin_amdgcn_s_setprio(0); } while (0)
; #define PG8_WAIT_V(n) asm volatile("s_waitcnt vmcnt(" #n ")" ::: "memory")
; #define PG8_WAIT_L(n) asm volatile("s_waitcnt lgkmcnt(" #n ")" ::: "memory")
; #define PG8_BAR __builtin_amdgcn_s_barrier()
; #define PG8_SCHED __builtin_amdgcn_sched_barrier(0)
; template <class Epi, class Sched, bool ALIGN_EPI = false, bool SP2 = false>
; __device__ __forceinline__ void gemm_phase(PG8_LAS unsigned char* lds, const Gemm g, const Sched& S, const Epi& E, int tid_in) {
;     ...
;             PG8_WAIT_V(8); PG8_WAIT_L(0); PG8_BAR; PG8_MMA(1, 0, At, B0); PG8_MMA(1, 1, At, B1); PG8_BAR; PG8_SCHED;
;             PG8_LDB(B0, 1, 0); PG8_LDB(B1, 1, 1); PG8_SCHED; PG8_LDA(At, 1, 0); PG8_STAGE(PG8_SA(0, 1), a2 + hstep, voffA);
;             PG8_WAIT_V(8); PG8_WAIT_L(0); PG8_BAR; PG8_MMA(0, 0, At, B0); PG8_MMA(0, 1, At, B1); PG8_BAR; PG8_SCHED;
	s_waitcnt lgkmcnt(0)
	v_mfma_f32_16x16x32_bf16 v[62:65], v[140:143], v[176:179], 0
	v_mfma_f32_16x16x32_bf16 v[58:61], v[152:155], v[176:179], 0
	v_mfma_f32_16x16x32_bf16 v[46:49], v[140:143], v[196:199], 0
	v_mfma_f32_16x16x32_bf16 v[42:45], v[152:155], v[196:199], 0
	v_mfma_f32_16x16x32_bf16 v[30:33], v[140:143], v[204:207], 0
	v_mfma_f32_16x16x32_bf16 v[26:29], v[152:155], v[204:207], 0
	v_mfma_f32_16x16x32_bf16 v[14:17], v[140:143], v[212:215], 0
	v_mfma_f32_16x16x32_bf16 v[10:13], v[152:155], v[212:215], 0
	v_mfma_f32_16x16x32_bf16 v[62:65], v[148:151], v[180:183], v[62:65]
	v_mfma_f32_16x16x32_bf16 v[58:61], v[156:159], v[180:183], v[58:61]
	v_mfma_f32_16x16x32_bf16 v[46:49], v[148:151], v[200:203], v[46:49]
	v_mfma_f32_16x16x32_bf16 v[42:45], v[156:159], v[200:203], v[42:45]
	v_mfma_f32_16x16x32_bf16 v[30:33], v[148:151], v[208:211], v[30:33]
	v_mfma_f32_16x16x32_bf16 v[26:29], v[156:159], v[208:211], v[26:29]
	v_mfma_f32_16x16x32_bf16 v[14:17], v[148:151], v[216:219], v[14:17]
	v_mfma_f32_16x16x32_bf16 v[10:13], v[156:159], v[216:219], v[10:13]
	v_mfma_f32_16x16x32_bf16 v[54:57], v[160:163], v[176:179], 0
	v_mfma_f32_16x16x32_bf16 v[50:53], v[168:171], v[176:179], 0
	v_mfma_f32_16x16x32_bf16 v[38:41], v[160:163], v[196:199], 0
	v_mfma_f32_16x16x32_bf16 v[34:37], v[168:171], v[196:199], 0
	v_mfma_f32_16x16x32_bf16 v[22:25], v[160:163], v[204:207], 0
	v_mfma_f32_16x16x32_bf16 v[18:21], v[168:171], v[204:207], 0
	v_mfma_f32_16x16x32_bf16 v[6:9], v[160:163], v[212:215], 0
	v_mfma_f32_16x16x32_bf16 v[2:5], v[168:171], v[212:215], 0
	v_mfma_f32_16x16x32_bf16 v[54:57], v[164:167], v[180:183], v[54:57]
	v_mfma_f32_16x16x32_bf16 v[50:53], v[172:175], v[180:183], v[50:53]
	v_mfma_f32_16x16x32_bf16 v[38:41], v[164:167], v[200:203], v[38:41]
	v_mfma_f32_16x16x32_bf16 v[34:37], v[172:175], v[200:203], v[34:37]
	v_mfma_f32_16x16x32_bf16 v[22:25], v[164:167], v[208:211], v[22:25]
	v_mfma_f32_16x16x32_bf16 v[18:21], v[172:175], v[208:211], v[18:21]
	v_mfma_f32_16x16x32_bf16 v[6:9], v[164:167], v[216:219], v[6:9]
	v_mfma_f32_16x16x32_bf16 v[2:5], v[172:175], v[216:219], v[2:5]
	s_barrier
	v_add_u32_e32 v156, s33, v146
	v_add_u32_e32 v172, s74, v146
	ds_read_b128 v[140:143], v156
	ds_read_b128 v[148:151], v156 offset:1024
	ds_read_b128 v[152:155], v156 offset:2048
	ds_read_b128 v[156:159], v156 offset:3072
	ds_read_b128 v[160:163], v172
	ds_read_b128 v[164:167], v172 offset:1024
	ds_read_b128 v[168:171], v172 offset:2048
	ds_read_b128 v[172:175], v172 offset:3072
	s_add_u32 s56, s56, 0x40000
	s_addc_u32 s57, s57, 0
	s_mov_b32 m0, s61
	v_lshl_add_u64 v[226:227], s[56:57], 0, v[134:135]
	ds_read_b128 v[176:179], v147 offset:32768
	ds_read_b128 v[180:183], v147 offset:33792
	ds_read_b128 v[196:199], v147 offset:34816
	ds_read_b128 v[200:203], v147 offset:35840
	ds_read_b128 v[204:207], v147 offset:36864
	ds_read_b128 v[208:211], v147 offset:37888
	ds_read_b128 v[212:215], v147 offset:38912
	ds_read_b128 v[216:219], v147 offset:39936
	global_load_lds_dwordx4 v[226:227], off
	v_lshl_add_u64 v[226:227], s[56:57], 0, v[132:133]
	s_mov_b32 m0, s62
	s_nop 0
	global_load_lds_dwordx4 v[226:227], off
	s_waitcnt vmcnt(8)
	s_waitcnt lgkmcnt(0)
	s_barrier
	s_waitcnt lgkmcnt(0)
	v_mfma_f32_16x16x32_bf16 v[126:129], v[140:143], v[176:179], v[126:129]
	v_mfma_f32_16x16x32_bf16 v[122:125], v[152:155], v[176:179], v[122:125]
	v_mfma_f32_16x16x32_bf16 v[110:113], v[140:143], v[196:199], v[110:113]
	v_mfma_f32_16x16x32_bf16 v[106:109], v[152:155], v[196:199], v[106:109]
	v_mfma_f32_16x16x32_bf16 v[94:97], v[140:143], v[204:207], v[94:97]
	v_mfma_f32_16x16x32_bf16 v[90:93], v[152:155], v[204:207], v[90:93]
	v_mfma_f32_16x16x32_bf16 v[78:81], v[140:143], v[212:215], v[78:81]
	v_mfma_f32_16x16x32_bf16 v[74:77], v[152:155], v[212:215], v[74:77]
	v_mfma_f32_16x16x32_bf16 v[126:129], v[148:151], v[180:183], v[126:129]
	v_mfma_f32_16x16x32_bf16 v[122:125], v[156:159], v[180:183], v[122:125]
	v_mfma_f32_16x16x32_bf16 v[110:113], v[148:151], v[200:203], v[110:113]
	v_mfma_f32_16x16x32_bf16 v[106:109], v[156:159], v[200:203], v[106:109]
	v_mfma_f32_16x16x32_bf16 v[94:97], v[148:151], v[208:211], v[94:97]
	v_mfma_f32_16x16x32_bf16 v[90:93], v[156:159], v[208:211], v[90:93]
	v_mfma_f32_16x16x32_bf16 v[78:81], v[148:151], v[216:219], v[78:81]
	v_mfma_f32_16x16x32_bf16 v[74:77], v[156:159], v[216:219], v[74:77]
	v_mfma_f32_16x16x32_bf16 v[118:121], v[160:163], v[176:179], v[118:121]
	v_mfma_f32_16x16x32_bf16 v[114:117], v[168:171], v[176:179], v[114:117]
	v_mfma_f32_16x16x32_bf16 v[102:105], v[160:163], v[196:199], v[102:105]
	v_mfma_f32_16x16x32_bf16 v[98:101], v[168:171], v[196:199], v[98:101]
	v_mfma_f32_16x16x32_bf16 v[86:89], v[160:163], v[204:207], v[86:89]
	v_mfma_f32_16x16x32_bf16 v[82:85], v[168:171], v[204:207], v[82:85]
	v_mfma_f32_16x16x32_bf16 v[70:73], v[160:163], v[212:215], v[70:73]
	v_mfma_f32_16x16x32_bf16 v[66:69], v[168:171], v[212:215], v[66:69]
	v_mfma_f32_16x16x32_bf16 v[118:121], v[164:167], v[180:183], v[118:121]
	v_mfma_f32_16x16x32_bf16 v[114:117], v[172:175], v[180:183], v[114:117]
	v_mfma_f32_16x16x32_bf16 v[102:105], v[164:167], v[200:203], v[102:105]
	v_mfma_f32_16x16x32_bf16 v[98:101], v[172:175], v[200:203], v[98:101]
	v_mfma_f32_16x16x32_bf16 v[86:89], v[164:167], v[208:211], v[86:89]
	v_mfma_f32_16x16x32_bf16 v[82:85], v[172:175], v[208:211], v[82:85]
	v_mfma_f32_16x16x32_bf16 v[70:73], v[164:167], v[216:219], v[70:73]
	v_mfma_f32_16x16x32_bf16 v[66:69], v[172:175], v[216:219], v[66:69]
	s_barrier
; #define PG8_STAGE(bufoff, gbase, voff) do { _Pragma("unroll") for (int _i = 0; _i < 2; ++_i) \
;         __builtin_amdgcn_global_load_lds((const unsigned*)((const char*)(gbase) + (voff)[_i]), (PG8_LAS unsigned*)(lds + (bufoff) + ldsw + _i * 8192), 16, 0, 0); } while (0)
; #define PG8_LDA(dst, b, h) do { _Pragma("unroll") for (int m = 0; m < 4; ++m) _Pragma("unroll") for (int k = 0; k < 2; ++k) dst[m][k] = *(const PG8_LAS bf16x8*)(lds + PG8_SA(b, h) + aoff + m * 2048 + k * 1024); } while (0)
; #define PG8_LDB(dst, b, h) do { _Pragma("unroll") for (int n = 0; n < 2; ++n) _Pragma("unroll") for (int k = 0; k < 2; ++k) dst[n][k] = *(const PG8_LAS bf16x8*)(lds + PG8_SB(b, h) + boff + n * 2048 + k * 1024); } while (0)
; template <class Epi, class Sched, bool ALIGN_EPI = false, bool SP2 = false>
; __device__ __forceinline__ void gemm_phase(PG8_LAS unsigned char* lds, const Gemm g, const Sched& S, const Epi& E, int tid_in) {
;     ...
;             const bool last = (t == nt - 2);
;             const char* a1 = cA + (size_t)(t + 1) * kstep;
;             const char* a2 = last ? nA : cA + (size_t)(t + 2) * kstep; const char* b2 = last ? nB : cB + (size_t)(t + 2) * kstep;
;             const char* a3 = a2 + kstep; const char* b3 = b2 + kstep;
;             if (last && has_next) S.a_ready(nxt);
;             if constexpr (SP2) {
;             PG8_LDB(B0, 0, 0); PG8_LDB(B1, 0, 1); PG8_SCHED; PG8_LDA(At, 0, 0); PG8_STAGE(PG8_SA(1, 1), a1 + hstep, voffA);
;             PG8_WAIT_V(8); PG8_WAIT_L(0); PG8_BAR; PG8_MMA(0, 0, At, B0); PG8_MMA(0, 1, At, B1); PG8_BAR; PG8_SCHED;
;             PG8_LDA(At, 0, 1); PG8_STAGE(PG8_SB(0, 0), b2, voffB); PG8_STAGE(PG8_SB(0, 1), b2 + hstep, voffB); PG8_STAGE(PG8_SA(0, 0), a2, voffA);
;             PG8_WAIT_V(8); PG8_WAIT_L(0); PG8_BAR; PG8_MMA(1, 0, At, B0); PG8_MMA(1, 1, At, B1); PG8_BAR; PG8_SCHED;
;             PG8_LDB(B0, 1, 0); PG8_LDB(B1, 1, 1); PG8_SCHED; PG8_LDA(At, 1, 0); PG8_STAGE(PG8_SA(0, 1), a2 + hstep, voffA);
;             PG8_WAIT_V(8); PG8_WAIT_L(0); PG8_BAR; PG8_MMA(0, 0, At, B0); PG8_MMA(0, 1, At, B1); PG8_BAR; PG8_SCHED;
;             PG8_LDA(At, 1, 1); PG8_STAGE(PG8_SB(1, 0), b3, voffB); PG8_STAGE(PG8_SB(1, 1), b3 + hstep, voffB); PG8_STAGE(PG8_SA(1, 0), a3, voffA);
;             PG8_WAIT_V(8); PG8_WAIT_L(0); PG8_BAR; PG8_MMA(1, 0, At, B0); PG8_MMA(1, 1, At, B1); PG8_BAR; PG8_SCHED;
	s_add_i32 s56, s33, s58
	v_lshl_add_u64 v[184:185], v[184:185], 0, s[26:27]
	s_mov_b32 m0, s56
	ds_read_b128 v[176:179], v147 offset:49152
	ds_read_b128 v[180:183], v147 offset:50176
	ds_read_b128 v[196:199], v147 offset:51200
	ds_read_b128 v[200:203], v147 offset:52224
	ds_read_b128 v[204:207], v147 offset:53248
	ds_read_b128 v[208:211], v147 offset:54272
	ds_read_b128 v[212:215], v147 offset:55296
	ds_read_b128 v[216:219], v147 offset:56320
	global_load_lds_dwordx4 v[184:185], off
	s_add_i32 m0, s56, 0x2000
	s_add_u32 s54, s54, 0x40080
	v_lshl_add_u64 v[184:185], v[220:221], 0, s[26:27]
	s_addc_u32 s55, s55, 0
	s_add_i32 s56, s74, s58
	global_load_lds_dwordx4 v[184:185], off
	v_lshl_add_u64 v[184:185], s[54:55], 0, v[0:1]
	s_mov_b32 m0, s56
	s_nop 0
	global_load_lds_dwordx4 v[184:185], off
	v_lshl_add_u64 v[184:185], s[54:55], 0, v[130:131]
	s_add_i32 m0, s56, 0x2000
	s_nop 0
	global_load_lds_dwordx4 v[184:185], off
	v_lshl_add_u64 v[184:185], v[222:223], 0, s[26:27]
	s_mov_b32 m0, s65
	s_nop 0
	global_load_lds_dwordx4 v[184:185], off
	v_lshl_add_u64 v[184:185], v[224:225], 0, s[26:27]
	s_mov_b32 m0, s68
	s_nop 0
	global_load_lds_dwordx4 v[184:185], off
	s_waitcnt vmcnt(8)
	s_waitcnt lgkmcnt(0)
	s_barrier
	s_waitcnt lgkmcnt(0)
	v_mfma_f32_16x16x32_bf16 v[62:65], v[140:143], v[176:179], v[62:65]
	v_mfma_f32_16x16x32_bf16 v[58:61], v[152:155], v[176:179], v[58:61]
	v_mfma_f32_16x16x32_bf16 v[46:49], v[140:143], v[196:199], v[46:49]
	v_mfma_f32_16x16x32_bf16 v[42:45], v[152:155], v[196:199], v[42:45]
	v_mfma_f32_16x16x32_bf16 v[30:33], v[140:143], v[204:207], v[30:33]
	v_mfma_f32_16x16x32_bf16 v[26:29], v[152:155], v[204:207], v[26:29]
	v_mfma_f32_16x16x32_bf16 v[14:17], v[140:143], v[212:215], v[14:17]
	v_mfma_f32_16x16x32_bf16 v[10:13], v[152:155], v[212:215], v[10:13]
	v_mfma_f32_16x16x32_bf16 v[62:65], v[148:151], v[180:183], v[62:65]
	v_mfma_f32_16x16x32_bf16 v[58:61], v[156:159], v[180:183], v[58:61]
	v_mfma_f32_16x16x32_bf16 v[46:49], v[148:151], v[200:203], v[46:49]
	v_mfma_f32_16x16x32_bf16 v[42:45], v[156:159], v[200:203], v[42:45]
	v_mfma_f32_16x16x32_bf16 v[30:33], v[148:151], v[208:211], v[30:33]
	v_mfma_f32_16x16x32_bf16 v[26:29], v[156:159], v[208:211], v[26:29]
	v_mfma_f32_16x16x32_bf16 v[14:17], v[148:151], v[216:219], v[14:17]
	v_mfma_f32_16x16x32_bf16 v[10:13], v[156:159], v[216:219], v[10:13]
	v_mfma_f32_16x16x32_bf16 v[54:57], v[160:163], v[176:179], v[54:57]
	v_mfma_f32_16x16x32_bf16 v[50:53], v[168:171], v[176:179], v[50:53]
	v_mfma_f32_16x16x32_bf16 v[38:41], v[160:163], v[196:199], v[38:41]
	v_mfma_f32_16x16x32_bf16 v[34:37], v[168:171], v[196:199], v[34:37]
	v_mfma_f32_16x16x32_bf16 v[22:25], v[160:163], v[204:207], v[22:25]
	v_mfma_f32_16x16x32_bf16 v[18:21], v[168:171], v[204:207], v[18:21]
	v_mfma_f32_16x16x32_bf16 v[6:9], v[160:163], v[212:215], v[6:9]
	v_mfma_f32_16x16x32_bf16 v[2:5], v[168:171], v[212:215], v[2:5]
	v_mfma_f32_16x16x32_bf16 v[54:57], v[164:167], v[180:183], v[54:57]
	v_mfma_f32_16x16x32_bf16 v[50:53], v[172:175], v[180:183], v[50:53]
	v_mfma_f32_16x16x32_bf16 v[38:41], v[164:167], v[200:203], v[38:41]
	v_mfma_f32_16x16x32_bf16 v[34:37], v[172:175], v[200:203], v[34:37]
	v_mfma_f32_16x16x32_bf16 v[22:25], v[164:167], v[208:211], v[22:25]
	v_mfma_f32_16x16x32_bf16 v[18:21], v[172:175], v[208:211], v[18:21]
	v_mfma_f32_16x16x32_bf16 v[6:9], v[164:167], v[216:219], v[6:9]
	v_mfma_f32_16x16x32_bf16 v[2:5], v[172:175], v[216:219], v[2:5]
	s_barrier
	s_add_i32 s82, s82, 2
	s_add_u32 s52, s52, 0x100
	s_addc_u32 s53, s53, 0
	s_add_u32 s80, s80, 0x100
	s_addc_u32 s81, s81, 0
	s_cmp_gt_u32 s82, 13
.LBB0_492:
	v_add_u32_e32 v156, s84, v146
	v_add_u32_e32 v172, s85, v146
	ds_read_b128 v[140:143], v156
	ds_read_b128 v[148:151], v156 offset:1024
	ds_read_b128 v[152:155], v156 offset:2048
	ds_read_b128 v[156:159], v156 offset:3072
	ds_read_b128 v[160:163], v172
	ds_read_b128 v[164:167], v172 offset:1024
	ds_read_b128 v[168:171], v172 offset:2048
	ds_read_b128 v[172:175], v172 offset:3072
	s_add_u32 s54, s52, 0xfffc0080
	s_addc_u32 s55, s53, -1
	s_cmp_eq_u32 s82, 12
	s_cselect_b32 s57, s43, s55
	s_cselect_b32 s56, s78, s54
	s_cselect_b32 s55, s45, s81
	s_cselect_b32 s54, s79, s80
	v_lshl_add_u64 v[184:185], s[52:53], 0, v[136:137]
	s_add_i32 m0, s59, 0xc000
	ds_read_b128 v[176:179], v147
	ds_read_b128 v[180:183], v147 offset:1024
	ds_read_b128 v[196:199], v147 offset:2048
	ds_read_b128 v[200:203], v147 offset:3072
	ds_read_b128 v[204:207], v147 offset:4096
	ds_read_b128 v[208:211], v147 offset:5120
	ds_read_b128 v[212:215], v147 offset:6144
	ds_read_b128 v[216:219], v147 offset:7168
	global_load_lds_dwordx4 v[184:185], off
	v_lshl_add_u64 v[184:185], s[52:53], 0, v[138:139]
	s_add_i32 m0, s59, 0xe000
	s_nop 0
	global_load_lds_dwordx4 v[184:185], off
	s_waitcnt vmcnt(8)
	s_waitcnt lgkmcnt(0)
	s_barrier
; #define PG8_STAGE(bufoff, gbase, voff) do { _Pragma("unroll") for (int _i = 0; _i < 2; ++_i) \
;         __builtin_amdgcn_global_load_lds((const unsigned*)((const char*)(gbase) + (voff)[_i]), (PG8_LAS unsigned*)(lds + (bufoff) + ldsw + _i * 8192), 16, 0, 0); } while (0)
; #define PG8_LDA(dst, b, h) do { _Pragma("unroll") for (int m = 0; m < 4; ++m) _Pragma("unroll") for (int k = 0; k < 2; ++k) dst[m][k] = *(const PG8_LAS bf16x8*)(lds + PG8_SA(b, h) + aoff + m * 2048 + k * 1024); } while (0)
; #define PG8_MMA(ai, bj, At, Bt) do { __builtin_amdgcn_s_setprio(1); _Pragma("unroll") for (int k = 0; k < 2; ++k) _Pragma("unroll") for (int m = 0; m < 4; ++m) _Pragma("unroll") for (int n = 0; n < 2; ++n) \
;         acc[ai][bj][m][n] = __builtin_amdgcn_mfma_f32_16x16x32_bf16(Bt[n][k], At[m][k], acc[ai][bj][m][n], 0, 0, 0); __builtin_amdgcn_s_setprio(0); } while (0)
; #define PG8_WAIT_V(n) asm volatile("s_waitcnt vmcnt(" #n ")" ::: "memory")
; #define PG8_WAIT_L(n) asm volatile("s_waitcnt lgkmcnt(" #n ")" ::: "memory")
; #define PG8_BAR __builtin_amdgcn_s_barrier()
; #define PG8_SCHED __builtin_amdgcn_sched_barrier(0)
; template <class Epi, class Sched, bool ALIGN_EPI = false, bool SP2 = false>
; __device__ __forceinline__ void gemm_phase(PG8_LAS unsigned char* lds, const Gemm g, const Sched& S, const Epi& E, int tid_in) {
;     ...
;             PG8_WAIT_V(8); PG8_WAIT_L(0); PG8_BAR; PG8_MMA(0, 0, At, B0); PG8_MMA(0, 1, At, B1); PG8_BAR; PG8_SCHED;
;             PG8_LDA(At, 0, 1); PG8_STAGE(PG8_SB(0, 0), b2, voffB); PG8_STAGE(PG8_SB(0, 1), b2 + hstep, voffB); PG8_STAGE(PG8_SA(0, 0), a2, voffA);
;             PG8_WAIT_V(8); PG8_WAIT_L(0); PG8_BAR; PG8_MMA(1, 0, At, B0); PG8_MMA(1, 1, At, B1); PG8_BAR; PG8_SCHED;
	s_waitcnt lgkmcnt(0)
	v_mfma_f32_16x16x32_bf16 v[126:129], v[140:143], v[176:179], v[126:129]
	v_mfma_f32_16x16x32_bf16 v[122:125], v[152:155], v[176:179], v[122:125]
	v_mfma_f32_16x16x32_bf16 v[110:113], v[140:143], v[196:199], v[110:113]
	v_mfma_f32_16x16x32_bf16 v[106:109], v[152:155], v[196:199], v[106:109]
	v_mfma_f32_16x16x32_bf16 v[94:97], v[140:143], v[204:207], v[94:97]
	v_mfma_f32_16x16x32_bf16 v[90:93], v[152:155], v[204:207], v[90:93]
	v_mfma_f32_16x16x32_bf16 v[78:81], v[140:143], v[212:215], v[78:81]
	v_mfma_f32_16x16x32_bf16 v[74:77], v[152:155], v[212:215], v[74:77]
	v_mfma_f32_16x16x32_bf16 v[126:129], v[148:151], v[180:183], v[126:129]
	v_mfma_f32_16x16x32_bf16 v[122:125], v[156:159], v[180:183], v[122:125]
	v_mfma_f32_16x16x32_bf16 v[110:113], v[148:151], v[200:203], v[110:113]
	v_mfma_f32_16x16x32_bf16 v[106:109], v[156:159], v[200:203], v[106:109]
	v_mfma_f32_16x16x32_bf16 v[94:97], v[148:151], v[208:211], v[94:97]
	v_mfma_f32_16x16x32_bf16 v[90:93], v[156:159], v[208:211], v[90:93]
	v_mfma_f32_16x16x32_bf16 v[78:81], v[148:151], v[216:219], v[78:81]
	v_mfma_f32_16x16x32_bf16 v[74:77], v[156:159], v[216:219], v[74:77]
	v_mfma_f32_16x16x32_bf16 v[118:121], v[160:163], v[176:179], v[118:121]
	v_mfma_f32_16x16x32_bf16 v[114:117], v[168:171], v[176:179], v[114:117]
	v_mfma_f32_16x16x32_bf16 v[102:105], v[160:163], v[196:199], v[102:105]
	v_mfma_f32_16x16x32_bf16 v[98:101], v[168:171], v[196:199], v[98:101]
	v_mfma_f32_16x16x32_bf16 v[86:89], v[160:163], v[204:207], v[86:89]
	v_mfma_f32_16x16x32_bf16 v[82:85], v[168:171], v[204:207], v[82:85]
	v_mfma_f32_16x16x32_bf16 v[70:73], v[160:163], v[212:215], v[70:73]
	v_mfma_f32_16x16x32_bf16 v[66:69], v[168:171], v[212:215], v[66:69]
	v_mfma_f32_16x16x32_bf16 v[118:121], v[164:167], v[180:183], v[118:121]
	v_mfma_f32_16x16x32_bf16 v[114:117], v[172:175], v[180:183], v[114:117]
	v_mfma_f32_16x16x32_bf16 v[102:105], v[164:167], v[200:203], v[102:105]
	v_mfma_f32_16x16x32_bf16 v[98:101], v[172:175], v[200:203], v[98:101]
	v_mfma_f32_16x16x32_bf16 v[86:89], v[164:167], v[208:211], v[86:89]
	v_mfma_f32_16x16x32_bf16 v[82:85], v[172:175], v[208:211], v[82:85]
	v_mfma_f32_16x16x32_bf16 v[70:73], v[164:167], v[216:219], v[70:73]
	v_mfma_f32_16x16x32_bf16 v[66:69], v[172:175], v[216:219], v[66:69]
	s_barrier
	s_add_i32 s83, s84, s58
	v_lshl_add_u64 v[184:185], s[54:55], 0, v[0:1]
	s_mov_b32 m0, s83
	ds_read_b128 v[176:179], v147 offset:16384
	ds_read_b128 v[180:183], v147 offset:17408
	ds_read_b128 v[196:199], v147 offset:18432
	ds_read_b128 v[200:203], v147 offset:19456
	ds_read_b128 v[204:207], v147 offset:20480
	ds_read_b128 v[208:211], v147 offset:21504
	ds_read_b128 v[212:215], v147 offset:22528
	ds_read_b128 v[216:219], v147 offset:23552
	global_load_lds_dwordx4 v[184:185], off
	s_add_i32 m0, s83, 0x2000
	s_add_u32 s86, s54, 0x40000
	v_lshl_add_u64 v[220:221], s[54:55], 0, v[130:131]
	s_addc_u32 s87, s55, 0
	s_add_i32 s83, s85, s58
	global_load_lds_dwordx4 v[220:221], off
	v_lshl_add_u64 v[222:223], s[86:87], 0, v[0:1]
	s_mov_b32 m0, s83
	v_lshl_add_u64 v[224:225], s[56:57], 0, v[132:133]
	global_load_lds_dwordx4 v[222:223], off
	v_lshl_add_u64 v[222:223], s[86:87], 0, v[130:131]
	s_add_i32 m0, s83, 0x2000
	s_nop 0
	global_load_lds_dwordx4 v[222:223], off
	v_lshl_add_u64 v[222:223], s[56:57], 0, v[134:135]
	s_mov_b32 m0, s59
	s_nop 0
	global_load_lds_dwordx4 v[222:223], off
	s_mov_b32 m0, s60
	s_nop 0
	global_load_lds_dwordx4 v[224:225], off
	s_waitcnt vmcnt(8)
	s_waitcnt lgkmcnt(0)
	s_barrier
	s_waitcnt lgkmcnt(0)
	v_mfma_f32_16x16x32_bf16 v[62:65], v[140:143], v[176:179], v[62:65]
	v_mfma_f32_16x16x32_bf16 v[58:61], v[152:155], v[176:179], v[58:61]
	v_mfma_f32_16x16x32_bf16 v[46:49], v[140:143], v[196:199], v[46:49]
	v_mfma_f32_16x16x32_bf16 v[42:45], v[152:155], v[196:199], v[42:45]
	v_mfma_f32_16x16x32_bf16 v[30:33], v[140:143], v[204:207], v[30:33]
	v_mfma_f32_16x16x32_bf16 v[26:29], v[152:155], v[204:207], v[26:29]
	v_mfma_f32_16x16x32_bf16 v[14:17], v[140:143], v[212:215], v[14:17]
	v_mfma_f32_16x16x32_bf16 v[10:13], v[152:155], v[212:215], v[10:13]
	v_mfma_f32_16x16x32_bf16 v[62:65], v[148:151], v[180:183], v[62:65]
	v_mfma_f32_16x16x32_bf16 v[58:61], v[156:159], v[180:183], v[58:61]
	v_mfma_f32_16x16x32_bf16 v[46:49], v[148:151], v[200:203], v[46:49]
	v_mfma_f32_16x16x32_bf16 v[42:45], v[156:159], v[200:203], v[42:45]
	v_mfma_f32_16x16x32_bf16 v[30:33], v[148:151], v[208:211], v[30:33]
	v_mfma_f32_16x16x32_bf16 v[26:29], v[156:159], v[208:211], v[26:29]
	v_mfma_f32_16x16x32_bf16 v[14:17], v[148:151], v[216:219], v[14:17]
	v_mfma_f32_16x16x32_bf16 v[10:13], v[156:159], v[216:219], v[10:13]
	v_mfma_f32_16x16x32_bf16 v[54:57], v[160:163], v[176:179], v[54:57]
	v_mfma_f32_16x16x32_bf16 v[50:53], v[168:171], v[176:179], v[50:53]
	v_mfma_f32_16x16x32_bf16 v[38:41], v[160:163], v[196:199], v[38:41]
	v_mfma_f32_16x16x32_bf16 v[34:37], v[168:171], v[196:199], v[34:37]
	v_mfma_f32_16x16x32_bf16 v[22:25], v[160:163], v[204:207], v[22:25]
	v_mfma_f32_16x16x32_bf16 v[18:21], v[168:171], v[204:207], v[18:21]
	v_mfma_f32_16x16x32_bf16 v[6:9], v[160:163], v[212:215], v[6:9]
	v_mfma_f32_16x16x32_bf16 v[2:5], v[168:171], v[212:215], v[2:5]
	v_mfma_f32_16x16x32_bf16 v[54:57], v[164:167], v[180:183], v[54:57]
	v_mfma_f32_16x16x32_bf16 v[50:53], v[172:175], v[180:183], v[50:53]
	v_mfma_f32_16x16x32_bf16 v[38:41], v[164:167], v[200:203], v[38:41]
	v_mfma_f32_16x16x32_bf16 v[34:37], v[172:175], v[200:203], v[34:37]
	v_mfma_f32_16x16x32_bf16 v[22:25], v[164:167], v[208:211], v[22:25]
	v_mfma_f32_16x16x32_bf16 v[18:21], v[172:175], v[208:211], v[18:21]
	v_mfma_f32_16x16x32_bf16 v[6:9], v[164:167], v[216:219], v[6:9]
	v_mfma_f32_16x16x32_bf16 v[2:5], v[172:175], v[216:219], v[2:5]
	s_barrier
; #define PG8_STAGE(bufoff, gbase, voff) do { _Pragma("unroll") for (int _i = 0; _i < 2; ++_i) \
;         __builtin_amdgcn_global_load_lds((const unsigned*)((const char*)(gbase) + (voff)[_i]), (PG8_LAS unsigned*)(lds + (bufoff) + ldsw + _i * 8192), 16, 0, 0); } while (0)
; #define PG8_LDA(dst, b, h) do { _Pragma("unroll") for (int m = 0; m < 4; ++m) _Pragma("unroll") for (int k = 0; k < 2; ++k) dst[m][k] = *(const PG8_LAS bf16x8*)(lds + PG8_SA(b, h) + aoff + m * 2048 + k * 1024); } while (0)
; #define PG8_LDB(dst, b, h) do { _Pragma("unroll") for (int n = 0; n < 2; ++n) _Pragma("unroll") for (int k = 0; k < 2; ++k) dst[n][k] = *(const PG8_LAS bf16x8*)(lds + PG8_SB(b, h) + boff + n * 2048 + k * 1024); } while (0)
; #define PG8_MMA(ai, bj, At, Bt) do { __builtin_amdgcn_s_setprio(1); _Pragma("unroll") for (int k = 0; k < 2; ++k) _Pragma("unroll") for (int m = 0; m < 4; ++m) _Pragma("unroll") for (int n = 0; n < 2; ++n) \
;         acc[ai][bj][m][n] = __builtin_amdgcn_mfma_f32_16x16x32_bf16(Bt[n][k], At[m][k], acc[ai][bj][m][n], 0, 0, 0); __builtin_amdgcn_s_setprio(0); } while (0)
; #define PG8_WAIT_V(n) asm volatile("s_waitcnt vmcnt(" #n ")" ::: "memory")
; #define PG8_WAIT_L(n) asm volatile("s_waitcnt lgkmcnt(" #n ")" ::: "memory")
; #define PG8_BAR __builtin_amdgcn_s_barrier()
; #define PG8_SCHED __builtin_amdgcn_sched_barrier(0)
; template <class Epi, class Sched, bool ALIGN_EPI = false, bool SP2 = false>
; __device__ __forceinline__ void gemm_phase(PG8_LAS unsigned char* lds, const Gemm g, const Sched& S, const Epi& E, int tid_in) {
;     ...
;             PG8_LDB(B0, 1, 0); PG8_LDB(B1, 1, 1); PG8_SCHED; PG8_LDA(At, 1, 0); PG8_STAGE(PG8_SA(0, 1), a2 + hstep, voffA);
;             PG8_WAIT_V(8); PG8_WAIT_L(0); PG8_BAR; PG8_MMA(0, 0, At, B0); PG8_MMA(0, 1, At, B1); PG8_BAR; PG8_SCHED;
	v_add_u32_e32 v156, s33, v146
	v_add_u32_e32 v172, s74, v146
	ds_read_b128 v[140:143], v156
	ds_read_b128 v[148:151], v156 offset:1024
	ds_read_b128 v[152:155], v156 offset:2048
	ds_read_b128 v[156:159], v156 offset:3072
	ds_read_b128 v[160:163], v172
	ds_read_b128 v[164:167], v172 offset:1024
	ds_read_b128 v[168:171], v172 offset:2048
	ds_read_b128 v[172:175], v172 offset:3072
	s_add_u32 s56, s56, 0x40000
	s_addc_u32 s57, s57, 0
	s_mov_b32 m0, s61
	v_lshl_add_u64 v[226:227], s[56:57], 0, v[134:135]
	ds_read_b128 v[176:179], v147 offset:32768
	ds_read_b128 v[180:183], v147 offset:33792
	ds_read_b128 v[196:199], v147 offset:34816
	ds_read_b128 v[200:203], v147 offset:35840
	ds_read_b128 v[204:207], v147 offset:36864
	ds_read_b128 v[208:211], v147 offset:37888
	ds_read_b128 v[212:215], v147 offset:38912
	ds_read_b128 v[216:219], v147 offset:39936
	global_load_lds_dwordx4 v[226:227], off
	v_lshl_add_u64 v[226:227], s[56:57], 0, v[132:133]
	s_mov_b32 m0, s62
	s_nop 0
	global_load_lds_dwordx4 v[226:227], off
	s_waitcnt vmcnt(8)
	s_waitcnt lgkmcnt(0)
	s_barrier
	s_waitcnt lgkmcnt(0)
	v_mfma_f32_16x16x32_bf16 v[126:129], v[140:143], v[176:179], v[126:129]
	v_mfma_f32_16x16x32_bf16 v[122:125], v[152:155], v[176:179], v[122:125]
	v_mfma_f32_16x16x32_bf16 v[110:113], v[140:143], v[196:199], v[110:113]
	v_mfma_f32_16x16x32_bf16 v[106:109], v[152:155], v[196:199], v[106:109]
	v_mfma_f32_16x16x32_bf16 v[94:97], v[140:143], v[204:207], v[94:97]
	v_mfma_f32_16x16x32_bf16 v[90:93], v[152:155], v[204:207], v[90:93]
	v_mfma_f32_16x16x32_bf16 v[78:81], v[140:143], v[212:215], v[78:81]
	v_mfma_f32_16x16x32_bf16 v[74:77], v[152:155], v[212:215], v[74:77]
	v_mfma_f32_16x16x32_bf16 v[126:129], v[148:151], v[180:183], v[126:129]
	v_mfma_f32_16x16x32_bf16 v[122:125], v[156:159], v[180:183], v[122:125]
	v_mfma_f32_16x16x32_bf16 v[110:113], v[148:151], v[200:203], v[110:113]
	v_mfma_f32_16x16x32_bf16 v[106:109], v[156:159], v[200:203], v[106:109]
	v_mfma_f32_16x16x32_bf16 v[94:97], v[148:151], v[208:211], v[94:97]
	v_mfma_f32_16x16x32_bf16 v[90:93], v[156:159], v[208:211], v[90:93]
	v_mfma_f32_16x16x32_bf16 v[78:81], v[148:151], v[216:219], v[78:81]
	v_mfma_f32_16x16x32_bf16 v[74:77], v[156:159], v[216:219], v[74:77]
	v_mfma_f32_16x16x32_bf16 v[118:121], v[160:163], v[176:179], v[118:121]
	v_mfma_f32_16x16x32_bf16 v[114:117], v[168:171], v[176:179], v[114:117]
	v_mfma_f32_16x16x32_bf16 v[102:105], v[160:163], v[196:199], v[102:105]
	v_mfma_f32_16x16x32_bf16 v[98:101], v[168:171], v[196:199], v[98:101]
	v_mfma_f32_16x16x32_bf16 v[86:89], v[160:163], v[204:207], v[86:89]
	v_mfma_f32_16x16x32_bf16 v[82:85], v[168:171], v[204:207], v[82:85]
	v_mfma_f32_16x16x32_bf16 v[70:73], v[160:163], v[212:215], v[70:73]
	v_mfma_f32_16x16x32_bf16 v[66:69], v[168:171], v[212:215], v[66:69]
	v_mfma_f32_16x16x32_bf16 v[118:121], v[164:167], v[180:183], v[118:121]
	v_mfma_f32_16x16x32_bf16 v[114:117], v[172:175], v[180:183], v[114:117]
	v_mfma_f32_16x16x32_bf16 v[102:105], v[164:167], v[200:203], v[102:105]
	v_mfma_f32_16x16x32_bf16 v[98:101], v[172:175], v[200:203], v[98:101]
	v_mfma_f32_16x16x32_bf16 v[86:89], v[164:167], v[208:211], v[86:89]
	v_mfma_f32_16x16x32_bf16 v[82:85], v[172:175], v[208:211], v[82:85]
	v_mfma_f32_16x16x32_bf16 v[70:73], v[164:167], v[216:219], v[70:73]
	v_mfma_f32_16x16x32_bf16 v[66:69], v[172:175], v[216:219], v[66:69]
	s_barrier
; #define PG8_STAGE(bufoff, gbase, voff) do { _Pragma("unroll") for (int _i = 0; _i < 2; ++_i) \
;         __builtin_amdgcn_global_load_lds((const unsigned*)((const char*)(gbase) + (voff)[_i]), (PG8_LAS unsigned*)(lds + (bufoff) + ldsw + _i * 8192), 16, 0, 0); } while (0)
; #define PG8_LDA(dst, b, h) do { _Pragma("unroll") for (int m = 0; m < 4; ++m) _Pragma("unroll") for (int k = 0; k < 2; ++k) dst[m][k] = *(const PG8_LAS bf16x8*)(lds + PG8_SA(b, h) + aoff + m * 2048 + k * 1024); } while (0)
; #define PG8_MMA(ai, bj, At, Bt) do { __builtin_amdgcn_s_setprio(1); _Pragma("unroll") for (int k = 0; k < 2; ++k) _Pragma("unroll") for (int m = 0; m < 4; ++m) _Pragma("unroll") for (int n = 0; n < 2; ++n) \
;         acc[ai][bj][m][n] = __builtin_amdgcn_mfma_f32_16x16x32_bf16(Bt[n][k], At[m][k], acc[ai][bj][m][n], 0, 0, 0); __builtin_amdgcn_s_setprio(0); } while (0)
; #define PG8_WAIT_V(n) asm volatile("s_waitcnt vmcnt(" #n ")" ::: "memory")
; #define PG8_WAIT_L(n) asm volatile("s_waitcnt lgkmcnt(" #n ")" ::: "memory")
; #define PG8_BAR __builtin_amdgcn_s_barrier()
; #define PG8_SCHED __builtin_amdgcn_sched_barrier(0)
; template <class Epi, class Sched, bool ALIGN_EPI = false, bool SP2 = false>
; __device__ __forceinline__ void gemm_phase(PG8_LAS unsigned char* lds, const Gemm g, const Sched& S, const Epi& E, int tid_in) {
;     ...
;             PG8_LDA(At, 1, 1); PG8_STAGE(PG8_SB(1, 0), b3, voffB); PG8_STAGE(PG8_SB(1, 1), b3 + hstep, voffB); PG8_STAGE(PG8_SA(1, 0), a3, voffA);
;             PG8_WAIT_V(8); PG8_WAIT_L(0); PG8_BAR; PG8_MMA(1, 0, At, B0); PG8_MMA(1, 1, At, B1); PG8_BAR; PG8_SCHED;
;     ...
;         if constexpr (ALIGN_EPI) { if (wr == 0) PG8_BAR; }
	s_add_i32 s56, s33, s58
	v_lshl_add_u64 v[184:185], v[184:185], 0, s[26:27]
	s_mov_b32 m0, s56
	ds_read_b128 v[176:179], v147 offset:49152
	ds_read_b128 v[180:183], v147 offset:50176
	ds_read_b128 v[196:199], v147 offset:51200
	ds_read_b128 v[200:203], v147 offset:52224
	ds_read_b128 v[204:207], v147 offset:53248
	ds_read_b128 v[208:211], v147 offset:54272
	ds_read_b128 v[212:215], v147 offset:55296
	ds_read_b128 v[216:219], v147 offset:56320
	global_load_lds_dwordx4 v[184:185], off
	s_add_i32 m0, s56, 0x2000
	s_add_u32 s54, s54, 0x40080
	v_lshl_add_u64 v[184:185], v[220:221], 0, s[26:27]
	s_addc_u32 s55, s55, 0
	s_add_i32 s56, s74, s58
	global_load_lds_dwordx4 v[184:185], off
	v_lshl_add_u64 v[184:185], s[54:55], 0, v[0:1]
	s_mov_b32 m0, s56
	s_nop 0
	global_load_lds_dwordx4 v[184:185], off
	v_lshl_add_u64 v[184:185], s[54:55], 0, v[130:131]
	s_add_i32 m0, s56, 0x2000
	s_nop 0
	global_load_lds_dwordx4 v[184:185], off
	v_lshl_add_u64 v[184:185], v[222:223], 0, s[26:27]
	s_mov_b32 m0, s65
	s_nop 0
	global_load_lds_dwordx4 v[184:185], off
	v_lshl_add_u64 v[184:185], v[224:225], 0, s[26:27]
	s_mov_b32 m0, s68
	s_nop 0
	global_load_lds_dwordx4 v[184:185], off
	s_waitcnt vmcnt(8)
	s_waitcnt lgkmcnt(0)
	s_barrier
	s_waitcnt lgkmcnt(0)
	v_mfma_f32_16x16x32_bf16 v[62:65], v[140:143], v[176:179], v[62:65]
	v_mfma_f32_16x16x32_bf16 v[58:61], v[152:155], v[176:179], v[58:61]
	v_mfma_f32_16x16x32_bf16 v[46:49], v[140:143], v[196:199], v[46:49]
	v_mfma_f32_16x16x32_bf16 v[42:45], v[152:155], v[196:199], v[42:45]
	v_mfma_f32_16x16x32_bf16 v[30:33], v[140:143], v[204:207], v[30:33]
	v_mfma_f32_16x16x32_bf16 v[26:29], v[152:155], v[204:207], v[26:29]
	v_mfma_f32_16x16x32_bf16 v[14:17], v[140:143], v[212:215], v[14:17]
	v_mfma_f32_16x16x32_bf16 v[10:13], v[152:155], v[212:215], v[10:13]
	v_mfma_f32_16x16x32_bf16 v[62:65], v[148:151], v[180:183], v[62:65]
	v_mfma_f32_16x16x32_bf16 v[58:61], v[156:159], v[180:183], v[58:61]
	v_mfma_f32_16x16x32_bf16 v[46:49], v[148:151], v[200:203], v[46:49]
	v_mfma_f32_16x16x32_bf16 v[42:45], v[156:159], v[200:203], v[42:45]
	v_mfma_f32_16x16x32_bf16 v[30:33], v[148:151], v[208:211], v[30:33]
	v_mfma_f32_16x16x32_bf16 v[26:29], v[156:159], v[208:211], v[26:29]
	v_mfma_f32_16x16x32_bf16 v[14:17], v[148:151], v[216:219], v[14:17]
	v_mfma_f32_16x16x32_bf16 v[10:13], v[156:159], v[216:219], v[10:13]
	v_mfma_f32_16x16x32_bf16 v[54:57], v[160:163], v[176:179], v[54:57]
	v_mfma_f32_16x16x32_bf16 v[50:53], v[168:171], v[176:179], v[50:53]
	v_mfma_f32_16x16x32_bf16 v[38:41], v[160:163], v[196:199], v[38:41]
	v_mfma_f32_16x16x32_bf16 v[34:37], v[168:171], v[196:199], v[34:37]
	v_mfma_f32_16x16x32_bf16 v[22:25], v[160:163], v[204:207], v[22:25]
	v_mfma_f32_16x16x32_bf16 v[18:21], v[168:171], v[204:207], v[18:21]
	v_mfma_f32_16x16x32_bf16 v[6:9], v[160:163], v[212:215], v[6:9]
	v_mfma_f32_16x16x32_bf16 v[2:5], v[168:171], v[212:215], v[2:5]
	v_mfma_f32_16x16x32_bf16 v[54:57], v[164:167], v[180:183], v[54:57]
	v_mfma_f32_16x16x32_bf16 v[50:53], v[172:175], v[180:183], v[50:53]
	v_mfma_f32_16x16x32_bf16 v[38:41], v[164:167], v[200:203], v[38:41]
	v_mfma_f32_16x16x32_bf16 v[34:37], v[172:175], v[200:203], v[34:37]
	v_mfma_f32_16x16x32_bf16 v[22:25], v[164:167], v[208:211], v[22:25]
	v_mfma_f32_16x16x32_bf16 v[18:21], v[172:175], v[208:211], v[18:21]
	v_mfma_f32_16x16x32_bf16 v[6:9], v[164:167], v[216:219], v[6:9]
	v_mfma_f32_16x16x32_bf16 v[2:5], v[172:175], v[216:219], v[2:5]
	s_barrier
	s_add_i32 s82, s82, 2
	s_add_u32 s52, s52, 0x100
	s_addc_u32 s53, s53, 0
	s_add_u32 s80, s80, 0x100
	s_addc_u32 s81, s81, 0
	s_cmp_gt_u32 s82, 13
	s_cbranch_scc0 .LBB0_492
	s_and_b64 vcc, exec, s[40:41]
	s_cbranch_vccz .LBB0_495
	s_barrier

;     __device__ __forceinline__ bool next(int i, Unit& u) const { if (i >= n) return false; int o = own; asm volatile("" : "+s"(o)); u.pm = swap ? i : o; u.pn = swap ? o : i; u.idx = i; return true; }
; #define PG8_STAGE(bufoff, gbase, voff) do { _Pragma("unroll") for (int _i = 0; _i < 2; ++_i) \
;         __builtin_amdgcn_global_load_lds((const unsigned*)((const char*)(gbase) + (voff)[_i]), (PG8_LAS unsigned*)(lds + (bufoff) + ldsw + _i * 8192), 16, 0, 0); } while (0)
; #define PG8_LDA(dst, b, h) do { _Pragma("unroll") for (int m = 0; m < 4; ++m) _Pragma("unroll") for (int k = 0; k < 2; ++k) dst[m][k] = *(const PG8_LAS bf16x8*)(lds + PG8_SA(b, h) + aoff + m * 2048 + k * 1024); } while (0)
; #define PG8_LDB(dst, b, h) do { _Pragma("unroll") for (int n = 0; n < 2; ++n) _Pragma("unroll") for (int k = 0; k < 2; ++k) dst[n][k] = *(const PG8_LAS bf16x8*)(lds + PG8_SB(b, h) + boff + n * 2048 + k * 1024); } while (0)
; #define PG8_WAIT_V(n) asm volatile("s_waitcnt vmcnt(" #n ")" ::: "memory")
; template <class Epi, class Sched, bool ALIGN_EPI = false, bool SP2 = false>
; __device__ __forceinline__ void gemm_phase(PG8_LAS unsigned char* lds, const Gemm g, const Sched& S, const Epi& E, int tid_in) {
;     ...
;         const bool has_next = S.next(ui + 1, nxt);
;         const char* nA = has_next ? (const char*)g.A + (size_t)nxt.pm * tstep : cA; const char* nB = has_next ? (const char*)g.Bt + (size_t)nxt.pn * tstep : cB;
;         for (int t = 0; t < nt; t += 2) {
;             const bool last = (t == nt - 2);
;             const char* a1 = cA + (size_t)(t + 1) * kstep;
;             const char* a2 = last ? nA : cA + (size_t)(t + 2) * kstep; const char* b2 = last ? nB : cB + (size_t)(t + 2) * kstep;
;             const char* a3 = a2 + kstep; const char* b3 = b2 + kstep;
;             if (last && has_next) S.a_ready(nxt);
;             if constexpr (SP2) {
;             PG8_LDB(B0, 0, 0); PG8_LDB(B1, 0, 1); PG8_SCHED; PG8_LDA(At, 0, 0); PG8_STAGE(PG8_SA(1, 1), a1 + hstep, voffA);
;             PG8_WAIT_V(8); PG8_WAIT_L(0); PG8_BAR; PG8_MMA(0, 0, At, B0); PG8_MMA(0, 1, At, B1); PG8_BAR; PG8_SCHED;
;             PG8_LDA(At, 0, 1); PG8_STAGE(PG8_SB(0, 0), b2, voffB); PG8_STAGE(PG8_SB(0, 1), b2 + hstep, voffB); PG8_STAGE(PG8_SA(0, 0), a2, voffA);
;             PG8_WAIT_V(8); PG8_WAIT_L(0); PG8_BAR; PG8_MMA(1, 0, At, B0); PG8_MMA(1, 1, At, B1); PG8_BAR; PG8_SCHED;
.LBB0_566:
	s_ashr_i32 s43, s42, 31
	s_lshl_b64 s[46:47], s[42:43], 21
	s_add_u32 s46, s58, s46
	s_addc_u32 s47, s59, s47
	s_and_b64 s[48:49], s[40:41], exec
	s_cselect_b32 s43, s47, s51
	s_cselect_b32 s79, s46, s50
	s_ashr_i32 s45, s44, 31
	s_lshl_b64 s[48:49], s[44:45], 21
	s_add_u32 s48, s56, s48
	s_addc_u32 s49, s57, s49
	s_and_b64 s[54:55], s[40:41], exec
	s_cselect_b32 s45, s49, s53
	s_cselect_b32 s80, s48, s52
	s_add_u32 s50, s50, 0x100080
	s_addc_u32 s51, s51, 0
	s_add_u32 s81, s52, 0x100
	s_addc_u32 s82, s53, 0
	s_mov_b32 s83, -2
	s_waitcnt lgkmcnt(0)
	v_add_u32_e32 v134, s84, v210
	v_add_u32_e32 v158, s85, v210
	ds_read_b128 v[106:109], v134
	ds_read_b128 v[110:113], v134 offset:1024
	ds_read_b128 v[130:133], v134 offset:2048
	ds_read_b128 v[134:137], v134 offset:3072
	ds_read_b128 v[146:149], v158
	ds_read_b128 v[150:153], v158 offset:1024
	ds_read_b128 v[154:157], v158 offset:2048
	ds_read_b128 v[158:161], v158 offset:3072
	s_add_u32 s52, s50, 0xfff00080
	s_addc_u32 s53, s51, -1
	s_cmp_eq_u32 s83, 60
	s_cselect_b32 s55, s43, s53
	s_cselect_b32 s54, s79, s52
	s_cselect_b32 s53, s45, s82
	s_cselect_b32 s52, s80, s81
	v_lshl_add_u64 v[216:217], s[50:51], 0, v[202:203]
	s_add_i32 m0, s61, 0xc000
	ds_read_b128 v[162:165], v211
	ds_read_b128 v[166:169], v211 offset:1024
	ds_read_b128 v[170:173], v211 offset:2048
	ds_read_b128 v[174:177], v211 offset:3072
	ds_read_b128 v[178:181], v211 offset:4096
	ds_read_b128 v[182:185], v211 offset:5120
	ds_read_b128 v[206:209], v211 offset:6144
	ds_read_b128 v[212:215], v211 offset:7168
	global_load_lds_dwordx4 v[216:217], off
	v_lshl_add_u64 v[216:217], s[50:51], 0, v[204:205]
	s_add_i32 m0, s61, 0xe000
	s_nop 0
	global_load_lds_dwordx4 v[216:217], off
	s_waitcnt vmcnt(8)
	s_waitcnt lgkmcnt(0)
	s_barrier
	s_waitcnt lgkmcnt(0)
	v_mfma_f32_16x16x32_bf16 v[142:145], v[106:109], v[162:165], 0
	v_mfma_f32_16x16x32_bf16 v[138:141], v[130:133], v[162:165], 0
	v_mfma_f32_16x16x32_bf16 v[118:121], v[106:109], v[170:173], 0
	v_mfma_f32_16x16x32_bf16 v[114:117], v[130:133], v[170:173], 0
	v_mfma_f32_16x16x32_bf16 v[94:97], v[106:109], v[178:181], 0
	v_mfma_f32_16x16x32_bf16 v[90:93], v[130:133], v[178:181], 0
	v_mfma_f32_16x16x32_bf16 v[78:81], v[106:109], v[206:209], 0
	v_mfma_f32_16x16x32_bf16 v[74:77], v[130:133], v[206:209], 0
	v_mfma_f32_16x16x32_bf16 v[142:145], v[110:113], v[166:169], v[142:145]
	v_mfma_f32_16x16x32_bf16 v[138:141], v[134:137], v[166:169], v[138:141]
	v_mfma_f32_16x16x32_bf16 v[118:121], v[110:113], v[174:177], v[118:121]
	v_mfma_f32_16x16x32_bf16 v[114:117], v[134:137], v[174:177], v[114:117]
	v_mfma_f32_16x16x32_bf16 v[94:97], v[110:113], v[182:185], v[94:97]
	v_mfma_f32_16x16x32_bf16 v[90:93], v[134:137], v[182:185], v[90:93]
	v_mfma_f32_16x16x32_bf16 v[78:81], v[110:113], v[212:215], v[78:81]
	v_mfma_f32_16x16x32_bf16 v[74:77], v[134:137], v[212:215], v[74:77]
	v_mfma_f32_16x16x32_bf16 v[126:129], v[146:149], v[162:165], 0
	v_mfma_f32_16x16x32_bf16 v[122:125], v[154:157], v[162:165], 0
	v_mfma_f32_16x16x32_bf16 v[102:105], v[146:149], v[170:173], 0
	v_mfma_f32_16x16x32_bf16 v[98:101], v[154:157], v[170:173], 0
	v_mfma_f32_16x16x32_bf16 v[86:89], v[146:149], v[178:181], 0
	v_mfma_f32_16x16x32_bf16 v[82:85], v[154:157], v[178:181], 0
	v_mfma_f32_16x16x32_bf16 v[70:73], v[146:149], v[206:209], 0
	v_mfma_f32_16x16x32_bf16 v[66:69], v[154:157], v[206:209], 0
	v_mfma_f32_16x16x32_bf16 v[126:129], v[150:153], v[166:169], v[126:129]
	v_mfma_f32_16x16x32_bf16 v[122:125], v[158:161], v[166:169], v[122:125]
	v_mfma_f32_16x16x32_bf16 v[102:105], v[150:153], v[174:177], v[102:105]
	v_mfma_f32_16x16x32_bf16 v[98:101], v[158:161], v[174:177], v[98:101]
	v_mfma_f32_16x16x32_bf16 v[86:89], v[150:153], v[182:185], v[86:89]
	v_mfma_f32_16x16x32_bf16 v[82:85], v[158:161], v[182:185], v[82:85]
	v_mfma_f32_16x16x32_bf16 v[70:73], v[150:153], v[212:215], v[70:73]
	v_mfma_f32_16x16x32_bf16 v[66:69], v[158:161], v[212:215], v[66:69]
	s_barrier
	s_add_i32 s86, s84, s60
	v_lshl_add_u64 v[216:217], s[52:53], 0, v[0:1]
	s_mov_b32 m0, s86
	ds_read_b128 v[162:165], v211 offset:16384
	ds_read_b128 v[166:169], v211 offset:17408
	ds_read_b128 v[170:173], v211 offset:18432
	ds_read_b128 v[174:177], v211 offset:19456
	ds_read_b128 v[178:181], v211 offset:20480
	ds_read_b128 v[182:185], v211 offset:21504
	ds_read_b128 v[206:209], v211 offset:22528
	ds_read_b128 v[212:215], v211 offset:23552
	global_load_lds_dwordx4 v[216:217], off
	s_add_i32 m0, s86, 0x2000
	s_add_u32 s86, s52, 0x100000
	v_lshl_add_u64 v[218:219], s[52:53], 0, v[196:197]
	s_addc_u32 s87, s53, 0
	s_add_i32 s92, s85, s60
	global_load_lds_dwordx4 v[218:219], off
	v_lshl_add_u64 v[220:221], s[86:87], 0, v[0:1]
	s_mov_b32 m0, s92
	v_lshl_add_u64 v[222:223], s[54:55], 0, v[198:199]
	global_load_lds_dwordx4 v[220:221], off
	v_lshl_add_u64 v[220:221], s[86:87], 0, v[196:197]
	s_add_i32 m0, s92, 0x2000
	s_nop 0
	global_load_lds_dwordx4 v[220:221], off
	v_lshl_add_u64 v[220:221], s[54:55], 0, v[200:201]
	s_mov_b32 m0, s61
	s_nop 0
	global_load_lds_dwordx4 v[220:221], off
	s_mov_b32 m0, s62
	s_nop 0
	global_load_lds_dwordx4 v[222:223], off
	s_waitcnt vmcnt(8)
	s_waitcnt lgkmcnt(0)
	s_barrier
; #define PG8_STAGE(bufoff, gbase, voff) do { _Pragma("unroll") for (int _i = 0; _i < 2; ++_i) \
;         __builtin_amdgcn_global_load_lds((const unsigned*)((const char*)(gbase) + (voff)[_i]), (PG8_LAS unsigned*)(lds + (bufoff) + ldsw + _i * 8192), 16, 0, 0); } while (0)
; #define PG8_LDA(dst, b, h) do { _Pragma("unroll") for (int m = 0; m < 4; ++m) _Pragma("unroll") for (int k = 0; k < 2; ++k) dst[m][k] = *(const PG8_LAS bf16x8*)(lds + PG8_SA(b, h) + aoff + m * 2048 + k * 1024); } while (0)
; #define PG8_LDB(dst, b, h) do { _Pragma("unroll") for (int n = 0; n < 2; ++n) _Pragma("unroll") for (int k = 0; k < 2; ++k) dst[n][k] = *(const PG8_LAS bf16x8*)(lds + PG8_SB(b, h) + boff + n * 2048 + k * 1024); } while (0)
; #define PG8_MMA(ai, bj, At, Bt) do { __builtin_amdgcn_s_setprio(1); _Pragma("unroll") for (int k = 0; k < 2; ++k) _Pragma("unroll") for (int m = 0; m < 4; ++m) _Pragma("unroll") for (int n = 0; n < 2; ++n) \
;         acc[ai][bj][m][n] = __builtin_amdgcn_mfma_f32_16x16x32_bf16(Bt[n][k], At[m][k], acc[ai][bj][m][n], 0, 0, 0); __builtin_amdgcn_s_setprio(0); } while (0)
; #define PG8_WAIT_V(n) asm volatile("s_waitcnt vmcnt(" #n ")" ::: "memory")
; #define PG8_WAIT_L(n) asm volatile("s_waitcnt lgkmcnt(" #n ")" ::: "memory")
; #define PG8_BAR __builtin_amdgcn_s_barrier()
; #define PG8_SCHED __builtin_amdgcn_sched_barrier(0)
; template <class Epi, class Sched, bool ALIGN_EPI = false, bool SP2 = false>
; __device__ __forceinline__ void gemm_phase(PG8_LAS unsigned char* lds, const Gemm g, const Sched& S, const Epi& E, int tid_in) {
;     ...
;             PG8_WAIT_V(8); PG8_WAIT_L(0); PG8_BAR; PG8_MMA(1, 0, At, B0); PG8_MMA(1, 1, At, B1); PG8_BAR; PG8_SCHED;
;             PG8_LDB(B0, 1, 0); PG8_LDB(B1, 1, 1); PG8_SCHED; PG8_LDA(At, 1, 0); PG8_STAGE(PG8_SA(0, 1), a2 + hstep, voffA);
;             PG8_WAIT_V(8); PG8_WAIT_L(0); PG8_BAR; PG8_MMA(0, 0, At, B0); PG8_MMA(0, 1, At, B1); PG8_BAR; PG8_SCHED;
	s_waitcnt lgkmcnt(0)
	v_mfma_f32_16x16x32_bf16 v[62:65], v[106:109], v[162:165], 0
	v_mfma_f32_16x16x32_bf16 v[58:61], v[130:133], v[162:165], 0
	v_mfma_f32_16x16x32_bf16 v[46:49], v[106:109], v[170:173], 0
	v_mfma_f32_16x16x32_bf16 v[42:45], v[130:133], v[170:173], 0
	v_mfma_f32_16x16x32_bf16 v[30:33], v[106:109], v[178:181], 0
	v_mfma_f32_16x16x32_bf16 v[26:29], v[130:133], v[178:181], 0
	v_mfma_f32_16x16x32_bf16 v[14:17], v[106:109], v[206:209], 0
	v_mfma_f32_16x16x32_bf16 v[10:13], v[130:133], v[206:209], 0
	v_mfma_f32_16x16x32_bf16 v[62:65], v[110:113], v[166:169], v[62:65]
	v_mfma_f32_16x16x32_bf16 v[58:61], v[134:137], v[166:169], v[58:61]
	v_mfma_f32_16x16x32_bf16 v[46:49], v[110:113], v[174:177], v[46:49]
	v_mfma_f32_16x16x32_bf16 v[42:45], v[134:137], v[174:177], v[42:45]
	v_mfma_f32_16x16x32_bf16 v[30:33], v[110:113], v[182:185], v[30:33]
	v_mfma_f32_16x16x32_bf16 v[26:29], v[134:137], v[182:185], v[26:29]
	v_mfma_f32_16x16x32_bf16 v[14:17], v[110:113], v[212:215], v[14:17]
	v_mfma_f32_16x16x32_bf16 v[10:13], v[134:137], v[212:215], v[10:13]
	v_mfma_f32_16x16x32_bf16 v[54:57], v[146:149], v[162:165], 0
	v_mfma_f32_16x16x32_bf16 v[50:53], v[154:157], v[162:165], 0
	v_mfma_f32_16x16x32_bf16 v[38:41], v[146:149], v[170:173], 0
	v_mfma_f32_16x16x32_bf16 v[34:37], v[154:157], v[170:173], 0
	v_mfma_f32_16x16x32_bf16 v[22:25], v[146:149], v[178:181], 0
	v_mfma_f32_16x16x32_bf16 v[18:21], v[154:157], v[178:181], 0
	v_mfma_f32_16x16x32_bf16 v[6:9], v[146:149], v[206:209], 0
	v_mfma_f32_16x16x32_bf16 v[2:5], v[154:157], v[206:209], 0
	v_mfma_f32_16x16x32_bf16 v[54:57], v[150:153], v[166:169], v[54:57]
	v_mfma_f32_16x16x32_bf16 v[50:53], v[158:161], v[166:169], v[50:53]
	v_mfma_f32_16x16x32_bf16 v[38:41], v[150:153], v[174:177], v[38:41]
	v_mfma_f32_16x16x32_bf16 v[34:37], v[158:161], v[174:177], v[34:37]
	v_mfma_f32_16x16x32_bf16 v[22:25], v[150:153], v[182:185], v[22:25]
	v_mfma_f32_16x16x32_bf16 v[18:21], v[158:161], v[182:185], v[18:21]
	v_mfma_f32_16x16x32_bf16 v[6:9], v[150:153], v[212:215], v[6:9]
	v_mfma_f32_16x16x32_bf16 v[2:5], v[158:161], v[212:215], v[2:5]
	s_barrier
	v_add_u32_e32 v134, s33, v210
	v_add_u32_e32 v158, s74, v210
	ds_read_b128 v[106:109], v134
	ds_read_b128 v[110:113], v134 offset:1024
	ds_read_b128 v[130:133], v134 offset:2048
	ds_read_b128 v[134:137], v134 offset:3072
	ds_read_b128 v[146:149], v158
	ds_read_b128 v[150:153], v158 offset:1024
	ds_read_b128 v[154:157], v158 offset:2048
	ds_read_b128 v[158:161], v158 offset:3072
	s_add_u32 s54, s54, 0x100000
	s_addc_u32 s55, s55, 0
	s_mov_b32 m0, s63
	v_lshl_add_u64 v[224:225], s[54:55], 0, v[200:201]
	ds_read_b128 v[162:165], v211 offset:32768
	ds_read_b128 v[166:169], v211 offset:33792
	ds_read_b128 v[170:173], v211 offset:34816
	ds_read_b128 v[174:177], v211 offset:35840
	ds_read_b128 v[178:181], v211 offset:36864
	ds_read_b128 v[182:185], v211 offset:37888
	ds_read_b128 v[206:209], v211 offset:38912
	ds_read_b128 v[212:215], v211 offset:39936
	global_load_lds_dwordx4 v[224:225], off
	v_lshl_add_u64 v[224:225], s[54:55], 0, v[198:199]
	s_mov_b32 m0, s64
	s_nop 0
	global_load_lds_dwordx4 v[224:225], off
	s_waitcnt vmcnt(8)
	s_waitcnt lgkmcnt(0)
	s_barrier
	s_waitcnt lgkmcnt(0)
	v_mfma_f32_16x16x32_bf16 v[142:145], v[106:109], v[162:165], v[142:145]
	v_mfma_f32_16x16x32_bf16 v[138:141], v[130:133], v[162:165], v[138:141]
	v_mfma_f32_16x16x32_bf16 v[118:121], v[106:109], v[170:173], v[118:121]
	v_mfma_f32_16x16x32_bf16 v[114:117], v[130:133], v[170:173], v[114:117]
	v_mfma_f32_16x16x32_bf16 v[94:97], v[106:109], v[178:181], v[94:97]
	v_mfma_f32_16x16x32_bf16 v[90:93], v[130:133], v[178:181], v[90:93]
	v_mfma_f32_16x16x32_bf16 v[78:81], v[106:109], v[206:209], v[78:81]
	v_mfma_f32_16x16x32_bf16 v[74:77], v[130:133], v[206:209], v[74:77]
	v_mfma_f32_16x16x32_bf16 v[142:145], v[110:113], v[166:169], v[142:145]
	v_mfma_f32_16x16x32_bf16 v[138:141], v[134:137], v[166:169], v[138:141]
	v_mfma_f32_16x16x32_bf16 v[118:121], v[110:113], v[174:177], v[118:121]
	v_mfma_f32_16x16x32_bf16 v[114:117], v[134:137], v[174:177], v[114:117]
	v_mfma_f32_16x16x32_bf16 v[94:97], v[110:113], v[182:185], v[94:97]
	v_mfma_f32_16x16x32_bf16 v[90:93], v[134:137], v[182:185], v[90:93]
	v_mfma_f32_16x16x32_bf16 v[78:81], v[110:113], v[212:215], v[78:81]
	v_mfma_f32_16x16x32_bf16 v[74:77], v[134:137], v[212:215], v[74:77]
	v_mfma_f32_16x16x32_bf16 v[126:129], v[146:149], v[162:165], v[126:129]
	v_mfma_f32_16x16x32_bf16 v[122:125], v[154:157], v[162:165], v[122:125]
	v_mfma_f32_16x16x32_bf16 v[102:105], v[146:149], v[170:173], v[102:105]
	v_mfma_f32_16x16x32_bf16 v[98:101], v[154:157], v[170:173], v[98:101]
	v_mfma_f32_16x16x32_bf16 v[86:89], v[146:149], v[178:181], v[86:89]
	v_mfma_f32_16x16x32_bf16 v[82:85], v[154:157], v[178:181], v[82:85]
	v_mfma_f32_16x16x32_bf16 v[70:73], v[146:149], v[206:209], v[70:73]
	v_mfma_f32_16x16x32_bf16 v[66:69], v[154:157], v[206:209], v[66:69]
	v_mfma_f32_16x16x32_bf16 v[126:129], v[150:153], v[166:169], v[126:129]
	v_mfma_f32_16x16x32_bf16 v[122:125], v[158:161], v[166:169], v[122:125]
	v_mfma_f32_16x16x32_bf16 v[102:105], v[150:153], v[174:177], v[102:105]
	v_mfma_f32_16x16x32_bf16 v[98:101], v[158:161], v[174:177], v[98:101]
	v_mfma_f32_16x16x32_bf16 v[86:89], v[150:153], v[182:185], v[86:89]
	v_mfma_f32_16x16x32_bf16 v[82:85], v[158:161], v[182:185], v[82:85]
	v_mfma_f32_16x16x32_bf16 v[70:73], v[150:153], v[212:215], v[70:73]
	v_mfma_f32_16x16x32_bf16 v[66:69], v[158:161], v[212:215], v[66:69]
	s_barrier
; #define PG8_STAGE(bufoff, gbase, voff) do { _Pragma("unroll") for (int _i = 0; _i < 2; ++_i) \
;         __builtin_amdgcn_global_load_lds((const unsigned*)((const char*)(gbase) + (voff)[_i]), (PG8_LAS unsigned*)(lds + (bufoff) + ldsw + _i * 8192), 16, 0, 0); } while (0)
; #define PG8_LDA(dst, b, h) do { _Pragma("unroll") for (int m = 0; m < 4; ++m) _Pragma("unroll") for (int k = 0; k < 2; ++k) dst[m][k] = *(const PG8_LAS bf16x8*)(lds + PG8_SA(b, h) + aoff + m * 2048 + k * 1024); } while (0)
; #define PG8_LDB(dst, b, h) do { _Pragma("unroll") for (int n = 0; n < 2; ++n) _Pragma("unroll") for (int k = 0; k < 2; ++k) dst[n][k] = *(const PG8_LAS bf16x8*)(lds + PG8_SB(b, h) + boff + n * 2048 + k * 1024); } while (0)
; template <class Epi, class Sched, bool ALIGN_EPI = false, bool SP2 = false>
; __device__ __forceinline__ void gemm_phase(PG8_LAS unsigned char* lds, const Gemm g, const Sched& S, const Epi& E, int tid_in) {
;     ...
;             const bool last = (t == nt - 2);
;             const char* a1 = cA + (size_t)(t + 1) * kstep;
;             const char* a2 = last ? nA : cA + (size_t)(t + 2) * kstep; const char* b2 = last ? nB : cB + (size_t)(t + 2) * kstep;
;             const char* a3 = a2 + kstep; const char* b3 = b2 + kstep;
;             if (last && has_next) S.a_ready(nxt);
;             if constexpr (SP2) {
;             PG8_LDB(B0, 0, 0); PG8_LDB(B1, 0, 1); PG8_SCHED; PG8_LDA(At, 0, 0); PG8_STAGE(PG8_SA(1, 1), a1 + hstep, voffA);
;             PG8_WAIT_V(8); PG8_WAIT_L(0); PG8_BAR; PG8_MMA(0, 0, At, B0); PG8_MMA(0, 1, At, B1); PG8_BAR; PG8_SCHED;
;             PG8_LDA(At, 0, 1); PG8_STAGE(PG8_SB(0, 0), b2, voffB); PG8_STAGE(PG8_SB(0, 1), b2 + hstep, voffB); PG8_STAGE(PG8_SA(0, 0), a2, voffA);
;             PG8_WAIT_V(8); PG8_WAIT_L(0); PG8_BAR; PG8_MMA(1, 0, At, B0); PG8_MMA(1, 1, At, B1); PG8_BAR; PG8_SCHED;
;             PG8_LDB(B0, 1, 0); PG8_LDB(B1, 1, 1); PG8_SCHED; PG8_LDA(At, 1, 0); PG8_STAGE(PG8_SA(0, 1), a2 + hstep, voffA);
;             PG8_WAIT_V(8); PG8_WAIT_L(0); PG8_BAR; PG8_MMA(0, 0, At, B0); PG8_MMA(0, 1, At, B1); PG8_BAR; PG8_SCHED;
;             PG8_LDA(At, 1, 1); PG8_STAGE(PG8_SB(1, 0), b3, voffB); PG8_STAGE(PG8_SB(1, 1), b3 + hstep, voffB); PG8_STAGE(PG8_SA(1, 0), a3, voffA);
;             PG8_WAIT_V(8); PG8_WAIT_L(0); PG8_BAR; PG8_MMA(1, 0, At, B0); PG8_MMA(1, 1, At, B1); PG8_BAR; PG8_SCHED;
	s_add_i32 s54, s33, s60
	v_lshl_add_u64 v[216:217], v[216:217], 0, s[26:27]
	s_mov_b32 m0, s54
	ds_read_b128 v[162:165], v211 offset:49152
	ds_read_b128 v[166:169], v211 offset:50176
	ds_read_b128 v[170:173], v211 offset:51200
	ds_read_b128 v[174:177], v211 offset:52224
	ds_read_b128 v[178:181], v211 offset:53248
	ds_read_b128 v[182:185], v211 offset:54272
	ds_read_b128 v[206:209], v211 offset:55296
	ds_read_b128 v[212:215], v211 offset:56320
	global_load_lds_dwordx4 v[216:217], off
	s_add_i32 m0, s54, 0x2000
	s_add_u32 s52, s52, 0x100080
	v_lshl_add_u64 v[216:217], v[218:219], 0, s[26:27]
	s_addc_u32 s53, s53, 0
	s_add_i32 s54, s74, s60
	global_load_lds_dwordx4 v[216:217], off
	v_lshl_add_u64 v[216:217], s[52:53], 0, v[0:1]
	s_mov_b32 m0, s54
	s_nop 0
	global_load_lds_dwordx4 v[216:217], off
	v_lshl_add_u64 v[216:217], s[52:53], 0, v[196:197]
	s_add_i32 m0, s54, 0x2000
	s_nop 0
	global_load_lds_dwordx4 v[216:217], off
	v_lshl_add_u64 v[216:217], v[220:221], 0, s[26:27]
	s_mov_b32 m0, s75
	s_nop 0
	global_load_lds_dwordx4 v[216:217], off
	v_lshl_add_u64 v[216:217], v[222:223], 0, s[26:27]
	s_mov_b32 m0, s76
	s_nop 0
	global_load_lds_dwordx4 v[216:217], off
	s_waitcnt vmcnt(8)
	s_waitcnt lgkmcnt(0)
	s_barrier
	s_waitcnt lgkmcnt(0)
	v_mfma_f32_16x16x32_bf16 v[62:65], v[106:109], v[162:165], v[62:65]
	v_mfma_f32_16x16x32_bf16 v[58:61], v[130:133], v[162:165], v[58:61]
	v_mfma_f32_16x16x32_bf16 v[46:49], v[106:109], v[170:173], v[46:49]
	v_mfma_f32_16x16x32_bf16 v[42:45], v[130:133], v[170:173], v[42:45]
	v_mfma_f32_16x16x32_bf16 v[30:33], v[106:109], v[178:181], v[30:33]
	v_mfma_f32_16x16x32_bf16 v[26:29], v[130:133], v[178:181], v[26:29]
	v_mfma_f32_16x16x32_bf16 v[14:17], v[106:109], v[206:209], v[14:17]
	v_mfma_f32_16x16x32_bf16 v[10:13], v[130:133], v[206:209], v[10:13]
	v_mfma_f32_16x16x32_bf16 v[62:65], v[110:113], v[166:169], v[62:65]
	v_mfma_f32_16x16x32_bf16 v[58:61], v[134:137], v[166:169], v[58:61]
	v_mfma_f32_16x16x32_bf16 v[46:49], v[110:113], v[174:177], v[46:49]
	v_mfma_f32_16x16x32_bf16 v[42:45], v[134:137], v[174:177], v[42:45]
	v_mfma_f32_16x16x32_bf16 v[30:33], v[110:113], v[182:185], v[30:33]
	v_mfma_f32_16x16x32_bf16 v[26:29], v[134:137], v[182:185], v[26:29]
	v_mfma_f32_16x16x32_bf16 v[14:17], v[110:113], v[212:215], v[14:17]
	v_mfma_f32_16x16x32_bf16 v[10:13], v[134:137], v[212:215], v[10:13]
	v_mfma_f32_16x16x32_bf16 v[54:57], v[146:149], v[162:165], v[54:57]
	v_mfma_f32_16x16x32_bf16 v[50:53], v[154:157], v[162:165], v[50:53]
	v_mfma_f32_16x16x32_bf16 v[38:41], v[146:149], v[170:173], v[38:41]
	v_mfma_f32_16x16x32_bf16 v[34:37], v[154:157], v[170:173], v[34:37]
	v_mfma_f32_16x16x32_bf16 v[22:25], v[146:149], v[178:181], v[22:25]
	v_mfma_f32_16x16x32_bf16 v[18:21], v[154:157], v[178:181], v[18:21]
	v_mfma_f32_16x16x32_bf16 v[6:9], v[146:149], v[206:209], v[6:9]
	v_mfma_f32_16x16x32_bf16 v[2:5], v[154:157], v[206:209], v[2:5]
	v_mfma_f32_16x16x32_bf16 v[54:57], v[150:153], v[166:169], v[54:57]
	v_mfma_f32_16x16x32_bf16 v[50:53], v[158:161], v[166:169], v[50:53]
	v_mfma_f32_16x16x32_bf16 v[38:41], v[150:153], v[174:177], v[38:41]
	v_mfma_f32_16x16x32_bf16 v[34:37], v[158:161], v[174:177], v[34:37]
	v_mfma_f32_16x16x32_bf16 v[22:25], v[150:153], v[182:185], v[22:25]
	v_mfma_f32_16x16x32_bf16 v[18:21], v[158:161], v[182:185], v[18:21]
	v_mfma_f32_16x16x32_bf16 v[6:9], v[150:153], v[212:215], v[6:9]
	v_mfma_f32_16x16x32_bf16 v[2:5], v[158:161], v[212:215], v[2:5]
	s_barrier
	s_add_i32 s83, s83, 2
	s_add_u32 s50, s50, 0x100
	s_addc_u32 s51, s51, 0
	s_add_u32 s81, s81, 0x100
	s_addc_u32 s82, s82, 0
	s_cmp_gt_u32 s83, 61
.LBB0_567:
	v_add_u32_e32 v134, s84, v210
	v_add_u32_e32 v158, s85, v210
	ds_read_b128 v[106:109], v134
	ds_read_b128 v[110:113], v134 offset:1024
	ds_read_b128 v[130:133], v134 offset:2048
	ds_read_b128 v[134:137], v134 offset:3072
	ds_read_b128 v[146:149], v158
	ds_read_b128 v[150:153], v158 offset:1024
	ds_read_b128 v[154:157], v158 offset:2048
	ds_read_b128 v[158:161], v158 offset:3072
	s_add_u32 s52, s50, 0xfff00080
	s_addc_u32 s53, s51, -1
	s_cmp_eq_u32 s83, 60
	s_cselect_b32 s55, s43, s53
	s_cselect_b32 s54, s79, s52
	s_cselect_b32 s53, s45, s82
	s_cselect_b32 s52, s80, s81
	v_lshl_add_u64 v[216:217], s[50:51], 0, v[202:203]
	s_add_i32 m0, s61, 0xc000
	ds_read_b128 v[162:165], v211
	ds_read_b128 v[166:169], v211 offset:1024
	ds_read_b128 v[170:173], v211 offset:2048
	ds_read_b128 v[174:177], v211 offset:3072
	ds_read_b128 v[178:181], v211 offset:4096
	ds_read_b128 v[182:185], v211 offset:5120
	ds_read_b128 v[206:209], v211 offset:6144
	ds_read_b128 v[212:215], v211 offset:7168
	global_load_lds_dwordx4 v[216:217], off
	v_lshl_add_u64 v[216:217], s[50:51], 0, v[204:205]
	s_add_i32 m0, s61, 0xe000
	s_nop 0
	global_load_lds_dwordx4 v[216:217], off
	s_waitcnt vmcnt(8)
	s_waitcnt lgkmcnt(0)
	s_barrier
; #define PG8_STAGE(bufoff, gbase, voff) do { _Pragma("unroll") for (int _i = 0; _i < 2; ++_i) \
;         __builtin_amdgcn_global_load_lds((const unsigned*)((const char*)(gbase) + (voff)[_i]), (PG8_LAS unsigned*)(lds + (bufoff) + ldsw + _i * 8192), 16, 0, 0); } while (0)
; #define PG8_LDA(dst, b, h) do { _Pragma("unroll") for (int m = 0; m < 4; ++m) _Pragma("unroll") for (int k = 0; k < 2; ++k) dst[m][k] = *(const PG8_LAS bf16x8*)(lds + PG8_SA(b, h) + aoff + m * 2048 + k * 1024); } while (0)
; #define PG8_MMA(ai, bj, At, Bt) do { __builtin_amdgcn_s_setprio(1); _Pragma("unroll") for (int k = 0; k < 2; ++k) _Pragma("unroll") for (int m = 0; m < 4; ++m) _Pragma("unroll") for (int n = 0; n < 2; ++n) \
;         acc[ai][bj][m][n] = __builtin_amdgcn_mfma_f32_16x16x32_bf16(Bt[n][k], At[m][k], acc[ai][bj][m][n], 0, 0, 0); __builtin_amdgcn_s_setprio(0); } while (0)
; #define PG8_WAIT_V(n) asm volatile("s_waitcnt vmcnt(" #n ")" ::: "memory")
; #define PG8_WAIT_L(n) asm volatile("s_waitcnt lgkmcnt(" #n ")" ::: "memory")
; #define PG8_BAR __builtin_amdgcn_s_barrier()
; #define PG8_SCHED __builtin_amdgcn_sched_barrier(0)
; template <class Epi, class Sched, bool ALIGN_EPI = false, bool SP2 = false>
; __device__ __forceinline__ void gemm_phase(PG8_LAS unsigned char* lds, const Gemm g, const Sched& S, const Epi& E, int tid_in) {
;     ...
;             PG8_WAIT_V(8); PG8_WAIT_L(0); PG8_BAR; PG8_MMA(0, 0, At, B0); PG8_MMA(0, 1, At, B1); PG8_BAR; PG8_SCHED;
;             PG8_LDA(At, 0, 1); PG8_STAGE(PG8_SB(0, 0), b2, voffB); PG8_STAGE(PG8_SB(0, 1), b2 + hstep, voffB); PG8_STAGE(PG8_SA(0, 0), a2, voffA);
;             PG8_WAIT_V(8); PG8_WAIT_L(0); PG8_BAR; PG8_MMA(1, 0, At, B0); PG8_MMA(1, 1, At, B1); PG8_BAR; PG8_SCHED;
	s_waitcnt lgkmcnt(0)
	v_mfma_f32_16x16x32_bf16 v[142:145], v[106:109], v[162:165], v[142:145]
	v_mfma_f32_16x16x32_bf16 v[138:141], v[130:133], v[162:165], v[138:141]
	v_mfma_f32_16x16x32_bf16 v[118:121], v[106:109], v[170:173], v[118:121]
	v_mfma_f32_16x16x32_bf16 v[114:117], v[130:133], v[170:173], v[114:117]
	v_mfma_f32_16x16x32_bf16 v[94:97], v[106:109], v[178:181], v[94:97]
	v_mfma_f32_16x16x32_bf16 v[90:93], v[130:133], v[178:181], v[90:93]
	v_mfma_f32_16x16x32_bf16 v[78:81], v[106:109], v[206:209], v[78:81]
	v_mfma_f32_16x16x32_bf16 v[74:77], v[130:133], v[206:209], v[74:77]
	v_mfma_f32_16x16x32_bf16 v[142:145], v[110:113], v[166:169], v[142:145]
	v_mfma_f32_16x16x32_bf16 v[138:141], v[134:137], v[166:169], v[138:141]
	v_mfma_f32_16x16x32_bf16 v[118:121], v[110:113], v[174:177], v[118:121]
	v_mfma_f32_16x16x32_bf16 v[114:117], v[134:137], v[174:177], v[114:117]
	v_mfma_f32_16x16x32_bf16 v[94:97], v[110:113], v[182:185], v[94:97]
	v_mfma_f32_16x16x32_bf16 v[90:93], v[134:137], v[182:185], v[90:93]
	v_mfma_f32_16x16x32_bf16 v[78:81], v[110:113], v[212:215], v[78:81]
	v_mfma_f32_16x16x32_bf16 v[74:77], v[134:137], v[212:215], v[74:77]
	v_mfma_f32_16x16x32_bf16 v[126:129], v[146:149], v[162:165], v[126:129]
	v_mfma_f32_16x16x32_bf16 v[122:125], v[154:157], v[162:165], v[122:125]
	v_mfma_f32_16x16x32_bf16 v[102:105], v[146:149], v[170:173], v[102:105]
	v_mfma_f32_16x16x32_bf16 v[98:101], v[154:157], v[170:173], v[98:101]
	v_mfma_f32_16x16x32_bf16 v[86:89], v[146:149], v[178:181], v[86:89]
	v_mfma_f32_16x16x32_bf16 v[82:85], v[154:157], v[178:181], v[82:85]
	v_mfma_f32_16x16x32_bf16 v[70:73], v[146:149], v[206:209], v[70:73]
	v_mfma_f32_16x16x32_bf16 v[66:69], v[154:157], v[206:209], v[66:69]
	v_mfma_f32_16x16x32_bf16 v[126:129], v[150:153], v[166:169], v[126:129]
	v_mfma_f32_16x16x32_bf16 v[122:125], v[158:161], v[166:169], v[122:125]
	v_mfma_f32_16x16x32_bf16 v[102:105], v[150:153], v[174:177], v[102:105]
	v_mfma_f32_16x16x32_bf16 v[98:101], v[158:161], v[174:177], v[98:101]
	v_mfma_f32_16x16x32_bf16 v[86:89], v[150:153], v[182:185], v[86:89]
	v_mfma_f32_16x16x32_bf16 v[82:85], v[158:161], v[182:185], v[82:85]
	v_mfma_f32_16x16x32_bf16 v[70:73], v[150:153], v[212:215], v[70:73]
	v_mfma_f32_16x16x32_bf16 v[66:69], v[158:161], v[212:215], v[66:69]
	s_barrier
	s_add_i32 s86, s84, s60
	v_lshl_add_u64 v[216:217], s[52:53], 0, v[0:1]
	s_mov_b32 m0, s86
	ds_read_b128 v[162:165], v211 offset:16384
	ds_read_b128 v[166:169], v211 offset:17408
	ds_read_b128 v[170:173], v211 offset:18432
	ds_read_b128 v[174:177], v211 offset:19456
	ds_read_b128 v[178:181], v211 offset:20480
	ds_read_b128 v[182:185], v211 offset:21504
	ds_read_b128 v[206:209], v211 offset:22528
	ds_read_b128 v[212:215], v211 offset:23552
	global_load_lds_dwordx4 v[216:217], off
	s_add_i32 m0, s86, 0x2000
	s_add_u32 s86, s52, 0x100000
	v_lshl_add_u64 v[218:219], s[52:53], 0, v[196:197]
	s_addc_u32 s87, s53, 0
	s_add_i32 s92, s85, s60
	global_load_lds_dwordx4 v[218:219], off
	v_lshl_add_u64 v[220:221], s[86:87], 0, v[0:1]
	s_mov_b32 m0, s92
	v_lshl_add_u64 v[222:223], s[54:55], 0, v[198:199]
	global_load_lds_dwordx4 v[220:221], off
	v_lshl_add_u64 v[220:221], s[86:87], 0, v[196:197]
	s_add_i32 m0, s92, 0x2000
	s_nop 0
	global_load_lds_dwordx4 v[220:221], off
	v_lshl_add_u64 v[220:221], s[54:55], 0, v[200:201]
	s_mov_b32 m0, s61
	s_nop 0
	global_load_lds_dwordx4 v[220:221], off
	s_mov_b32 m0, s62
	s_nop 0
	global_load_lds_dwordx4 v[222:223], off
	s_waitcnt vmcnt(8)
	s_waitcnt lgkmcnt(0)
	s_barrier
	s_waitcnt lgkmcnt(0)
	v_mfma_f32_16x16x32_bf16 v[62:65], v[106:109], v[162:165], v[62:65]
	v_mfma_f32_16x16x32_bf16 v[58:61], v[130:133], v[162:165], v[58:61]
	v_mfma_f32_16x16x32_bf16 v[46:49], v[106:109], v[170:173], v[46:49]
	v_mfma_f32_16x16x32_bf16 v[42:45], v[130:133], v[170:173], v[42:45]
	v_mfma_f32_16x16x32_bf16 v[30:33], v[106:109], v[178:181], v[30:33]
	v_mfma_f32_16x16x32_bf16 v[26:29], v[130:133], v[178:181], v[26:29]
	v_mfma_f32_16x16x32_bf16 v[14:17], v[106:109], v[206:209], v[14:17]
	v_mfma_f32_16x16x32_bf16 v[10:13], v[130:133], v[206:209], v[10:13]
	v_mfma_f32_16x16x32_bf16 v[62:65], v[110:113], v[166:169], v[62:65]
	v_mfma_f32_16x16x32_bf16 v[58:61], v[134:137], v[166:169], v[58:61]
	v_mfma_f32_16x16x32_bf16 v[46:49], v[110:113], v[174:177], v[46:49]
	v_mfma_f32_16x16x32_bf16 v[42:45], v[134:137], v[174:177], v[42:45]
	v_mfma_f32_16x16x32_bf16 v[30:33], v[110:113], v[182:185], v[30:33]
	v_mfma_f32_16x16x32_bf16 v[26:29], v[134:137], v[182:185], v[26:29]
	v_mfma_f32_16x16x32_bf16 v[14:17], v[110:113], v[212:215], v[14:17]
	v_mfma_f32_16x16x32_bf16 v[10:13], v[134:137], v[212:215], v[10:13]
	v_mfma_f32_16x16x32_bf16 v[54:57], v[146:149], v[162:165], v[54:57]
	v_mfma_f32_16x16x32_bf16 v[50:53], v[154:157], v[162:165], v[50:53]
	v_mfma_f32_16x16x32_bf16 v[38:41], v[146:149], v[170:173], v[38:41]
	v_mfma_f32_16x16x32_bf16 v[34:37], v[154:157], v[170:173], v[34:37]
	v_mfma_f32_16x16x32_bf16 v[22:25], v[146:149], v[178:181], v[22:25]
	v_mfma_f32_16x16x32_bf16 v[18:21], v[154:157], v[178:181], v[18:21]
	v_mfma_f32_16x16x32_bf16 v[6:9], v[146:149], v[206:209], v[6:9]
	v_mfma_f32_16x16x32_bf16 v[2:5], v[154:157], v[206:209], v[2:5]
	v_mfma_f32_16x16x32_bf16 v[54:57], v[150:153], v[166:169], v[54:57]
	v_mfma_f32_16x16x32_bf16 v[50:53], v[158:161], v[166:169], v[50:53]
	v_mfma_f32_16x16x32_bf16 v[38:41], v[150:153], v[174:177], v[38:41]
	v_mfma_f32_16x16x32_bf16 v[34:37], v[158:161], v[174:177], v[34:37]
	v_mfma_f32_16x16x32_bf16 v[22:25], v[150:153], v[182:185], v[22:25]
	v_mfma_f32_16x16x32_bf16 v[18:21], v[158:161], v[182:185], v[18:21]
	v_mfma_f32_16x16x32_bf16 v[6:9], v[150:153], v[212:215], v[6:9]
	v_mfma_f32_16x16x32_bf16 v[2:5], v[158:161], v[212:215], v[2:5]
	s_barrier
; #define PG8_STAGE(bufoff, gbase, voff) do { _Pragma("unroll") for (int _i = 0; _i < 2; ++_i) \
;         __builtin_amdgcn_global_load_lds((const unsigned*)((const char*)(gbase) + (voff)[_i]), (PG8_LAS unsigned*)(lds + (bufoff) + ldsw + _i * 8192), 16, 0, 0); } while (0)
; #define PG8_LDA(dst, b, h) do { _Pragma("unroll") for (int m = 0; m < 4; ++m) _Pragma("unroll") for (int k = 0; k < 2; ++k) dst[m][k] = *(const PG8_LAS bf16x8*)(lds + PG8_SA(b, h) + aoff + m * 2048 + k * 1024); } while (0)
; #define PG8_LDB(dst, b, h) do { _Pragma("unroll") for (int n = 0; n < 2; ++n) _Pragma("unroll") for (int k = 0; k < 2; ++k) dst[n][k] = *(const PG8_LAS bf16x8*)(lds + PG8_SB(b, h) + boff + n * 2048 + k * 1024); } while (0)
; #define PG8_MMA(ai, bj, At, Bt) do { __builtin_amdgcn_s_setprio(1); _Pragma("unroll") for (int k = 0; k < 2; ++k) _Pragma("unroll") for (int m = 0; m < 4; ++m) _Pragma("unroll") for (int n = 0; n < 2; ++n) \
;         acc[ai][bj][m][n] = __builtin_amdgcn_mfma_f32_16x16x32_bf16(Bt[n][k], At[m][k], acc[ai][bj][m][n], 0, 0, 0); __builtin_amdgcn_s_setprio(0); } while (0)
; #define PG8_WAIT_V(n) asm volatile("s_waitcnt vmcnt(" #n ")" ::: "memory")
; #define PG8_WAIT_L(n) asm volatile("s_waitcnt lgkmcnt(" #n ")" ::: "memory")
; #define PG8_BAR __builtin_amdgcn_s_barrier()
; #define PG8_SCHED __builtin_amdgcn_sched_barrier(0)
; template <class Epi, class Sched, bool ALIGN_EPI = false, bool SP2 = false>
; __device__ __forceinline__ void gemm_phase(PG8_LAS unsigned char* lds, const Gemm g, const Sched& S, const Epi& E, int tid_in) {
;     ...
;             PG8_LDB(B0, 1, 0); PG8_LDB(B1, 1, 1); PG8_SCHED; PG8_LDA(At, 1, 0); PG8_STAGE(PG8_SA(0, 1), a2 + hstep, voffA);
;             PG8_WAIT_V(8); PG8_WAIT_L(0); PG8_BAR; PG8_MMA(0, 0, At, B0); PG8_MMA(0, 1, At, B1); PG8_BAR; PG8_SCHED;
	v_add_u32_e32 v134, s33, v210
	v_add_u32_e32 v158, s74, v210
	ds_read_b128 v[106:109], v134
	ds_read_b128 v[110:113], v134 offset:1024
	ds_read_b128 v[130:133], v134 offset:2048
	ds_read_b128 v[134:137], v134 offset:3072
	ds_read_b128 v[146:149], v158
	ds_read_b128 v[150:153], v158 offset:1024
	ds_read_b128 v[154:157], v158 offset:2048
	ds_read_b128 v[158:161], v158 offset:3072
	s_add_u32 s54, s54, 0x100000
	s_addc_u32 s55, s55, 0
	s_mov_b32 m0, s63
	v_lshl_add_u64 v[224:225], s[54:55], 0, v[200:201]
	ds_read_b128 v[162:165], v211 offset:32768
	ds_read_b128 v[166:169], v211 offset:33792
	ds_read_b128 v[170:173], v211 offset:34816
	ds_read_b128 v[174:177], v211 offset:35840
	ds_read_b128 v[178:181], v211 offset:36864
	ds_read_b128 v[182:185], v211 offset:37888
	ds_read_b128 v[206:209], v211 offset:38912
	ds_read_b128 v[212:215], v211 offset:39936
	global_load_lds_dwordx4 v[224:225], off
	v_lshl_add_u64 v[224:225], s[54:55], 0, v[198:199]
	s_mov_b32 m0, s64
	s_nop 0
	global_load_lds_dwordx4 v[224:225], off
	s_waitcnt vmcnt(8)
	s_waitcnt lgkmcnt(0)
	s_barrier
	s_waitcnt lgkmcnt(0)
	v_mfma_f32_16x16x32_bf16 v[142:145], v[106:109], v[162:165], v[142:145]
	v_mfma_f32_16x16x32_bf16 v[138:141], v[130:133], v[162:165], v[138:141]
	v_mfma_f32_16x16x32_bf16 v[118:121], v[106:109], v[170:173], v[118:121]
	v_mfma_f32_16x16x32_bf16 v[114:117], v[130:133], v[170:173], v[114:117]
	v_mfma_f32_16x16x32_bf16 v[94:97], v[106:109], v[178:181], v[94:97]
	v_mfma_f32_16x16x32_bf16 v[90:93], v[130:133], v[178:181], v[90:93]
	v_mfma_f32_16x16x32_bf16 v[78:81], v[106:109], v[206:209], v[78:81]
	v_mfma_f32_16x16x32_bf16 v[74:77], v[130:133], v[206:209], v[74:77]
	v_mfma_f32_16x16x32_bf16 v[142:145], v[110:113], v[166:169], v[142:145]
	v_mfma_f32_16x16x32_bf16 v[138:141], v[134:137], v[166:169], v[138:141]
	v_mfma_f32_16x16x32_bf16 v[118:121], v[110:113], v[174:177], v[118:121]
	v_mfma_f32_16x16x32_bf16 v[114:117], v[134:137], v[174:177], v[114:117]
	v_mfma_f32_16x16x32_bf16 v[94:97], v[110:113], v[182:185], v[94:97]
	v_mfma_f32_16x16x32_bf16 v[90:93], v[134:137], v[182:185], v[90:93]
	v_mfma_f32_16x16x32_bf16 v[78:81], v[110:113], v[212:215], v[78:81]
	v_mfma_f32_16x16x32_bf16 v[74:77], v[134:137], v[212:215], v[74:77]
	v_mfma_f32_16x16x32_bf16 v[126:129], v[146:149], v[162:165], v[126:129]
	v_mfma_f32_16x16x32_bf16 v[122:125], v[154:157], v[162:165], v[122:125]
	v_mfma_f32_16x16x32_bf16 v[102:105], v[146:149], v[170:173], v[102:105]
	v_mfma_f32_16x16x32_bf16 v[98:101], v[154:157], v[170:173], v[98:101]
	v_mfma_f32_16x16x32_bf16 v[86:89], v[146:149], v[178:181], v[86:89]
	v_mfma_f32_16x16x32_bf16 v[82:85], v[154:157], v[178:181], v[82:85]
	v_mfma_f32_16x16x32_bf16 v[70:73], v[146:149], v[206:209], v[70:73]
	v_mfma_f32_16x16x32_bf16 v[66:69], v[154:157], v[206:209], v[66:69]
	v_mfma_f32_16x16x32_bf16 v[126:129], v[150:153], v[166:169], v[126:129]
	v_mfma_f32_16x16x32_bf16 v[122:125], v[158:161], v[166:169], v[122:125]
	v_mfma_f32_16x16x32_bf16 v[102:105], v[150:153], v[174:177], v[102:105]
	v_mfma_f32_16x16x32_bf16 v[98:101], v[158:161], v[174:177], v[98:101]
	v_mfma_f32_16x16x32_bf16 v[86:89], v[150:153], v[182:185], v[86:89]
	v_mfma_f32_16x16x32_bf16 v[82:85], v[158:161], v[182:185], v[82:85]
	v_mfma_f32_16x16x32_bf16 v[70:73], v[150:153], v[212:215], v[70:73]
	v_mfma_f32_16x16x32_bf16 v[66:69], v[158:161], v[212:215], v[66:69]
	s_barrier
; #define PG8_STAGE(bufoff, gbase, voff) do { _Pragma("unroll") for (int _i = 0; _i < 2; ++_i) \
;         __builtin_amdgcn_global_load_lds((const unsigned*)((const char*)(gbase) + (voff)[_i]), (PG8_LAS unsigned*)(lds + (bufoff) + ldsw + _i * 8192), 16, 0, 0); } while (0)
; #define PG8_LDA(dst, b, h) do { _Pragma("unroll") for (int m = 0; m < 4; ++m) _Pragma("unroll") for (int k = 0; k < 2; ++k) dst[m][k] = *(const PG8_LAS bf16x8*)(lds + PG8_SA(b, h) + aoff + m * 2048 + k * 1024); } while (0)
; #define PG8_MMA(ai, bj, At, Bt) do { __builtin_amdgcn_s_setprio(1); _Pragma("unroll") for (int k = 0; k < 2; ++k) _Pragma("unroll") for (int m = 0; m < 4; ++m) _Pragma("unroll") for (int n = 0; n < 2; ++n) \
;         acc[ai][bj][m][n] = __builtin_amdgcn_mfma_f32_16x16x32_bf16(Bt[n][k], At[m][k], acc[ai][bj][m][n], 0, 0, 0); __builtin_amdgcn_s_setprio(0); } while (0)
; #define PG8_WAIT_V(n) asm volatile("s_waitcnt vmcnt(" #n ")" ::: "memory")
; #define PG8_WAIT_L(n) asm volatile("s_waitcnt lgkmcnt(" #n ")" ::: "memory")
; #define PG8_BAR __builtin_amdgcn_s_barrier()
; #define PG8_SCHED __builtin_amdgcn_sched_barrier(0)
; template <class Epi, class Sched, bool ALIGN_EPI = false, bool SP2 = false>
; __device__ __forceinline__ void gemm_phase(PG8_LAS unsigned char* lds, const Gemm g, const Sched& S, const Epi& E, int tid_in) {
;     ...
;             PG8_LDA(At, 1, 1); PG8_STAGE(PG8_SB(1, 0), b3, voffB); PG8_STAGE(PG8_SB(1, 1), b3 + hstep, voffB); PG8_STAGE(PG8_SA(1, 0), a3, voffA);
;             PG8_WAIT_V(8); PG8_WAIT_L(0); PG8_BAR; PG8_MMA(1, 0, At, B0); PG8_MMA(1, 1, At, B1); PG8_BAR; PG8_SCHED;
;     ...
;         if constexpr (ALIGN_EPI) { if (wr == 0) PG8_BAR; }
	s_add_i32 s54, s33, s60
	v_lshl_add_u64 v[216:217], v[216:217], 0, s[26:27]
	s_mov_b32 m0, s54
	ds_read_b128 v[162:165], v211 offset:49152
	ds_read_b128 v[166:169], v211 offset:50176
	ds_read_b128 v[170:173], v211 offset:51200
	ds_read_b128 v[174:177], v211 offset:52224
	ds_read_b128 v[178:181], v211 offset:53248
	ds_read_b128 v[182:185], v211 offset:54272
	ds_read_b128 v[206:209], v211 offset:55296
	ds_read_b128 v[212:215], v211 offset:56320
	global_load_lds_dwordx4 v[216:217], off
	s_add_i32 m0, s54, 0x2000
	s_add_u32 s52, s52, 0x100080
	v_lshl_add_u64 v[216:217], v[218:219], 0, s[26:27]
	s_addc_u32 s53, s53, 0
	s_add_i32 s54, s74, s60
	global_load_lds_dwordx4 v[216:217], off
	v_lshl_add_u64 v[216:217], s[52:53], 0, v[0:1]
	s_mov_b32 m0, s54
	s_nop 0
	global_load_lds_dwordx4 v[216:217], off
	v_lshl_add_u64 v[216:217], s[52:53], 0, v[196:197]
	s_add_i32 m0, s54, 0x2000
	s_nop 0
	global_load_lds_dwordx4 v[216:217], off
	v_lshl_add_u64 v[216:217], v[220:221], 0, s[26:27]
	s_mov_b32 m0, s75
	s_nop 0
	global_load_lds_dwordx4 v[216:217], off
	v_lshl_add_u64 v[216:217], v[222:223], 0, s[26:27]
	s_mov_b32 m0, s76
	s_nop 0
	global_load_lds_dwordx4 v[216:217], off
	s_waitcnt vmcnt(8)
	s_waitcnt lgkmcnt(0)
	s_barrier
	s_waitcnt lgkmcnt(0)
	v_mfma_f32_16x16x32_bf16 v[62:65], v[106:109], v[162:165], v[62:65]
	v_mfma_f32_16x16x32_bf16 v[58:61], v[130:133], v[162:165], v[58:61]
	v_mfma_f32_16x16x32_bf16 v[46:49], v[106:109], v[170:173], v[46:49]
	v_mfma_f32_16x16x32_bf16 v[42:45], v[130:133], v[170:173], v[42:45]
	v_mfma_f32_16x16x32_bf16 v[30:33], v[106:109], v[178:181], v[30:33]
	v_mfma_f32_16x16x32_bf16 v[26:29], v[130:133], v[178:181], v[26:29]
	v_mfma_f32_16x16x32_bf16 v[14:17], v[106:109], v[206:209], v[14:17]
	v_mfma_f32_16x16x32_bf16 v[10:13], v[130:133], v[206:209], v[10:13]
	v_mfma_f32_16x16x32_bf16 v[62:65], v[110:113], v[166:169], v[62:65]
	v_mfma_f32_16x16x32_bf16 v[58:61], v[134:137], v[166:169], v[58:61]
	v_mfma_f32_16x16x32_bf16 v[46:49], v[110:113], v[174:177], v[46:49]
	v_mfma_f32_16x16x32_bf16 v[42:45], v[134:137], v[174:177], v[42:45]
	v_mfma_f32_16x16x32_bf16 v[30:33], v[110:113], v[182:185], v[30:33]
	v_mfma_f32_16x16x32_bf16 v[26:29], v[134:137], v[182:185], v[26:29]
	v_mfma_f32_16x16x32_bf16 v[14:17], v[110:113], v[212:215], v[14:17]
	v_mfma_f32_16x16x32_bf16 v[10:13], v[134:137], v[212:215], v[10:13]
	v_mfma_f32_16x16x32_bf16 v[54:57], v[146:149], v[162:165], v[54:57]
	v_mfma_f32_16x16x32_bf16 v[50:53], v[154:157], v[162:165], v[50:53]
	v_mfma_f32_16x16x32_bf16 v[38:41], v[146:149], v[170:173], v[38:41]
	v_mfma_f32_16x16x32_bf16 v[34:37], v[154:157], v[170:173], v[34:37]
	v_mfma_f32_16x16x32_bf16 v[22:25], v[146:149], v[178:181], v[22:25]
	v_mfma_f32_16x16x32_bf16 v[18:21], v[154:157], v[178:181], v[18:21]
	v_mfma_f32_16x16x32_bf16 v[6:9], v[146:149], v[206:209], v[6:9]
	v_mfma_f32_16x16x32_bf16 v[2:5], v[154:157], v[206:209], v[2:5]
	v_mfma_f32_16x16x32_bf16 v[54:57], v[150:153], v[166:169], v[54:57]
	v_mfma_f32_16x16x32_bf16 v[50:53], v[158:161], v[166:169], v[50:53]
	v_mfma_f32_16x16x32_bf16 v[38:41], v[150:153], v[174:177], v[38:41]
	v_mfma_f32_16x16x32_bf16 v[34:37], v[158:161], v[174:177], v[34:37]
	v_mfma_f32_16x16x32_bf16 v[22:25], v[150:153], v[182:185], v[22:25]
	v_mfma_f32_16x16x32_bf16 v[18:21], v[158:161], v[182:185], v[18:21]
	v_mfma_f32_16x16x32_bf16 v[6:9], v[150:153], v[212:215], v[6:9]
	v_mfma_f32_16x16x32_bf16 v[2:5], v[158:161], v[212:215], v[2:5]
	s_barrier
	s_add_i32 s83, s83, 2
	s_add_u32 s50, s50, 0x100
	s_addc_u32 s51, s51, 0
	s_add_u32 s81, s81, 0x100
	s_addc_u32 s82, s82, 0
	s_cmp_gt_u32 s83, 61
	s_cbranch_scc0 .LBB0_567
	s_and_b64 vcc, exec, s[38:39]
	s_cbranch_vccz .LBB0_570
	s_barrier
